# GEMM epilogue: FLAT dwordx4 loads/stores replaced by GLOBAL forms (same addresses; no LDS-aperture path, no lgkmcnt)
# speedup vs baseline: 1.0061x; 1.0011x over previous
; DEVI float bf_lo(unsigned u) { return __uint_as_float(u << 16); }
; DEVI float bf_hi(unsigned u) { return __uint_as_float(u & 0xffff0000u); }
; DEVI float sigmoidf_(float x) { return 1.f / (1.f + __expf(-x)); }
; DEVI u32x4 pack8(f32x4 a, f32x4 b) { u32x4 o; o.x = cvt_pk_bf16(a[0], a[1]); o.y = cvt_pk_bf16(a[2], a[3]); o.z = cvt_pk_bf16(b[0], b[1]); o.w = cvt_pk_bf16(b[2], b[3]); return o; }
; DEVI void gemm_epi(const GJob& jb, int row, int col, f32x4 v0, f32x4 v1) {
;   const int mode = jb.mode;
;   if (mode == 0) { *(u32x4*)((bf16_t*)jb.out + (size_t)row * jb.ldo + col) = pack8(v0, v1); }
;   else if (mode == 1) { float* p = (float*)jb.out + (size_t)row * jb.ldo + col; *(f32x4*)p = v0; *(f32x4*)(p + 4) = v1; }
;   else if (mode == 2) { f32x4 s0, s1; for (int i = 0; i < 4; ++i) { s0[i] = sigmoidf_(v0[i]); s1[i] = sigmoidf_(v1[i]); } *(u32x4*)((bf16_t*)jb.out + (size_t)row * jb.ldo + col) = pack8(s0, s1); }
;   else if (mode == 7) {
;     const u32x4 g = *(const u32x4*)((const bf16_t*)jb.aux + (size_t)row * NGATE + 2 * 2048 + col);
;     const f32x4 g0 = {bf_lo(g.x), bf_hi(g.x), bf_lo(g.y), bf_hi(g.y)}, g1 = {bf_lo(g.z), bf_hi(g.z), bf_lo(g.w), bf_hi(g.w)};
;     *(u32x4*)((bf16_t*)jb.out + (size_t)row * 2048 + col) = pack8(g0 * v0, g1 * v1);
.LBB0_424:
	v_or_b32_e32 v0, s43, v159
	v_add_u32_e32 v132, s47, v0
	v_or_b32_e32 v0, s12, v158
	v_ashrrev_i32_e32 v133, 31, v132
	v_or_b32_e32 v130, s68, v0
	s_cmp_eq_u32 s71, 6
	s_cbranch_scc1 .Lepi6
	v_mad_i64_i32 v[136:137], s[0:1], v132, s33, 0
	v_lshlrev_b64 v[134:135], 12, v[132:133]
	s_mov_b64 s[12:13], -1
	s_mov_b64 s[10:11], 0
	s_cmp_lt_i32 s71, 2
	s_mov_b64 s[8:9], 0
	s_cbranch_scc1 .LBB0_433
	s_cmp_gt_i32 s71, 6
	s_cbranch_scc0 .LBB0_429
	s_cmp_eq_u32 s71, 7
	s_mov_b64 s[8:9], -1
	s_cbranch_scc0 .LBB0_428
	v_ashrrev_i32_e32 v131, 31, v130
	v_lshl_add_u64 v[138:139], s[94:95], 0, v[136:137]
	v_lshlrev_b64 v[142:143], 1, v[130:131]
	v_lshl_add_u64 v[138:139], v[138:139], 0, v[142:143]
	v_add_co_u32_e32 v138, vcc, 0x2000, v138
	v_lshl_add_u64 v[144:145], s[90:91], 0, v[134:135]
	s_nop 0
	v_addc_co_u32_e32 v139, vcc, 0, v139, vcc
	global_load_dwordx4 v[138:141], v[138:139], off
	v_lshl_add_u64 v[142:143], v[144:145], 0, v[142:143]
	s_mov_b64 s[8:9], 0
	s_waitcnt vmcnt(0) lgkmcnt(0)
	v_lshlrev_b32_e32 v144, 16, v138
	v_and_b32_e32 v145, 0xffff0000, v138
	v_lshlrev_b32_e32 v138, 16, v139
	v_and_b32_e32 v139, 0xffff0000, v139
	v_lshlrev_b32_e32 v146, 16, v140
	v_and_b32_e32 v147, 0xffff0000, v140
	v_lshlrev_b32_e32 v140, 16, v141
	v_and_b32_e32 v141, 0xffff0000, v141
	v_pk_mul_f32 v[148:149], v[128:129], v[138:139]
	v_pk_mul_f32 v[138:139], v[126:127], v[144:145]
	v_pk_mul_f32 v[144:145], v[124:125], v[140:141]
	v_pk_mul_f32 v[140:141], v[122:123], v[146:147]
	v_cvt_pk_bf16_f32 v138, v138, v139
	v_cvt_pk_bf16_f32 v139, v148, v149
	s_nop 0
	v_cvt_pk_bf16_f32 v140, v140, v141
	v_cvt_pk_bf16_f32 v141, v144, v145
	global_store_dwordx4 v[142:143], v[138:141], off

; DEVI u32x4 pack8(f32x4 a, f32x4 b) { u32x4 o; o.x = cvt_pk_bf16(a[0], a[1]); o.y = cvt_pk_bf16(a[2], a[3]); o.z = cvt_pk_bf16(b[0], b[1]); o.w = cvt_pk_bf16(b[2], b[3]); return o; }
; DEVI float sigmoidf_(float x) { return 1.f / (1.f + __expf(-x)); }
; DEVI void gemm_epi(const GJob& jb, int row, int col, f32x4 v0, f32x4 v1) {
;     ...
;   else if (mode == 2) { f32x4 s0, s1; for (int i = 0; i < 4; ++i) { s0[i] = sigmoidf_(v0[i]); s1[i] = sigmoidf_(v1[i]); } *(u32x4*)((bf16_t*)jb.out + (size_t)row * jb.ldo + col) = pack8(s0, s1); }
.LBB0_429:
	s_and_b64 vcc, exec, s[12:13]
	s_cbranch_vccz .LBB0_432
	s_cmp_eq_u32 s71, 2
	s_mov_b64 s[8:9], -1
	s_cbranch_scc0 .LBB0_432
	v_mul_f32_e32 v0, 0xbfb8aa3b, v126
	v_exp_f32_e32 v0, v0
	s_mov_b64 s[8:9], 0
	v_add_f32_e32 v0, 1.0, v0
	v_div_scale_f32 v131, s[0:1], v0, v0, 1.0
	v_rcp_f32_e32 v133, v131
	s_nop 0
	v_fma_f32 v138, -v131, v133, 1.0
	v_fmac_f32_e32 v133, v138, v133
	v_div_scale_f32 v138, vcc, 1.0, v0, 1.0
	v_mul_f32_e32 v139, v138, v133
	v_fma_f32 v140, -v131, v139, v138
	v_fmac_f32_e32 v139, v140, v133
	v_fma_f32 v131, -v131, v139, v138
	v_div_fmas_f32 v131, v131, v133, v139
	v_div_fixup_f32 v0, v131, v0, 1.0
	v_mul_f32_e32 v131, 0xbfb8aa3b, v122
	v_exp_f32_e32 v131, v131
	s_nop 0
	v_add_f32_e32 v131, 1.0, v131
	v_div_scale_f32 v133, s[0:1], v131, v131, 1.0
	v_rcp_f32_e32 v138, v133
	s_nop 0
	v_fma_f32 v139, -v133, v138, 1.0
	v_fmac_f32_e32 v138, v139, v138
	v_div_scale_f32 v139, vcc, 1.0, v131, 1.0
	v_mul_f32_e32 v140, v139, v138
	v_fma_f32 v141, -v133, v140, v139
	v_fmac_f32_e32 v140, v141, v138
	v_fma_f32 v133, -v133, v140, v139
	v_div_fmas_f32 v133, v133, v138, v140
	v_div_fixup_f32 v131, v133, v131, 1.0
	v_mul_f32_e32 v133, 0xbfb8aa3b, v127
	v_exp_f32_e32 v133, v133
	s_nop 0
	v_add_f32_e32 v133, 1.0, v133
	v_div_scale_f32 v138, s[0:1], v133, v133, 1.0
	v_rcp_f32_e32 v139, v138
	s_nop 0
	v_fma_f32 v140, -v138, v139, 1.0
	v_fmac_f32_e32 v139, v140, v139
	v_div_scale_f32 v140, vcc, 1.0, v133, 1.0
	v_mul_f32_e32 v141, v140, v139
	v_fma_f32 v142, -v138, v141, v140
	v_fmac_f32_e32 v141, v142, v139
	v_fma_f32 v138, -v138, v141, v140
	v_div_fmas_f32 v138, v138, v139, v141
	v_div_fixup_f32 v133, v138, v133, 1.0
	v_mul_f32_e32 v138, 0xbfb8aa3b, v123
	v_exp_f32_e32 v138, v138
	s_nop 0
	v_add_f32_e32 v138, 1.0, v138
	v_div_scale_f32 v139, s[0:1], v138, v138, 1.0
	v_rcp_f32_e32 v140, v139
	s_nop 0
	v_fma_f32 v141, -v139, v140, 1.0
	v_fmac_f32_e32 v140, v141, v140
	v_div_scale_f32 v141, vcc, 1.0, v138, 1.0
	v_mul_f32_e32 v142, v141, v140
	v_fma_f32 v143, -v139, v142, v141
	v_fmac_f32_e32 v142, v143, v140
	v_fma_f32 v139, -v139, v142, v141
	v_div_fmas_f32 v139, v139, v140, v142
	v_div_fixup_f32 v140, v139, v138, 1.0
	v_mul_f32_e32 v138, 0xbfb8aa3b, v128
	v_exp_f32_e32 v138, v138
	v_cvt_pk_bf16_f32 v140, v131, v140
	v_ashrrev_i32_e32 v131, 31, v130
	v_add_f32_e32 v138, 1.0, v138
	v_div_scale_f32 v139, s[0:1], v138, v138, 1.0
	v_rcp_f32_e32 v141, v139
	s_nop 0
	v_fma_f32 v142, -v139, v141, 1.0
	v_fmac_f32_e32 v141, v142, v141
	v_div_scale_f32 v142, vcc, 1.0, v138, 1.0
	v_mul_f32_e32 v143, v142, v141
	v_fma_f32 v144, -v139, v143, v142
	v_fmac_f32_e32 v143, v144, v141
	v_fma_f32 v139, -v139, v143, v142
	v_div_fmas_f32 v139, v139, v141, v143
	v_div_fixup_f32 v139, v139, v138, 1.0
	v_mul_f32_e32 v138, 0xbfb8aa3b, v124
	v_exp_f32_e32 v138, v138
	s_nop 0
	v_add_f32_e32 v138, 1.0, v138
	v_div_scale_f32 v141, s[0:1], v138, v138, 1.0
	v_rcp_f32_e32 v142, v141
	s_nop 0
	v_fma_f32 v143, -v141, v142, 1.0
	v_fmac_f32_e32 v142, v143, v142
	v_div_scale_f32 v143, vcc, 1.0, v138, 1.0
	v_mul_f32_e32 v144, v143, v142
	v_fma_f32 v145, -v141, v144, v143
	v_fmac_f32_e32 v144, v145, v142
	v_fma_f32 v141, -v141, v144, v143
	v_div_fmas_f32 v141, v141, v142, v144
	v_div_fixup_f32 v141, v141, v138, 1.0
	v_mul_f32_e32 v138, 0xbfb8aa3b, v129
	v_exp_f32_e32 v138, v138
	s_nop 0
	v_add_f32_e32 v138, 1.0, v138
	v_div_scale_f32 v142, s[0:1], v138, v138, 1.0
	v_rcp_f32_e32 v143, v142
	s_nop 0
	v_fma_f32 v144, -v142, v143, 1.0
	v_fmac_f32_e32 v143, v144, v143
	v_div_scale_f32 v144, vcc, 1.0, v138, 1.0
	v_mul_f32_e32 v145, v144, v143
	v_fma_f32 v146, -v142, v145, v144
	v_fmac_f32_e32 v145, v146, v143
	v_fma_f32 v142, -v142, v145, v144
	v_div_fmas_f32 v142, v142, v143, v145
	v_div_fixup_f32 v142, v142, v138, 1.0
	v_mul_f32_e32 v138, 0xbfb8aa3b, v125
	v_exp_f32_e32 v138, v138
	v_cvt_pk_bf16_f32 v139, v139, v142
	s_nop 0
	v_add_f32_e32 v138, 1.0, v138
	v_div_scale_f32 v143, s[0:1], v138, v138, 1.0
	v_rcp_f32_e32 v144, v143
	s_nop 0
	v_fma_f32 v145, -v143, v144, 1.0
	v_fmac_f32_e32 v144, v145, v144
	v_div_scale_f32 v145, vcc, 1.0, v138, 1.0
	v_mul_f32_e32 v146, v145, v144
	v_fma_f32 v147, -v143, v146, v145
	v_fmac_f32_e32 v146, v147, v144
	v_fma_f32 v143, -v143, v146, v145
	v_div_fmas_f32 v143, v143, v144, v146
	v_div_fixup_f32 v143, v143, v138, 1.0
	v_cvt_pk_bf16_f32 v141, v141, v143
	v_mad_i64_i32 v[142:143], s[0:1], v132, s29, 0
	v_lshl_add_u64 v[142:143], v[142:143], 1, s[90:91]
	v_lshl_add_u64 v[142:143], v[130:131], 1, v[142:143]
	v_cvt_pk_bf16_f32 v138, v0, v133
	global_store_dwordx4 v[142:143], v[138:141], off

; DEVI void gemm_epi(const GJob& jb, int row, int col, f32x4 v0, f32x4 v1) {
;     ...
;   else if (mode == 1) { float* p = (float*)jb.out + (size_t)row * jb.ldo + col; *(f32x4*)p = v0; *(f32x4*)(p + 4) = v1; }
.LBB0_433:
	s_and_b64 vcc, exec, s[12:13]
	s_cbranch_vccz .LBB0_438
	s_cmp_gt_i32 s71, 0
	s_mov_b64 s[10:11], -1
	s_cbranch_scc0 .LBB0_436
	v_mad_i64_i32 v[138:139], s[0:1], v132, s29, 0
	v_lshl_add_u64 v[138:139], v[138:139], 2, s[90:91]
	v_ashrrev_i32_e32 v131, 31, v130
	v_lshl_add_u64 v[138:139], v[130:131], 2, v[138:139]
	global_store_dwordx4 v[138:139], v[126:129], off
	global_store_dwordx4 v[138:139], v[122:125], off offset:16
	s_mov_b64 s[10:11], 0

; DEVI u32x4 pack8(f32x4 a, f32x4 b) { u32x4 o; o.x = cvt_pk_bf16(a[0], a[1]); o.y = cvt_pk_bf16(a[2], a[3]); o.z = cvt_pk_bf16(b[0], b[1]); o.w = cvt_pk_bf16(b[2], b[3]); return o; }
; DEVI void gemm_epi(const GJob& jb, int row, int col, f32x4 v0, f32x4 v1) {
;     ...
;   if (mode == 0) { *(u32x4*)((bf16_t*)jb.out + (size_t)row * jb.ldo + col) = pack8(v0, v1); }
;     ...
;     const float* xp = (const float*)jb.aux + (size_t)row * jb.ldo + col; const float* gp = (const float*)jb.aux2 + col;
;     float* op = (float*)jb.out + (size_t)row * jb.ldo + col;
;     const f32x4 x0 = *(const f32x4*)xp, x1 = *(const f32x4*)(xp + 4), t0 = *(const f32x4*)gp, t1 = *(const f32x4*)(gp + 4);
;     *(f32x4*)op = x0 + t0 * v0; *(f32x4*)(op + 4) = x1 + t1 * v1;
.LBB0_438:
	s_and_b64 vcc, exec, s[8:9]
	v_ashrrev_i32_e32 v131, 31, v130
	s_cbranch_vccz .LBB0_440
	v_mad_i64_i32 v[138:139], s[0:1], v132, s29, 0
	v_lshlrev_b64 v[138:139], 2, v[138:139]
	v_lshl_add_u64 v[140:141], s[94:95], 0, v[138:139]
	v_lshlrev_b64 v[142:143], 2, v[130:131]
	v_lshl_add_u64 v[144:145], v[140:141], 0, v[142:143]
	v_lshl_add_u64 v[150:151], s[88:89], 0, v[142:143]
	v_lshl_add_u64 v[138:139], s[90:91], 0, v[138:139]
	v_lshl_add_u64 v[154:155], v[138:139], 0, v[142:143]
	global_load_dwordx4 v[138:141], v[144:145], off
	s_nop 0
	global_load_dwordx4 v[142:145], v[144:145], off offset:16
	s_nop 0
	global_load_dwordx4 v[146:149], v[150:151], off
	s_nop 0
	global_load_dwordx4 v[150:153], v[150:151], off offset:16
	s_mov_b64 s[10:11], 0
	s_waitcnt vmcnt(0) lgkmcnt(0)
	v_pk_fma_f32 v[140:141], v[128:129], v[148:149], v[140:141]
	v_pk_fma_f32 v[138:139], v[126:127], v[146:147], v[138:139]
	global_store_dwordx4 v[154:155], v[138:141], off
	s_nop 1
	v_pk_fma_f32 v[140:141], v[124:125], v[152:153], v[144:145]
	v_pk_fma_f32 v[138:139], v[122:123], v[150:151], v[142:143]
	global_store_dwordx4 v[154:155], v[138:141], off offset:16
.LBB0_440:
	s_andn2_b64 vcc, exec, s[10:11]
	s_cbranch_vccnz .LBB0_442
	v_cvt_pk_bf16_f32 v126, v126, v127
	v_cvt_pk_bf16_f32 v127, v128, v129
	v_cvt_pk_bf16_f32 v128, v122, v123
	v_mad_i64_i32 v[122:123], s[0:1], v132, s29, 0
	v_lshl_add_u64 v[122:123], v[122:123], 1, s[90:91]
	v_lshl_add_u64 v[122:123], v[130:131], 1, v[122:123]
	v_cvt_pk_bf16_f32 v129, v124, v125
	global_store_dwordx4 v[122:123], v[126:129], off
.LBB0_442:
	v_or_b32_e32 v122, 0x80, v130
	s_mov_b64 s[12:13], -1
	s_mov_b64 s[10:11], 0
	s_cmp_lt_i32 s71, 2
	s_mov_b64 s[8:9], 0
	s_cbranch_scc1 .LBB0_451
	s_cmp_gt_i32 s71, 6
	s_cbranch_scc0 .LBB0_447
	s_cmp_eq_u32 s71, 7
	s_mov_b64 s[8:9], -1
	s_cbranch_scc0 .LBB0_446
	v_lshl_add_u64 v[124:125], s[94:95], 0, v[136:137]
	v_ashrrev_i32_e32 v123, 31, v122
	v_lshl_add_u64 v[124:125], v[122:123], 1, v[124:125]
	v_add_co_u32_e32 v124, vcc, 0x2000, v124
	v_lshl_add_u64 v[128:129], s[90:91], 0, v[134:135]
	s_nop 0
	v_addc_co_u32_e32 v125, vcc, 0, v125, vcc
	global_load_dwordx4 v[124:127], v[124:125], off
	v_lshl_add_u64 v[128:129], v[130:131], 1, v[128:129]
	s_mov_b64 s[8:9], 0
	s_waitcnt vmcnt(0) lgkmcnt(0)
	v_lshlrev_b32_e32 v134, 16, v124
	v_and_b32_e32 v135, 0xffff0000, v124
	v_lshlrev_b32_e32 v124, 16, v125
	v_and_b32_e32 v125, 0xffff0000, v125
	v_lshlrev_b32_e32 v136, 16, v126
	v_and_b32_e32 v137, 0xffff0000, v126
	v_lshlrev_b32_e32 v126, 16, v127
	v_and_b32_e32 v127, 0xffff0000, v127
	v_pk_mul_f32 v[138:139], v[120:121], v[124:125]
	v_pk_mul_f32 v[124:125], v[118:119], v[134:135]
	v_pk_mul_f32 v[134:135], v[116:117], v[126:127]
	v_pk_mul_f32 v[126:127], v[114:115], v[136:137]
	v_cvt_pk_bf16_f32 v124, v124, v125
	v_cvt_pk_bf16_f32 v125, v138, v139
	s_nop 0
	v_cvt_pk_bf16_f32 v126, v126, v127
	v_cvt_pk_bf16_f32 v127, v134, v135
	global_store_dwordx4 v[128:129], v[124:127], off offset:256

; DEVI u32x4 pack8(f32x4 a, f32x4 b) { u32x4 o; o.x = cvt_pk_bf16(a[0], a[1]); o.y = cvt_pk_bf16(a[2], a[3]); o.z = cvt_pk_bf16(b[0], b[1]); o.w = cvt_pk_bf16(b[2], b[3]); return o; }
; DEVI float sigmoidf_(float x) { return 1.f / (1.f + __expf(-x)); }
; DEVI void gemm_epi(const GJob& jb, int row, int col, f32x4 v0, f32x4 v1) {
;     ...
;   else if (mode == 2) { f32x4 s0, s1; for (int i = 0; i < 4; ++i) { s0[i] = sigmoidf_(v0[i]); s1[i] = sigmoidf_(v1[i]); } *(u32x4*)((bf16_t*)jb.out + (size_t)row * jb.ldo + col) = pack8(s0, s1); }
.LBB0_447:
	s_and_b64 vcc, exec, s[12:13]
	s_cbranch_vccz .LBB0_450
	s_cmp_eq_u32 s71, 2
	s_mov_b64 s[8:9], -1
	s_cbranch_scc0 .LBB0_450
	v_mul_f32_e32 v0, 0xbfb8aa3b, v118
	v_exp_f32_e32 v0, v0
	s_mov_b64 s[8:9], 0
	v_add_f32_e32 v0, 1.0, v0
	v_div_scale_f32 v123, s[0:1], v0, v0, 1.0
	v_rcp_f32_e32 v124, v123
	s_nop 0
	v_fma_f32 v125, -v123, v124, 1.0
	v_fmac_f32_e32 v124, v125, v124
	v_div_scale_f32 v125, vcc, 1.0, v0, 1.0
	v_mul_f32_e32 v126, v125, v124
	v_fma_f32 v127, -v123, v126, v125
	v_fmac_f32_e32 v126, v127, v124
	v_fma_f32 v123, -v123, v126, v125
	v_div_fmas_f32 v123, v123, v124, v126
	v_div_fixup_f32 v0, v123, v0, 1.0
	v_mul_f32_e32 v123, 0xbfb8aa3b, v114
	v_exp_f32_e32 v123, v123
	s_nop 0
	v_add_f32_e32 v123, 1.0, v123
	v_div_scale_f32 v124, s[0:1], v123, v123, 1.0
	v_rcp_f32_e32 v125, v124
	s_nop 0
	v_fma_f32 v126, -v124, v125, 1.0
	v_fmac_f32_e32 v125, v126, v125
	v_div_scale_f32 v126, vcc, 1.0, v123, 1.0
	v_mul_f32_e32 v127, v126, v125
	v_fma_f32 v128, -v124, v127, v126
	v_fmac_f32_e32 v127, v128, v125
	v_fma_f32 v124, -v124, v127, v126
	v_div_fmas_f32 v124, v124, v125, v127
	v_div_fixup_f32 v123, v124, v123, 1.0
	v_mul_f32_e32 v124, 0xbfb8aa3b, v119
	v_exp_f32_e32 v124, v124
	s_nop 0
	v_add_f32_e32 v124, 1.0, v124
	v_div_scale_f32 v125, s[0:1], v124, v124, 1.0
	v_rcp_f32_e32 v126, v125
	s_nop 0
	v_fma_f32 v127, -v125, v126, 1.0
	v_fmac_f32_e32 v126, v127, v126
	v_div_scale_f32 v127, vcc, 1.0, v124, 1.0
	v_mul_f32_e32 v128, v127, v126
	v_fma_f32 v129, -v125, v128, v127
	v_fmac_f32_e32 v128, v129, v126
	v_fma_f32 v125, -v125, v128, v127
	v_div_fmas_f32 v125, v125, v126, v128
	v_div_fixup_f32 v124, v125, v124, 1.0
	v_mul_f32_e32 v125, 0xbfb8aa3b, v115
	v_exp_f32_e32 v125, v125
	v_cvt_pk_bf16_f32 v124, v0, v124
	s_nop 0
	v_add_f32_e32 v125, 1.0, v125
	v_div_scale_f32 v126, s[0:1], v125, v125, 1.0
	v_rcp_f32_e32 v127, v126
	s_nop 0
	v_fma_f32 v128, -v126, v127, 1.0
	v_fmac_f32_e32 v127, v128, v127
	v_div_scale_f32 v128, vcc, 1.0, v125, 1.0
	v_mul_f32_e32 v129, v128, v127
	v_fma_f32 v133, -v126, v129, v128
	v_fmac_f32_e32 v129, v133, v127
	v_fma_f32 v126, -v126, v129, v128
	v_div_fmas_f32 v126, v126, v127, v129
	v_div_fixup_f32 v126, v126, v125, 1.0
	v_mul_f32_e32 v125, 0xbfb8aa3b, v120
	v_exp_f32_e32 v125, v125
	v_cvt_pk_bf16_f32 v126, v123, v126
	s_nop 0
	v_add_f32_e32 v125, 1.0, v125
	v_div_scale_f32 v127, s[0:1], v125, v125, 1.0
	v_rcp_f32_e32 v128, v127
	s_nop 0
	v_fma_f32 v129, -v127, v128, 1.0
	v_fmac_f32_e32 v128, v129, v128
	v_div_scale_f32 v129, vcc, 1.0, v125, 1.0
	v_mul_f32_e32 v133, v129, v128
	v_fma_f32 v134, -v127, v133, v129
	v_fmac_f32_e32 v133, v134, v128
	v_fma_f32 v127, -v127, v133, v129
	v_div_fmas_f32 v127, v127, v128, v133
	v_div_fixup_f32 v125, v127, v125, 1.0
	v_mul_f32_e32 v127, 0xbfb8aa3b, v116
	v_exp_f32_e32 v127, v127
	s_nop 0
	v_add_f32_e32 v127, 1.0, v127
	v_div_scale_f32 v128, s[0:1], v127, v127, 1.0
	v_rcp_f32_e32 v129, v128
	s_nop 0
	v_fma_f32 v133, -v128, v129, 1.0
	v_fmac_f32_e32 v129, v133, v129
	v_div_scale_f32 v133, vcc, 1.0, v127, 1.0
	v_mul_f32_e32 v134, v133, v129
	v_fma_f32 v135, -v128, v134, v133
	v_fmac_f32_e32 v134, v135, v129
	v_fma_f32 v128, -v128, v134, v133
	v_div_fmas_f32 v128, v128, v129, v134
	v_div_fixup_f32 v127, v128, v127, 1.0
	v_mul_f32_e32 v128, 0xbfb8aa3b, v121
	v_exp_f32_e32 v128, v128
	s_nop 0
	v_add_f32_e32 v128, 1.0, v128
	v_div_scale_f32 v129, s[0:1], v128, v128, 1.0
	v_rcp_f32_e32 v133, v129
	s_nop 0
	v_fma_f32 v134, -v129, v133, 1.0
	v_fmac_f32_e32 v133, v134, v133
	v_div_scale_f32 v134, vcc, 1.0, v128, 1.0
	v_mul_f32_e32 v135, v134, v133
	v_fma_f32 v136, -v129, v135, v134
	v_fmac_f32_e32 v135, v136, v133
	v_fma_f32 v129, -v129, v135, v134
	v_div_fmas_f32 v129, v129, v133, v135
	v_div_fixup_f32 v128, v129, v128, 1.0
	v_mul_f32_e32 v129, 0xbfb8aa3b, v117
	v_exp_f32_e32 v129, v129
	v_cvt_pk_bf16_f32 v125, v125, v128
	s_nop 0
	v_add_f32_e32 v129, 1.0, v129
	v_div_scale_f32 v133, s[0:1], v129, v129, 1.0
	v_rcp_f32_e32 v134, v133
	s_nop 0
	v_fma_f32 v135, -v133, v134, 1.0
	v_fmac_f32_e32 v134, v135, v134
	v_div_scale_f32 v135, vcc, 1.0, v129, 1.0
	v_mul_f32_e32 v136, v135, v134
	v_fma_f32 v137, -v133, v136, v135
	v_fmac_f32_e32 v136, v137, v134
	v_fma_f32 v133, -v133, v136, v135
	v_div_fmas_f32 v133, v133, v134, v136
	v_div_fixup_f32 v129, v133, v129, 1.0
	v_cvt_pk_bf16_f32 v127, v127, v129
	v_mad_i64_i32 v[128:129], s[0:1], v132, s29, 0
	v_lshl_add_u64 v[128:129], v[128:129], 1, s[90:91]
	v_lshl_add_u64 v[128:129], v[130:131], 1, v[128:129]
	global_store_dwordx4 v[128:129], v[124:127], off offset:256

; DEVI void gemm_epi(const GJob& jb, int row, int col, f32x4 v0, f32x4 v1) {
;     ...
;   else if (mode == 1) { float* p = (float*)jb.out + (size_t)row * jb.ldo + col; *(f32x4*)p = v0; *(f32x4*)(p + 4) = v1; }
.LBB0_451:
	s_and_b64 vcc, exec, s[12:13]
	s_cbranch_vccz .LBB0_456
	s_cmp_gt_i32 s71, 0
	s_mov_b64 s[10:11], -1
	s_cbranch_scc0 .LBB0_454
	v_mad_i64_i32 v[124:125], s[0:1], v132, s29, 0
	v_lshl_add_u64 v[124:125], v[124:125], 2, s[90:91]
	v_lshl_add_u64 v[124:125], v[130:131], 2, v[124:125]
	global_store_dwordx4 v[124:125], v[118:121], off offset:512
	global_store_dwordx4 v[124:125], v[114:117], off offset:528
	s_mov_b64 s[10:11], 0

; DEVI float bf_lo(unsigned u) { return __uint_as_float(u << 16); }
; DEVI float bf_hi(unsigned u) { return __uint_as_float(u & 0xffff0000u); }
; DEVI float sigmoidf_(float x) { return 1.f / (1.f + __expf(-x)); }
; DEVI u32x4 pack8(f32x4 a, f32x4 b) { u32x4 o; o.x = cvt_pk_bf16(a[0], a[1]); o.y = cvt_pk_bf16(a[2], a[3]); o.z = cvt_pk_bf16(b[0], b[1]); o.w = cvt_pk_bf16(b[2], b[3]); return o; }
; DEVI void gemm_epi(const GJob& jb, int row, int col, f32x4 v0, f32x4 v1) {
;     ...
;   if (mode == 0) { *(u32x4*)((bf16_t*)jb.out + (size_t)row * jb.ldo + col) = pack8(v0, v1); }
;   else if (mode == 1) { float* p = (float*)jb.out + (size_t)row * jb.ldo + col; *(f32x4*)p = v0; *(f32x4*)(p + 4) = v1; }
;   else if (mode == 2) { f32x4 s0, s1; for (int i = 0; i < 4; ++i) { s0[i] = sigmoidf_(v0[i]); s1[i] = sigmoidf_(v1[i]); } *(u32x4*)((bf16_t*)jb.out + (size_t)row * jb.ldo + col) = pack8(s0, s1); }
;   else if (mode == 7) {
;     const u32x4 g = *(const u32x4*)((const bf16_t*)jb.aux + (size_t)row * NGATE + 2 * 2048 + col);
;     const f32x4 g0 = {bf_lo(g.x), bf_hi(g.x), bf_lo(g.y), bf_hi(g.y)}, g1 = {bf_lo(g.z), bf_hi(g.z), bf_lo(g.w), bf_hi(g.w)};
;     *(u32x4*)((bf16_t*)jb.out + (size_t)row * 2048 + col) = pack8(g0 * v0, g1 * v1);
;   } else {
;     const float* xp = (const float*)jb.aux + (size_t)row * jb.ldo + col; const float* gp = (const float*)jb.aux2 + col;
;     float* op = (float*)jb.out + (size_t)row * jb.ldo + col;
;     const f32x4 x0 = *(const f32x4*)xp, x1 = *(const f32x4*)(xp + 4), t0 = *(const f32x4*)gp, t1 = *(const f32x4*)(gp + 4);
;     *(f32x4*)op = x0 + t0 * v0; *(f32x4*)(op + 4) = x1 + t1 * v1;
.LBB0_456:
	s_and_b64 vcc, exec, s[8:9]
	s_cbranch_vccz .LBB0_458
	v_mad_i64_i32 v[124:125], s[0:1], v132, s29, 0
	v_lshlrev_b64 v[124:125], 2, v[124:125]
	v_lshl_add_u64 v[126:127], s[94:95], 0, v[124:125]
	v_lshlrev_b64 v[128:129], 2, v[130:131]
	v_lshl_add_u64 v[134:135], v[126:127], 0, v[128:129]
	v_lshl_add_u64 v[142:143], s[88:89], 0, v[128:129]
	v_lshl_add_u64 v[124:125], s[90:91], 0, v[124:125]
	v_lshl_add_u64 v[128:129], v[124:125], 0, v[128:129]
	global_load_dwordx4 v[124:127], v[134:135], off offset:512
	s_nop 0
	global_load_dwordx4 v[134:137], v[134:135], off offset:528
	s_nop 0
	global_load_dwordx4 v[138:141], v[142:143], off offset:512
	s_nop 0
	global_load_dwordx4 v[142:145], v[142:143], off offset:528
	s_mov_b64 s[10:11], 0
	s_waitcnt vmcnt(0) lgkmcnt(0)
	v_pk_fma_f32 v[126:127], v[120:121], v[140:141], v[126:127]
	v_pk_fma_f32 v[124:125], v[118:119], v[138:139], v[124:125]
	global_store_dwordx4 v[128:129], v[124:127], off offset:512
	s_nop 1
	v_pk_fma_f32 v[126:127], v[116:117], v[144:145], v[136:137]
	v_pk_fma_f32 v[124:125], v[114:115], v[142:143], v[134:135]
	global_store_dwordx4 v[128:129], v[124:127], off offset:528
.LBB0_458:
	s_andn2_b64 vcc, exec, s[10:11]
	s_cbranch_vccnz .LBB0_460
	v_cvt_pk_bf16_f32 v118, v118, v119
	v_cvt_pk_bf16_f32 v119, v120, v121
	v_cvt_pk_bf16_f32 v120, v114, v115
	v_mad_i64_i32 v[114:115], s[0:1], v132, s29, 0
	v_lshl_add_u64 v[114:115], v[114:115], 1, s[90:91]
	v_lshl_add_u64 v[114:115], v[130:131], 1, v[114:115]
	v_cvt_pk_bf16_f32 v121, v116, v117
	global_store_dwordx4 v[114:115], v[118:121], off offset:256
.LBB0_460:
	v_or_b32_e32 v114, 16, v132
	v_ashrrev_i32_e32 v115, 31, v114
	v_mad_i64_i32 v[118:119], s[0:1], v114, s33, 0
	v_lshlrev_b64 v[116:117], 12, v[114:115]
	s_mov_b64 s[12:13], -1
	s_mov_b64 s[10:11], 0
	s_cmp_lt_i32 s71, 2
	s_mov_b64 s[8:9], 0
	s_cbranch_scc1 .LBB0_469
	s_cmp_gt_i32 s71, 6
	s_cbranch_scc0 .LBB0_465
	s_cmp_eq_u32 s71, 7
	s_mov_b64 s[8:9], -1
	s_cbranch_scc0 .LBB0_464
	v_lshl_add_u64 v[120:121], s[94:95], 0, v[118:119]
	v_lshlrev_b64 v[128:129], 1, v[130:131]
	v_lshl_add_u64 v[120:121], v[120:121], 0, v[128:129]
	v_add_co_u32_e32 v120, vcc, 0x2000, v120
	s_mov_b64 s[8:9], 0
	s_nop 0
	v_addc_co_u32_e32 v121, vcc, 0, v121, vcc
	global_load_dwordx4 v[124:127], v[120:121], off
	v_lshl_add_u64 v[120:121], s[90:91], 0, v[116:117]
	v_lshl_add_u64 v[120:121], v[120:121], 0, v[128:129]
	s_waitcnt vmcnt(0) lgkmcnt(0)
	v_lshlrev_b32_e32 v128, 16, v124
	v_and_b32_e32 v129, 0xffff0000, v124
	v_lshlrev_b32_e32 v124, 16, v125
	v_and_b32_e32 v125, 0xffff0000, v125
	v_lshlrev_b32_e32 v134, 16, v126
	v_and_b32_e32 v135, 0xffff0000, v126
	v_lshlrev_b32_e32 v126, 16, v127
	v_and_b32_e32 v127, 0xffff0000, v127
	v_pk_mul_f32 v[136:137], v[112:113], v[124:125]
	v_pk_mul_f32 v[124:125], v[110:111], v[128:129]
	v_pk_mul_f32 v[128:129], v[108:109], v[126:127]
	v_pk_mul_f32 v[126:127], v[106:107], v[134:135]
	v_cvt_pk_bf16_f32 v124, v124, v125
	v_cvt_pk_bf16_f32 v125, v136, v137
	s_nop 0
	v_cvt_pk_bf16_f32 v126, v126, v127
	v_cvt_pk_bf16_f32 v127, v128, v129
	global_store_dwordx4 v[120:121], v[124:127], off

; DEVI u32x4 pack8(f32x4 a, f32x4 b) { u32x4 o; o.x = cvt_pk_bf16(a[0], a[1]); o.y = cvt_pk_bf16(a[2], a[3]); o.z = cvt_pk_bf16(b[0], b[1]); o.w = cvt_pk_bf16(b[2], b[3]); return o; }
; DEVI float sigmoidf_(float x) { return 1.f / (1.f + __expf(-x)); }
; DEVI void gemm_epi(const GJob& jb, int row, int col, f32x4 v0, f32x4 v1) {
;     ...
;   else if (mode == 2) { f32x4 s0, s1; for (int i = 0; i < 4; ++i) { s0[i] = sigmoidf_(v0[i]); s1[i] = sigmoidf_(v1[i]); } *(u32x4*)((bf16_t*)jb.out + (size_t)row * jb.ldo + col) = pack8(s0, s1); }
.LBB0_465:
	s_and_b64 vcc, exec, s[12:13]
	s_cbranch_vccz .LBB0_468
	s_cmp_eq_u32 s71, 2
	s_mov_b64 s[8:9], -1
	s_cbranch_scc0 .LBB0_468
	v_mul_f32_e32 v0, 0xbfb8aa3b, v110
	v_exp_f32_e32 v0, v0
	s_mov_b64 s[8:9], 0
	v_add_f32_e32 v0, 1.0, v0
	v_div_scale_f32 v115, s[0:1], v0, v0, 1.0
	v_rcp_f32_e32 v120, v115
	s_nop 0
	v_fma_f32 v121, -v115, v120, 1.0
	v_fmac_f32_e32 v120, v121, v120
	v_div_scale_f32 v121, vcc, 1.0, v0, 1.0
	v_mul_f32_e32 v123, v121, v120
	v_fma_f32 v124, -v115, v123, v121
	v_fmac_f32_e32 v123, v124, v120
	v_fma_f32 v115, -v115, v123, v121
	v_div_fmas_f32 v115, v115, v120, v123
	v_div_fixup_f32 v0, v115, v0, 1.0
	v_mul_f32_e32 v115, 0xbfb8aa3b, v106
	v_exp_f32_e32 v115, v115
	s_nop 0
	v_add_f32_e32 v115, 1.0, v115
	v_div_scale_f32 v120, s[0:1], v115, v115, 1.0
	v_rcp_f32_e32 v121, v120
	s_nop 0
	v_fma_f32 v123, -v120, v121, 1.0
	v_fmac_f32_e32 v121, v123, v121
	v_div_scale_f32 v123, vcc, 1.0, v115, 1.0
	v_mul_f32_e32 v124, v123, v121
	v_fma_f32 v125, -v120, v124, v123
	v_fmac_f32_e32 v124, v125, v121
	v_fma_f32 v120, -v120, v124, v123
	v_div_fmas_f32 v120, v120, v121, v124
	v_div_fixup_f32 v115, v120, v115, 1.0
	v_mul_f32_e32 v120, 0xbfb8aa3b, v111
	v_exp_f32_e32 v120, v120
	s_nop 0
	v_add_f32_e32 v120, 1.0, v120
	v_div_scale_f32 v121, s[0:1], v120, v120, 1.0
	v_rcp_f32_e32 v123, v121
	s_nop 0
	v_fma_f32 v124, -v121, v123, 1.0
	v_fmac_f32_e32 v123, v124, v123
	v_div_scale_f32 v124, vcc, 1.0, v120, 1.0
	v_mul_f32_e32 v125, v124, v123
	v_fma_f32 v126, -v121, v125, v124
	v_fmac_f32_e32 v125, v126, v123
	v_fma_f32 v121, -v121, v125, v124
	v_div_fmas_f32 v121, v121, v123, v125
	v_div_fixup_f32 v120, v121, v120, 1.0
	v_mul_f32_e32 v121, 0xbfb8aa3b, v107
	v_exp_f32_e32 v121, v121
	s_nop 0
	v_add_f32_e32 v121, 1.0, v121
	v_div_scale_f32 v123, s[0:1], v121, v121, 1.0
	v_rcp_f32_e32 v124, v123
	s_nop 0
	v_fma_f32 v125, -v123, v124, 1.0
	v_fmac_f32_e32 v124, v125, v124
	v_div_scale_f32 v125, vcc, 1.0, v121, 1.0
	v_mul_f32_e32 v126, v125, v124
	v_fma_f32 v127, -v123, v126, v125
	v_fmac_f32_e32 v126, v127, v124
	v_fma_f32 v123, -v123, v126, v125
	v_div_fmas_f32 v123, v123, v124, v126
	v_div_fixup_f32 v121, v123, v121, 1.0
	v_mul_f32_e32 v123, 0xbfb8aa3b, v112
	v_exp_f32_e32 v123, v123
	s_nop 0
	v_add_f32_e32 v123, 1.0, v123
	v_div_scale_f32 v124, s[0:1], v123, v123, 1.0
	v_rcp_f32_e32 v125, v124
	s_nop 0
	v_fma_f32 v126, -v124, v125, 1.0
	v_fmac_f32_e32 v125, v126, v125
	v_div_scale_f32 v126, vcc, 1.0, v123, 1.0
	v_mul_f32_e32 v127, v126, v125
	v_fma_f32 v128, -v124, v127, v126
	v_fmac_f32_e32 v127, v128, v125
	v_fma_f32 v124, -v124, v127, v126
	v_div_fmas_f32 v124, v124, v125, v127
	v_div_fixup_f32 v123, v124, v123, 1.0
	v_mul_f32_e32 v124, 0xbfb8aa3b, v108
	v_exp_f32_e32 v124, v124
	s_nop 0
	v_add_f32_e32 v124, 1.0, v124
	v_div_scale_f32 v125, s[0:1], v124, v124, 1.0
	v_rcp_f32_e32 v126, v125
	s_nop 0
	v_fma_f32 v127, -v125, v126, 1.0
	v_fmac_f32_e32 v126, v127, v126
	v_div_scale_f32 v127, vcc, 1.0, v124, 1.0
	v_mul_f32_e32 v128, v127, v126
	v_fma_f32 v129, -v125, v128, v127
	v_fmac_f32_e32 v128, v129, v126
	v_fma_f32 v125, -v125, v128, v127
	v_div_fmas_f32 v125, v125, v126, v128
	v_div_fixup_f32 v127, v125, v124, 1.0
	v_mul_f32_e32 v124, 0xbfb8aa3b, v113
	v_exp_f32_e32 v124, v124
	s_nop 0
	v_add_f32_e32 v124, 1.0, v124
	v_div_scale_f32 v125, s[0:1], v124, v124, 1.0
	v_rcp_f32_e32 v126, v125
	s_nop 0
	v_fma_f32 v128, -v125, v126, 1.0
	v_fmac_f32_e32 v126, v128, v126
	v_div_scale_f32 v128, vcc, 1.0, v124, 1.0
	v_mul_f32_e32 v129, v128, v126
	v_fma_f32 v133, -v125, v129, v128
	v_fmac_f32_e32 v129, v133, v126
	v_fma_f32 v125, -v125, v129, v128
	v_div_fmas_f32 v125, v125, v126, v129
	v_div_fixup_f32 v125, v125, v124, 1.0
	v_mul_f32_e32 v124, 0xbfb8aa3b, v109
	v_exp_f32_e32 v124, v124
	v_cvt_pk_bf16_f32 v125, v123, v125
	s_nop 0
	v_add_f32_e32 v124, 1.0, v124
	v_div_scale_f32 v126, s[0:1], v124, v124, 1.0
	v_rcp_f32_e32 v128, v126
	s_nop 0
	v_fma_f32 v129, -v126, v128, 1.0
	v_fmac_f32_e32 v128, v129, v128
	v_div_scale_f32 v129, vcc, 1.0, v124, 1.0
	v_mul_f32_e32 v133, v129, v128
	v_fma_f32 v134, -v126, v133, v129
	v_fmac_f32_e32 v133, v134, v128
	v_fma_f32 v126, -v126, v133, v129
	v_div_fmas_f32 v126, v126, v128, v133
	v_div_fixup_f32 v128, v126, v124, 1.0
	v_cvt_pk_bf16_f32 v124, v0, v120
	v_cvt_pk_bf16_f32 v126, v115, v121
	v_mad_i64_i32 v[120:121], s[0:1], v114, s29, 0
	v_lshl_add_u64 v[120:121], v[120:121], 1, s[90:91]
	v_lshl_add_u64 v[120:121], v[130:131], 1, v[120:121]
	v_cvt_pk_bf16_f32 v127, v127, v128
	global_store_dwordx4 v[120:121], v[124:127], off

; DEVI void gemm_epi(const GJob& jb, int row, int col, f32x4 v0, f32x4 v1) {
;     ...
;   else if (mode == 1) { float* p = (float*)jb.out + (size_t)row * jb.ldo + col; *(f32x4*)p = v0; *(f32x4*)(p + 4) = v1; }
.LBB0_469:
	s_and_b64 vcc, exec, s[12:13]
	s_cbranch_vccz .LBB0_474
	s_cmp_gt_i32 s71, 0
	s_mov_b64 s[10:11], -1
	s_cbranch_scc0 .LBB0_472
	v_mad_i64_i32 v[120:121], s[0:1], v114, s29, 0
	v_lshl_add_u64 v[120:121], v[120:121], 2, s[90:91]
	v_lshl_add_u64 v[120:121], v[130:131], 2, v[120:121]
	global_store_dwordx4 v[120:121], v[110:113], off
	global_store_dwordx4 v[120:121], v[106:109], off offset:16
	s_mov_b64 s[10:11], 0

; DEVI float bf_lo(unsigned u) { return __uint_as_float(u << 16); }
; DEVI float bf_hi(unsigned u) { return __uint_as_float(u & 0xffff0000u); }
; DEVI float sigmoidf_(float x) { return 1.f / (1.f + __expf(-x)); }
; DEVI u32x4 pack8(f32x4 a, f32x4 b) { u32x4 o; o.x = cvt_pk_bf16(a[0], a[1]); o.y = cvt_pk_bf16(a[2], a[3]); o.z = cvt_pk_bf16(b[0], b[1]); o.w = cvt_pk_bf16(b[2], b[3]); return o; }
; DEVI void gemm_epi(const GJob& jb, int row, int col, f32x4 v0, f32x4 v1) {
;     ...
;   if (mode == 0) { *(u32x4*)((bf16_t*)jb.out + (size_t)row * jb.ldo + col) = pack8(v0, v1); }
;   else if (mode == 1) { float* p = (float*)jb.out + (size_t)row * jb.ldo + col; *(f32x4*)p = v0; *(f32x4*)(p + 4) = v1; }
;   else if (mode == 2) { f32x4 s0, s1; for (int i = 0; i < 4; ++i) { s0[i] = sigmoidf_(v0[i]); s1[i] = sigmoidf_(v1[i]); } *(u32x4*)((bf16_t*)jb.out + (size_t)row * jb.ldo + col) = pack8(s0, s1); }
;   else if (mode == 7) {
;     const u32x4 g = *(const u32x4*)((const bf16_t*)jb.aux + (size_t)row * NGATE + 2 * 2048 + col);
;     const f32x4 g0 = {bf_lo(g.x), bf_hi(g.x), bf_lo(g.y), bf_hi(g.y)}, g1 = {bf_lo(g.z), bf_hi(g.z), bf_lo(g.w), bf_hi(g.w)};
;     *(u32x4*)((bf16_t*)jb.out + (size_t)row * 2048 + col) = pack8(g0 * v0, g1 * v1);
;   } else {
;     const float* xp = (const float*)jb.aux + (size_t)row * jb.ldo + col; const float* gp = (const float*)jb.aux2 + col;
;     float* op = (float*)jb.out + (size_t)row * jb.ldo + col;
;     const f32x4 x0 = *(const f32x4*)xp, x1 = *(const f32x4*)(xp + 4), t0 = *(const f32x4*)gp, t1 = *(const f32x4*)(gp + 4);
;     *(f32x4*)op = x0 + t0 * v0; *(f32x4*)(op + 4) = x1 + t1 * v1;
.LBB0_474:
	s_and_b64 vcc, exec, s[8:9]
	s_cbranch_vccz .LBB0_476
	v_mad_i64_i32 v[120:121], s[0:1], v114, s29, 0
	v_lshlrev_b64 v[120:121], 2, v[120:121]
	v_lshl_add_u64 v[124:125], s[94:95], 0, v[120:121]
	v_lshlrev_b64 v[126:127], 2, v[130:131]
	v_lshl_add_u64 v[128:129], v[124:125], 0, v[126:127]
	v_lshl_add_u64 v[142:143], s[88:89], 0, v[126:127]
	v_lshl_add_u64 v[120:121], s[90:91], 0, v[120:121]
	v_lshl_add_u64 v[120:121], v[120:121], 0, v[126:127]
	global_load_dwordx4 v[124:127], v[128:129], off
	global_load_dwordx4 v[134:137], v[128:129], off offset:16
	global_load_dwordx4 v[138:141], v[142:143], off
	s_nop 0
	global_load_dwordx4 v[142:145], v[142:143], off offset:16
	s_mov_b64 s[10:11], 0
	s_waitcnt vmcnt(0) lgkmcnt(0)
	v_pk_fma_f32 v[126:127], v[112:113], v[140:141], v[126:127]
	v_pk_fma_f32 v[124:125], v[110:111], v[138:139], v[124:125]
	global_store_dwordx4 v[120:121], v[124:127], off
	s_nop 1
	v_pk_fma_f32 v[126:127], v[108:109], v[144:145], v[136:137]
	v_pk_fma_f32 v[124:125], v[106:107], v[142:143], v[134:135]
	global_store_dwordx4 v[120:121], v[124:127], off offset:16
.LBB0_476:
	s_andn2_b64 vcc, exec, s[10:11]
	s_cbranch_vccnz .LBB0_478
	v_cvt_pk_bf16_f32 v110, v110, v111
	v_cvt_pk_bf16_f32 v111, v112, v113
	v_cvt_pk_bf16_f32 v112, v106, v107
	v_mad_i64_i32 v[106:107], s[0:1], v114, s29, 0
	v_lshl_add_u64 v[106:107], v[106:107], 1, s[90:91]
	v_lshl_add_u64 v[106:107], v[130:131], 1, v[106:107]
	v_cvt_pk_bf16_f32 v113, v108, v109
	global_store_dwordx4 v[106:107], v[110:113], off
.LBB0_478:
	s_mov_b64 s[12:13], -1
	s_mov_b64 s[10:11], 0
	s_cmp_lt_i32 s71, 2
	s_mov_b64 s[8:9], 0
	s_cbranch_scc1 .LBB0_487
	s_cmp_gt_i32 s71, 6
	s_cbranch_scc0 .LBB0_483
	s_cmp_eq_u32 s71, 7
	s_mov_b64 s[8:9], -1
	s_cbranch_scc0 .LBB0_482
	v_lshl_add_u64 v[106:107], s[94:95], 0, v[118:119]
	v_ashrrev_i32_e32 v123, 31, v122
	v_lshl_add_u64 v[106:107], v[122:123], 1, v[106:107]
	v_add_co_u32_e32 v106, vcc, 0x2000, v106
	v_lshl_add_u64 v[110:111], s[90:91], 0, v[116:117]
	s_nop 0
	v_addc_co_u32_e32 v107, vcc, 0, v107, vcc
	global_load_dwordx4 v[106:109], v[106:107], off
	v_lshl_add_u64 v[110:111], v[130:131], 1, v[110:111]
	s_mov_b64 s[8:9], 0
	s_waitcnt vmcnt(0) lgkmcnt(0)
	v_lshlrev_b32_e32 v112, 16, v106
	v_and_b32_e32 v113, 0xffff0000, v106
	v_lshlrev_b32_e32 v106, 16, v107
	v_and_b32_e32 v107, 0xffff0000, v107
	v_lshlrev_b32_e32 v116, 16, v108
	v_and_b32_e32 v117, 0xffff0000, v108
	v_lshlrev_b32_e32 v108, 16, v109
	v_and_b32_e32 v109, 0xffff0000, v109
	v_pk_mul_f32 v[118:119], v[104:105], v[106:107]
	v_pk_mul_f32 v[106:107], v[102:103], v[112:113]
	v_pk_mul_f32 v[112:113], v[100:101], v[108:109]
	v_pk_mul_f32 v[108:109], v[98:99], v[116:117]
	v_cvt_pk_bf16_f32 v106, v106, v107
	v_cvt_pk_bf16_f32 v107, v118, v119
	s_nop 0
	v_cvt_pk_bf16_f32 v108, v108, v109
	v_cvt_pk_bf16_f32 v109, v112, v113
	global_store_dwordx4 v[110:111], v[106:109], off offset:256

; DEVI u32x4 pack8(f32x4 a, f32x4 b) { u32x4 o; o.x = cvt_pk_bf16(a[0], a[1]); o.y = cvt_pk_bf16(a[2], a[3]); o.z = cvt_pk_bf16(b[0], b[1]); o.w = cvt_pk_bf16(b[2], b[3]); return o; }
; DEVI float sigmoidf_(float x) { return 1.f / (1.f + __expf(-x)); }
; DEVI void gemm_epi(const GJob& jb, int row, int col, f32x4 v0, f32x4 v1) {
;     ...
;   else if (mode == 2) { f32x4 s0, s1; for (int i = 0; i < 4; ++i) { s0[i] = sigmoidf_(v0[i]); s1[i] = sigmoidf_(v1[i]); } *(u32x4*)((bf16_t*)jb.out + (size_t)row * jb.ldo + col) = pack8(s0, s1); }
.LBB0_483:
	s_and_b64 vcc, exec, s[12:13]
	s_cbranch_vccz .LBB0_486
	s_cmp_eq_u32 s71, 2
	s_mov_b64 s[8:9], -1
	s_cbranch_scc0 .LBB0_486
	v_mul_f32_e32 v0, 0xbfb8aa3b, v102
	v_exp_f32_e32 v0, v0
	s_mov_b64 s[8:9], 0
	v_add_f32_e32 v0, 1.0, v0
	v_div_scale_f32 v106, s[0:1], v0, v0, 1.0
	v_rcp_f32_e32 v107, v106
	s_nop 0
	v_fma_f32 v108, -v106, v107, 1.0
	v_fmac_f32_e32 v107, v108, v107
	v_div_scale_f32 v108, vcc, 1.0, v0, 1.0
	v_mul_f32_e32 v109, v108, v107
	v_fma_f32 v110, -v106, v109, v108
	v_fmac_f32_e32 v109, v110, v107
	v_fma_f32 v106, -v106, v109, v108
	v_div_fmas_f32 v106, v106, v107, v109
	v_div_fixup_f32 v0, v106, v0, 1.0
	v_mul_f32_e32 v106, 0xbfb8aa3b, v98
	v_exp_f32_e32 v106, v106
	s_nop 0
	v_add_f32_e32 v106, 1.0, v106
	v_div_scale_f32 v107, s[0:1], v106, v106, 1.0
	v_rcp_f32_e32 v108, v107
	s_nop 0
	v_fma_f32 v109, -v107, v108, 1.0
	v_fmac_f32_e32 v108, v109, v108
	v_div_scale_f32 v109, vcc, 1.0, v106, 1.0
	v_mul_f32_e32 v110, v109, v108
	v_fma_f32 v111, -v107, v110, v109
	v_fmac_f32_e32 v110, v111, v108
	v_fma_f32 v107, -v107, v110, v109
	v_div_fmas_f32 v107, v107, v108, v110
	v_div_fixup_f32 v108, v107, v106, 1.0
	v_mul_f32_e32 v106, 0xbfb8aa3b, v103
	v_exp_f32_e32 v106, v106
	s_nop 0
	v_add_f32_e32 v106, 1.0, v106
	v_div_scale_f32 v107, s[0:1], v106, v106, 1.0
	v_rcp_f32_e32 v109, v107
	s_nop 0
	v_fma_f32 v110, -v107, v109, 1.0
	v_fmac_f32_e32 v109, v110, v109
	v_div_scale_f32 v110, vcc, 1.0, v106, 1.0
	v_mul_f32_e32 v111, v110, v109
	v_fma_f32 v112, -v107, v111, v110
	v_fmac_f32_e32 v111, v112, v109
	v_fma_f32 v107, -v107, v111, v110
	v_div_fmas_f32 v107, v107, v109, v111
	v_div_fixup_f32 v106, v107, v106, 1.0
	v_mul_f32_e32 v107, 0xbfb8aa3b, v99
	v_exp_f32_e32 v107, v107
	v_cvt_pk_bf16_f32 v106, v0, v106
	s_nop 0
	v_add_f32_e32 v107, 1.0, v107
	v_div_scale_f32 v109, s[0:1], v107, v107, 1.0
	v_rcp_f32_e32 v110, v109
	s_nop 0
	v_fma_f32 v111, -v109, v110, 1.0
	v_fmac_f32_e32 v110, v111, v110
	v_div_scale_f32 v111, vcc, 1.0, v107, 1.0
	v_mul_f32_e32 v112, v111, v110
	v_fma_f32 v113, -v109, v112, v111
	v_fmac_f32_e32 v112, v113, v110
	v_fma_f32 v109, -v109, v112, v111
	v_div_fmas_f32 v109, v109, v110, v112
	v_div_fixup_f32 v109, v109, v107, 1.0
	v_mul_f32_e32 v107, 0xbfb8aa3b, v104
	v_exp_f32_e32 v107, v107
	v_cvt_pk_bf16_f32 v108, v108, v109
	s_nop 0
	v_add_f32_e32 v107, 1.0, v107
	v_div_scale_f32 v110, s[0:1], v107, v107, 1.0
	v_rcp_f32_e32 v111, v110
	s_nop 0
	v_fma_f32 v112, -v110, v111, 1.0
	v_fmac_f32_e32 v111, v112, v111
	v_div_scale_f32 v112, vcc, 1.0, v107, 1.0
	v_mul_f32_e32 v113, v112, v111
	v_fma_f32 v115, -v110, v113, v112
	v_fmac_f32_e32 v113, v115, v111
	v_fma_f32 v110, -v110, v113, v112
	v_div_fmas_f32 v110, v110, v111, v113
	v_div_fixup_f32 v107, v110, v107, 1.0
	v_mul_f32_e32 v110, 0xbfb8aa3b, v100
	v_exp_f32_e32 v110, v110
	s_nop 0
	v_add_f32_e32 v110, 1.0, v110
	v_div_scale_f32 v111, s[0:1], v110, v110, 1.0
	v_rcp_f32_e32 v112, v111
	s_nop 0
	v_fma_f32 v113, -v111, v112, 1.0
	v_fmac_f32_e32 v112, v113, v112
	v_div_scale_f32 v113, vcc, 1.0, v110, 1.0
	v_mul_f32_e32 v115, v113, v112
	v_fma_f32 v116, -v111, v115, v113
	v_fmac_f32_e32 v115, v116, v112
	v_fma_f32 v111, -v111, v115, v113
	v_div_fmas_f32 v111, v111, v112, v115
	v_div_fixup_f32 v110, v111, v110, 1.0
	v_mul_f32_e32 v111, 0xbfb8aa3b, v105
	v_exp_f32_e32 v111, v111
	s_nop 0
	v_add_f32_e32 v111, 1.0, v111
	v_div_scale_f32 v112, s[0:1], v111, v111, 1.0
	v_rcp_f32_e32 v113, v112
	s_nop 0
	v_fma_f32 v115, -v112, v113, 1.0
	v_fmac_f32_e32 v113, v115, v113
	v_div_scale_f32 v115, vcc, 1.0, v111, 1.0
	v_mul_f32_e32 v116, v115, v113
	v_fma_f32 v117, -v112, v116, v115
	v_fmac_f32_e32 v116, v117, v113
	v_fma_f32 v112, -v112, v116, v115
	v_div_fmas_f32 v112, v112, v113, v116
	v_div_fixup_f32 v111, v112, v111, 1.0
	v_mul_f32_e32 v112, 0xbfb8aa3b, v101
	v_exp_f32_e32 v112, v112
	v_cvt_pk_bf16_f32 v107, v107, v111
	s_nop 0
	v_add_f32_e32 v112, 1.0, v112
	v_div_scale_f32 v113, s[0:1], v112, v112, 1.0
	v_rcp_f32_e32 v115, v113
	s_nop 0
	v_fma_f32 v116, -v113, v115, 1.0
	v_fmac_f32_e32 v115, v116, v115
	v_div_scale_f32 v116, vcc, 1.0, v112, 1.0
	v_mul_f32_e32 v117, v116, v115
	v_fma_f32 v118, -v113, v117, v116
	v_fmac_f32_e32 v117, v118, v115
	v_fma_f32 v113, -v113, v117, v116
	v_div_fmas_f32 v113, v113, v115, v117
	v_div_fixup_f32 v112, v113, v112, 1.0
	v_cvt_pk_bf16_f32 v109, v110, v112
	v_mad_i64_i32 v[110:111], s[0:1], v114, s29, 0
	v_lshl_add_u64 v[110:111], v[110:111], 1, s[90:91]
	v_lshl_add_u64 v[110:111], v[130:131], 1, v[110:111]
	global_store_dwordx4 v[110:111], v[106:109], off offset:256

; DEVI void gemm_epi(const GJob& jb, int row, int col, f32x4 v0, f32x4 v1) {
;     ...
;   else if (mode == 1) { float* p = (float*)jb.out + (size_t)row * jb.ldo + col; *(f32x4*)p = v0; *(f32x4*)(p + 4) = v1; }
.LBB0_487:
	s_and_b64 vcc, exec, s[12:13]
	s_cbranch_vccz .LBB0_492
	s_cmp_gt_i32 s71, 0
	s_mov_b64 s[10:11], -1
	s_cbranch_scc0 .LBB0_490
	v_mad_i64_i32 v[106:107], s[0:1], v114, s29, 0
	v_lshl_add_u64 v[106:107], v[106:107], 2, s[90:91]
	v_lshl_add_u64 v[106:107], v[130:131], 2, v[106:107]
	global_store_dwordx4 v[106:107], v[102:105], off offset:512
	global_store_dwordx4 v[106:107], v[98:101], off offset:528
	s_mov_b64 s[10:11], 0

; DEVI float bf_lo(unsigned u) { return __uint_as_float(u << 16); }
; DEVI float bf_hi(unsigned u) { return __uint_as_float(u & 0xffff0000u); }
; DEVI float sigmoidf_(float x) { return 1.f / (1.f + __expf(-x)); }
; DEVI u32x4 pack8(f32x4 a, f32x4 b) { u32x4 o; o.x = cvt_pk_bf16(a[0], a[1]); o.y = cvt_pk_bf16(a[2], a[3]); o.z = cvt_pk_bf16(b[0], b[1]); o.w = cvt_pk_bf16(b[2], b[3]); return o; }
; DEVI void gemm_epi(const GJob& jb, int row, int col, f32x4 v0, f32x4 v1) {
;     ...
;   if (mode == 0) { *(u32x4*)((bf16_t*)jb.out + (size_t)row * jb.ldo + col) = pack8(v0, v1); }
;   else if (mode == 1) { float* p = (float*)jb.out + (size_t)row * jb.ldo + col; *(f32x4*)p = v0; *(f32x4*)(p + 4) = v1; }
;   else if (mode == 2) { f32x4 s0, s1; for (int i = 0; i < 4; ++i) { s0[i] = sigmoidf_(v0[i]); s1[i] = sigmoidf_(v1[i]); } *(u32x4*)((bf16_t*)jb.out + (size_t)row * jb.ldo + col) = pack8(s0, s1); }
;   else if (mode == 7) {
;     const u32x4 g = *(const u32x4*)((const bf16_t*)jb.aux + (size_t)row * NGATE + 2 * 2048 + col);
;     const f32x4 g0 = {bf_lo(g.x), bf_hi(g.x), bf_lo(g.y), bf_hi(g.y)}, g1 = {bf_lo(g.z), bf_hi(g.z), bf_lo(g.w), bf_hi(g.w)};
;     *(u32x4*)((bf16_t*)jb.out + (size_t)row * 2048 + col) = pack8(g0 * v0, g1 * v1);
;   } else {
;     const float* xp = (const float*)jb.aux + (size_t)row * jb.ldo + col; const float* gp = (const float*)jb.aux2 + col;
;     float* op = (float*)jb.out + (size_t)row * jb.ldo + col;
;     const f32x4 x0 = *(const f32x4*)xp, x1 = *(const f32x4*)(xp + 4), t0 = *(const f32x4*)gp, t1 = *(const f32x4*)(gp + 4);
;     *(f32x4*)op = x0 + t0 * v0; *(f32x4*)(op + 4) = x1 + t1 * v1;
.LBB0_492:
	s_and_b64 vcc, exec, s[8:9]
	s_cbranch_vccz .LBB0_494
	v_mad_i64_i32 v[106:107], s[0:1], v114, s29, 0
	v_lshlrev_b64 v[106:107], 2, v[106:107]
	v_lshl_add_u64 v[108:109], s[94:95], 0, v[106:107]
	v_lshlrev_b64 v[110:111], 2, v[130:131]
	v_lshl_add_u64 v[112:113], v[108:109], 0, v[110:111]
	v_lshl_add_u64 v[106:107], s[90:91], 0, v[106:107]
	v_lshl_add_u64 v[120:121], s[88:89], 0, v[110:111]
	v_lshl_add_u64 v[128:129], v[106:107], 0, v[110:111]
	global_load_dwordx4 v[106:109], v[112:113], off offset:512
	s_nop 0
	global_load_dwordx4 v[110:113], v[112:113], off offset:528
	s_nop 0
	global_load_dwordx4 v[116:119], v[120:121], off offset:512
	global_load_dwordx4 v[124:127], v[120:121], off offset:528
	s_mov_b64 s[10:11], 0
	s_waitcnt vmcnt(0) lgkmcnt(0)
	v_pk_fma_f32 v[108:109], v[104:105], v[118:119], v[108:109]
	v_pk_fma_f32 v[106:107], v[102:103], v[116:117], v[106:107]
	global_store_dwordx4 v[128:129], v[106:109], off offset:512
	s_nop 1
	v_pk_fma_f32 v[108:109], v[100:101], v[126:127], v[112:113]
	v_pk_fma_f32 v[106:107], v[98:99], v[124:125], v[110:111]
	global_store_dwordx4 v[128:129], v[106:109], off offset:528
.LBB0_494:
	s_andn2_b64 vcc, exec, s[10:11]
	s_cbranch_vccnz .LBB0_496
	v_cvt_pk_bf16_f32 v102, v102, v103
	v_cvt_pk_bf16_f32 v103, v104, v105
	v_cvt_pk_bf16_f32 v104, v98, v99
	v_mad_i64_i32 v[98:99], s[0:1], v114, s29, 0
	v_lshl_add_u64 v[98:99], v[98:99], 1, s[90:91]
	v_lshl_add_u64 v[98:99], v[130:131], 1, v[98:99]
	v_cvt_pk_bf16_f32 v105, v100, v101
	global_store_dwordx4 v[98:99], v[102:105], off offset:256
.LBB0_496:
	v_or_b32_e32 v98, 32, v132
	v_ashrrev_i32_e32 v99, 31, v98
	v_mad_i64_i32 v[102:103], s[0:1], v98, s33, 0
	v_lshlrev_b64 v[100:101], 12, v[98:99]
	s_mov_b64 s[12:13], -1
	s_mov_b64 s[10:11], 0
	s_cmp_lt_i32 s71, 2
	s_mov_b64 s[8:9], 0
	s_cbranch_scc1 .LBB0_505
	s_cmp_gt_i32 s71, 6
	s_cbranch_scc0 .LBB0_501
	s_cmp_eq_u32 s71, 7
	s_mov_b64 s[8:9], -1
	s_cbranch_scc0 .LBB0_500
	v_lshl_add_u64 v[104:105], s[94:95], 0, v[102:103]
	v_lshlrev_b64 v[108:109], 1, v[130:131]
	v_lshl_add_u64 v[104:105], v[104:105], 0, v[108:109]
	v_add_co_u32_e32 v104, vcc, 0x2000, v104
	v_lshl_add_u64 v[110:111], s[90:91], 0, v[100:101]
	s_nop 0
	v_addc_co_u32_e32 v105, vcc, 0, v105, vcc
	global_load_dwordx4 v[104:107], v[104:105], off
	v_lshl_add_u64 v[108:109], v[110:111], 0, v[108:109]
	s_mov_b64 s[8:9], 0
	s_waitcnt vmcnt(0) lgkmcnt(0)
	v_lshlrev_b32_e32 v110, 16, v104
	v_and_b32_e32 v111, 0xffff0000, v104
	v_lshlrev_b32_e32 v104, 16, v105
	v_and_b32_e32 v105, 0xffff0000, v105
	v_lshlrev_b32_e32 v112, 16, v106
	v_and_b32_e32 v113, 0xffff0000, v106
	v_lshlrev_b32_e32 v106, 16, v107
	v_and_b32_e32 v107, 0xffff0000, v107
	v_pk_mul_f32 v[114:115], v[96:97], v[104:105]
	v_pk_mul_f32 v[104:105], v[94:95], v[110:111]
	v_pk_mul_f32 v[110:111], v[92:93], v[106:107]
	v_pk_mul_f32 v[106:107], v[90:91], v[112:113]
	v_cvt_pk_bf16_f32 v104, v104, v105
	v_cvt_pk_bf16_f32 v105, v114, v115
	s_nop 0
	v_cvt_pk_bf16_f32 v106, v106, v107
	v_cvt_pk_bf16_f32 v107, v110, v111
	global_store_dwordx4 v[108:109], v[104:107], off

; DEVI u32x4 pack8(f32x4 a, f32x4 b) { u32x4 o; o.x = cvt_pk_bf16(a[0], a[1]); o.y = cvt_pk_bf16(a[2], a[3]); o.z = cvt_pk_bf16(b[0], b[1]); o.w = cvt_pk_bf16(b[2], b[3]); return o; }
; DEVI float sigmoidf_(float x) { return 1.f / (1.f + __expf(-x)); }
; DEVI void gemm_epi(const GJob& jb, int row, int col, f32x4 v0, f32x4 v1) {
;     ...
;   else if (mode == 2) { f32x4 s0, s1; for (int i = 0; i < 4; ++i) { s0[i] = sigmoidf_(v0[i]); s1[i] = sigmoidf_(v1[i]); } *(u32x4*)((bf16_t*)jb.out + (size_t)row * jb.ldo + col) = pack8(s0, s1); }
.LBB0_501:
	s_and_b64 vcc, exec, s[12:13]
	s_cbranch_vccz .LBB0_504
	s_cmp_eq_u32 s71, 2
	s_mov_b64 s[8:9], -1
	s_cbranch_scc0 .LBB0_504
	v_mul_f32_e32 v0, 0xbfb8aa3b, v94
	v_exp_f32_e32 v0, v0
	s_mov_b64 s[8:9], 0
	v_add_f32_e32 v0, 1.0, v0
	v_div_scale_f32 v99, s[0:1], v0, v0, 1.0
	v_rcp_f32_e32 v104, v99
	s_nop 0
	v_fma_f32 v105, -v99, v104, 1.0
	v_fmac_f32_e32 v104, v105, v104
	v_div_scale_f32 v105, vcc, 1.0, v0, 1.0
	v_mul_f32_e32 v106, v105, v104
	v_fma_f32 v107, -v99, v106, v105
	v_fmac_f32_e32 v106, v107, v104
	v_fma_f32 v99, -v99, v106, v105
	v_div_fmas_f32 v99, v99, v104, v106
	v_div_fixup_f32 v0, v99, v0, 1.0
	v_mul_f32_e32 v99, 0xbfb8aa3b, v90
	v_exp_f32_e32 v99, v99
	s_nop 0
	v_add_f32_e32 v99, 1.0, v99
	v_div_scale_f32 v104, s[0:1], v99, v99, 1.0
	v_rcp_f32_e32 v105, v104
	s_nop 0
	v_fma_f32 v106, -v104, v105, 1.0
	v_fmac_f32_e32 v105, v106, v105
	v_div_scale_f32 v106, vcc, 1.0, v99, 1.0
	v_mul_f32_e32 v107, v106, v105
	v_fma_f32 v108, -v104, v107, v106
	v_fmac_f32_e32 v107, v108, v105
	v_fma_f32 v104, -v104, v107, v106
	v_div_fmas_f32 v104, v104, v105, v107
	v_div_fixup_f32 v99, v104, v99, 1.0
	v_mul_f32_e32 v104, 0xbfb8aa3b, v95
	v_exp_f32_e32 v104, v104
	s_nop 0
	v_add_f32_e32 v104, 1.0, v104
	v_div_scale_f32 v105, s[0:1], v104, v104, 1.0
	v_rcp_f32_e32 v106, v105
	s_nop 0
	v_fma_f32 v107, -v105, v106, 1.0
	v_fmac_f32_e32 v106, v107, v106
	v_div_scale_f32 v107, vcc, 1.0, v104, 1.0
	v_mul_f32_e32 v108, v107, v106
	v_fma_f32 v109, -v105, v108, v107
	v_fmac_f32_e32 v108, v109, v106
	v_fma_f32 v105, -v105, v108, v107
	v_div_fmas_f32 v105, v105, v106, v108
	v_div_fixup_f32 v104, v105, v104, 1.0
	v_mul_f32_e32 v105, 0xbfb8aa3b, v91
	v_exp_f32_e32 v105, v105
	v_cvt_pk_bf16_f32 v104, v0, v104
	s_nop 0
	v_add_f32_e32 v105, 1.0, v105
	v_div_scale_f32 v106, s[0:1], v105, v105, 1.0
	v_rcp_f32_e32 v107, v106
	s_nop 0
	v_fma_f32 v108, -v106, v107, 1.0
	v_fmac_f32_e32 v107, v108, v107
	v_div_scale_f32 v108, vcc, 1.0, v105, 1.0
	v_mul_f32_e32 v109, v108, v107
	v_fma_f32 v110, -v106, v109, v108
	v_fmac_f32_e32 v109, v110, v107
	v_fma_f32 v106, -v106, v109, v108
	v_div_fmas_f32 v106, v106, v107, v109
	v_div_fixup_f32 v106, v106, v105, 1.0
	v_mul_f32_e32 v105, 0xbfb8aa3b, v96
	v_exp_f32_e32 v105, v105
	v_cvt_pk_bf16_f32 v106, v99, v106
	s_nop 0
	v_add_f32_e32 v105, 1.0, v105
	v_div_scale_f32 v107, s[0:1], v105, v105, 1.0
	v_rcp_f32_e32 v108, v107
	s_nop 0
	v_fma_f32 v109, -v107, v108, 1.0
	v_fmac_f32_e32 v108, v109, v108
	v_div_scale_f32 v109, vcc, 1.0, v105, 1.0
	v_mul_f32_e32 v110, v109, v108
	v_fma_f32 v111, -v107, v110, v109
	v_fmac_f32_e32 v110, v111, v108
	v_fma_f32 v107, -v107, v110, v109
	v_div_fmas_f32 v107, v107, v108, v110
	v_div_fixup_f32 v105, v107, v105, 1.0
	v_mul_f32_e32 v107, 0xbfb8aa3b, v92
	v_exp_f32_e32 v107, v107
	s_nop 0
	v_add_f32_e32 v107, 1.0, v107
	v_div_scale_f32 v108, s[0:1], v107, v107, 1.0
	v_rcp_f32_e32 v109, v108
	s_nop 0
	v_fma_f32 v110, -v108, v109, 1.0
	v_fmac_f32_e32 v109, v110, v109
	v_div_scale_f32 v110, vcc, 1.0, v107, 1.0
	v_mul_f32_e32 v111, v110, v109
	v_fma_f32 v112, -v108, v111, v110
	v_fmac_f32_e32 v111, v112, v109
	v_fma_f32 v108, -v108, v111, v110
	v_div_fmas_f32 v108, v108, v109, v111
	v_div_fixup_f32 v107, v108, v107, 1.0
	v_mul_f32_e32 v108, 0xbfb8aa3b, v97
	v_exp_f32_e32 v108, v108
	s_nop 0
	v_add_f32_e32 v108, 1.0, v108
	v_div_scale_f32 v109, s[0:1], v108, v108, 1.0
	v_rcp_f32_e32 v110, v109
	s_nop 0
	v_fma_f32 v111, -v109, v110, 1.0
	v_fmac_f32_e32 v110, v111, v110
	v_div_scale_f32 v111, vcc, 1.0, v108, 1.0
	v_mul_f32_e32 v112, v111, v110
	v_fma_f32 v113, -v109, v112, v111
	v_fmac_f32_e32 v112, v113, v110
	v_fma_f32 v109, -v109, v112, v111
	v_div_fmas_f32 v109, v109, v110, v112
	v_div_fixup_f32 v108, v109, v108, 1.0
	v_mul_f32_e32 v109, 0xbfb8aa3b, v93
	v_exp_f32_e32 v109, v109
	v_cvt_pk_bf16_f32 v105, v105, v108
	s_nop 0
	v_add_f32_e32 v109, 1.0, v109
	v_div_scale_f32 v110, s[0:1], v109, v109, 1.0
	v_rcp_f32_e32 v111, v110
	s_nop 0
	v_fma_f32 v112, -v110, v111, 1.0
	v_fmac_f32_e32 v111, v112, v111
	v_div_scale_f32 v112, vcc, 1.0, v109, 1.0
	v_mul_f32_e32 v113, v112, v111
	v_fma_f32 v114, -v110, v113, v112
	v_fmac_f32_e32 v113, v114, v111
	v_fma_f32 v110, -v110, v113, v112
	v_div_fmas_f32 v110, v110, v111, v113
	v_div_fixup_f32 v109, v110, v109, 1.0
	v_cvt_pk_bf16_f32 v107, v107, v109
	v_mad_i64_i32 v[108:109], s[0:1], v98, s29, 0
	v_lshl_add_u64 v[108:109], v[108:109], 1, s[90:91]
	v_lshl_add_u64 v[108:109], v[130:131], 1, v[108:109]
	global_store_dwordx4 v[108:109], v[104:107], off

; DEVI void gemm_epi(const GJob& jb, int row, int col, f32x4 v0, f32x4 v1) {
;     ...
;   else if (mode == 1) { float* p = (float*)jb.out + (size_t)row * jb.ldo + col; *(f32x4*)p = v0; *(f32x4*)(p + 4) = v1; }
.LBB0_505:
	s_and_b64 vcc, exec, s[12:13]
	s_cbranch_vccz .LBB0_510
	s_cmp_gt_i32 s71, 0
	s_mov_b64 s[10:11], -1
	s_cbranch_scc0 .LBB0_508
	v_mad_i64_i32 v[104:105], s[0:1], v98, s29, 0
	v_lshl_add_u64 v[104:105], v[104:105], 2, s[90:91]
	v_lshl_add_u64 v[104:105], v[130:131], 2, v[104:105]
	global_store_dwordx4 v[104:105], v[94:97], off
	global_store_dwordx4 v[104:105], v[90:93], off offset:16
	s_mov_b64 s[10:11], 0

; DEVI float bf_lo(unsigned u) { return __uint_as_float(u << 16); }
; DEVI float bf_hi(unsigned u) { return __uint_as_float(u & 0xffff0000u); }
; DEVI float sigmoidf_(float x) { return 1.f / (1.f + __expf(-x)); }
; DEVI u32x4 pack8(f32x4 a, f32x4 b) { u32x4 o; o.x = cvt_pk_bf16(a[0], a[1]); o.y = cvt_pk_bf16(a[2], a[3]); o.z = cvt_pk_bf16(b[0], b[1]); o.w = cvt_pk_bf16(b[2], b[3]); return o; }
; DEVI void gemm_epi(const GJob& jb, int row, int col, f32x4 v0, f32x4 v1) {
;     ...
;   if (mode == 0) { *(u32x4*)((bf16_t*)jb.out + (size_t)row * jb.ldo + col) = pack8(v0, v1); }
;   else if (mode == 1) { float* p = (float*)jb.out + (size_t)row * jb.ldo + col; *(f32x4*)p = v0; *(f32x4*)(p + 4) = v1; }
;   else if (mode == 2) { f32x4 s0, s1; for (int i = 0; i < 4; ++i) { s0[i] = sigmoidf_(v0[i]); s1[i] = sigmoidf_(v1[i]); } *(u32x4*)((bf16_t*)jb.out + (size_t)row * jb.ldo + col) = pack8(s0, s1); }
;   else if (mode == 7) {
;     const u32x4 g = *(const u32x4*)((const bf16_t*)jb.aux + (size_t)row * NGATE + 2 * 2048 + col);
;     const f32x4 g0 = {bf_lo(g.x), bf_hi(g.x), bf_lo(g.y), bf_hi(g.y)}, g1 = {bf_lo(g.z), bf_hi(g.z), bf_lo(g.w), bf_hi(g.w)};
;     *(u32x4*)((bf16_t*)jb.out + (size_t)row * 2048 + col) = pack8(g0 * v0, g1 * v1);
;   } else {
;     const float* xp = (const float*)jb.aux + (size_t)row * jb.ldo + col; const float* gp = (const float*)jb.aux2 + col;
;     float* op = (float*)jb.out + (size_t)row * jb.ldo + col;
;     const f32x4 x0 = *(const f32x4*)xp, x1 = *(const f32x4*)(xp + 4), t0 = *(const f32x4*)gp, t1 = *(const f32x4*)(gp + 4);
;     *(f32x4*)op = x0 + t0 * v0; *(f32x4*)(op + 4) = x1 + t1 * v1;
.LBB0_510:
	s_and_b64 vcc, exec, s[8:9]
	s_cbranch_vccz .LBB0_512
	v_mad_i64_i32 v[104:105], s[0:1], v98, s29, 0
	v_lshlrev_b64 v[104:105], 2, v[104:105]
	v_lshl_add_u64 v[106:107], s[94:95], 0, v[104:105]
	v_lshlrev_b64 v[108:109], 2, v[130:131]
	v_lshl_add_u64 v[110:111], v[106:107], 0, v[108:109]
	v_lshl_add_u64 v[116:117], s[88:89], 0, v[108:109]
	v_lshl_add_u64 v[104:105], s[90:91], 0, v[104:105]
	v_lshl_add_u64 v[120:121], v[104:105], 0, v[108:109]
	global_load_dwordx4 v[104:107], v[110:111], off
	s_nop 0
	global_load_dwordx4 v[108:111], v[110:111], off offset:16
	s_nop 0
	global_load_dwordx4 v[112:115], v[116:117], off
	s_nop 0
	global_load_dwordx4 v[116:119], v[116:117], off offset:16
	s_mov_b64 s[10:11], 0
	s_waitcnt vmcnt(0) lgkmcnt(0)
	v_pk_fma_f32 v[106:107], v[96:97], v[114:115], v[106:107]
	v_pk_fma_f32 v[104:105], v[94:95], v[112:113], v[104:105]
	global_store_dwordx4 v[120:121], v[104:107], off
	s_nop 1
	v_pk_fma_f32 v[106:107], v[92:93], v[118:119], v[110:111]
	v_pk_fma_f32 v[104:105], v[90:91], v[116:117], v[108:109]
	global_store_dwordx4 v[120:121], v[104:107], off offset:16
.LBB0_512:
	s_andn2_b64 vcc, exec, s[10:11]
	s_cbranch_vccnz .LBB0_514
	v_cvt_pk_bf16_f32 v94, v94, v95
	v_cvt_pk_bf16_f32 v95, v96, v97
	v_cvt_pk_bf16_f32 v96, v90, v91
	v_mad_i64_i32 v[90:91], s[0:1], v98, s29, 0
	v_lshl_add_u64 v[90:91], v[90:91], 1, s[90:91]
	v_lshl_add_u64 v[90:91], v[130:131], 1, v[90:91]
	v_cvt_pk_bf16_f32 v97, v92, v93
	global_store_dwordx4 v[90:91], v[94:97], off
.LBB0_514:
	s_mov_b64 s[12:13], -1
	s_mov_b64 s[10:11], 0
	s_cmp_lt_i32 s71, 2
	s_mov_b64 s[8:9], 0
	s_cbranch_scc1 .LBB0_523
	s_cmp_gt_i32 s71, 6
	s_cbranch_scc0 .LBB0_519
	s_cmp_eq_u32 s71, 7
	s_mov_b64 s[8:9], -1
	s_cbranch_scc0 .LBB0_518
	v_lshl_add_u64 v[90:91], s[94:95], 0, v[102:103]
	v_ashrrev_i32_e32 v123, 31, v122
	v_lshl_add_u64 v[90:91], v[122:123], 1, v[90:91]
	v_add_co_u32_e32 v90, vcc, 0x2000, v90
	v_lshl_add_u64 v[94:95], s[90:91], 0, v[100:101]
	s_nop 0
	v_addc_co_u32_e32 v91, vcc, 0, v91, vcc
	global_load_dwordx4 v[90:93], v[90:91], off
	v_lshl_add_u64 v[94:95], v[130:131], 1, v[94:95]
	s_mov_b64 s[8:9], 0
	s_waitcnt vmcnt(0) lgkmcnt(0)
	v_lshlrev_b32_e32 v96, 16, v90
	v_and_b32_e32 v97, 0xffff0000, v90
	v_lshlrev_b32_e32 v90, 16, v91
	v_and_b32_e32 v91, 0xffff0000, v91
	v_lshlrev_b32_e32 v100, 16, v92
	v_and_b32_e32 v101, 0xffff0000, v92
	v_lshlrev_b32_e32 v92, 16, v93
	v_and_b32_e32 v93, 0xffff0000, v93
	v_pk_mul_f32 v[102:103], v[88:89], v[90:91]
	v_pk_mul_f32 v[90:91], v[86:87], v[96:97]
	v_pk_mul_f32 v[96:97], v[84:85], v[92:93]
	v_pk_mul_f32 v[92:93], v[82:83], v[100:101]
	v_cvt_pk_bf16_f32 v90, v90, v91
	v_cvt_pk_bf16_f32 v91, v102, v103
	s_nop 0
	v_cvt_pk_bf16_f32 v92, v92, v93
	v_cvt_pk_bf16_f32 v93, v96, v97
	global_store_dwordx4 v[94:95], v[90:93], off offset:256

; DEVI u32x4 pack8(f32x4 a, f32x4 b) { u32x4 o; o.x = cvt_pk_bf16(a[0], a[1]); o.y = cvt_pk_bf16(a[2], a[3]); o.z = cvt_pk_bf16(b[0], b[1]); o.w = cvt_pk_bf16(b[2], b[3]); return o; }
; DEVI float sigmoidf_(float x) { return 1.f / (1.f + __expf(-x)); }
; DEVI void gemm_epi(const GJob& jb, int row, int col, f32x4 v0, f32x4 v1) {
;     ...
;   else if (mode == 2) { f32x4 s0, s1; for (int i = 0; i < 4; ++i) { s0[i] = sigmoidf_(v0[i]); s1[i] = sigmoidf_(v1[i]); } *(u32x4*)((bf16_t*)jb.out + (size_t)row * jb.ldo + col) = pack8(s0, s1); }
.LBB0_519:
	s_and_b64 vcc, exec, s[12:13]
	s_cbranch_vccz .LBB0_522
	s_cmp_eq_u32 s71, 2
	s_mov_b64 s[8:9], -1
	s_cbranch_scc0 .LBB0_522
	v_mul_f32_e32 v0, 0xbfb8aa3b, v86
	v_exp_f32_e32 v0, v0
	s_mov_b64 s[8:9], 0
	v_add_f32_e32 v0, 1.0, v0
	v_div_scale_f32 v90, s[0:1], v0, v0, 1.0
	v_rcp_f32_e32 v91, v90
	s_nop 0
	v_fma_f32 v92, -v90, v91, 1.0
	v_fmac_f32_e32 v91, v92, v91
	v_div_scale_f32 v92, vcc, 1.0, v0, 1.0
	v_mul_f32_e32 v93, v92, v91
	v_fma_f32 v94, -v90, v93, v92
	v_fmac_f32_e32 v93, v94, v91
	v_fma_f32 v90, -v90, v93, v92
	v_div_fmas_f32 v90, v90, v91, v93
	v_div_fixup_f32 v0, v90, v0, 1.0
	v_mul_f32_e32 v90, 0xbfb8aa3b, v82
	v_exp_f32_e32 v90, v90
	s_nop 0
	v_add_f32_e32 v90, 1.0, v90
	v_div_scale_f32 v91, s[0:1], v90, v90, 1.0
	v_rcp_f32_e32 v92, v91
	s_nop 0
	v_fma_f32 v93, -v91, v92, 1.0
	v_fmac_f32_e32 v92, v93, v92
	v_div_scale_f32 v93, vcc, 1.0, v90, 1.0
	v_mul_f32_e32 v94, v93, v92
	v_fma_f32 v95, -v91, v94, v93
	v_fmac_f32_e32 v94, v95, v92
	v_fma_f32 v91, -v91, v94, v93
	v_div_fmas_f32 v91, v91, v92, v94
	v_div_fixup_f32 v92, v91, v90, 1.0
	v_mul_f32_e32 v90, 0xbfb8aa3b, v87
	v_exp_f32_e32 v90, v90
	s_nop 0
	v_add_f32_e32 v90, 1.0, v90
	v_div_scale_f32 v91, s[0:1], v90, v90, 1.0
	v_rcp_f32_e32 v93, v91
	s_nop 0
	v_fma_f32 v94, -v91, v93, 1.0
	v_fmac_f32_e32 v93, v94, v93
	v_div_scale_f32 v94, vcc, 1.0, v90, 1.0
	v_mul_f32_e32 v95, v94, v93
	v_fma_f32 v96, -v91, v95, v94
	v_fmac_f32_e32 v95, v96, v93
	v_fma_f32 v91, -v91, v95, v94
	v_div_fmas_f32 v91, v91, v93, v95
	v_div_fixup_f32 v90, v91, v90, 1.0
	v_mul_f32_e32 v91, 0xbfb8aa3b, v83
	v_exp_f32_e32 v91, v91
	v_cvt_pk_bf16_f32 v90, v0, v90
	s_nop 0
	v_add_f32_e32 v91, 1.0, v91
	v_div_scale_f32 v93, s[0:1], v91, v91, 1.0
	v_rcp_f32_e32 v94, v93
	s_nop 0
	v_fma_f32 v95, -v93, v94, 1.0
	v_fmac_f32_e32 v94, v95, v94
	v_div_scale_f32 v95, vcc, 1.0, v91, 1.0
	v_mul_f32_e32 v96, v95, v94
	v_fma_f32 v97, -v93, v96, v95
	v_fmac_f32_e32 v96, v97, v94
	v_fma_f32 v93, -v93, v96, v95
	v_div_fmas_f32 v93, v93, v94, v96
	v_div_fixup_f32 v93, v93, v91, 1.0
	v_mul_f32_e32 v91, 0xbfb8aa3b, v88
	v_exp_f32_e32 v91, v91
	v_cvt_pk_bf16_f32 v92, v92, v93
	s_nop 0
	v_add_f32_e32 v91, 1.0, v91
	v_div_scale_f32 v94, s[0:1], v91, v91, 1.0
	v_rcp_f32_e32 v95, v94
	s_nop 0
	v_fma_f32 v96, -v94, v95, 1.0
	v_fmac_f32_e32 v95, v96, v95
	v_div_scale_f32 v96, vcc, 1.0, v91, 1.0
	v_mul_f32_e32 v97, v96, v95
	v_fma_f32 v99, -v94, v97, v96
	v_fmac_f32_e32 v97, v99, v95
	v_fma_f32 v94, -v94, v97, v96
	v_div_fmas_f32 v94, v94, v95, v97
	v_div_fixup_f32 v91, v94, v91, 1.0
	v_mul_f32_e32 v94, 0xbfb8aa3b, v84
	v_exp_f32_e32 v94, v94
	s_nop 0
	v_add_f32_e32 v94, 1.0, v94
	v_div_scale_f32 v95, s[0:1], v94, v94, 1.0
	v_rcp_f32_e32 v96, v95
	s_nop 0
	v_fma_f32 v97, -v95, v96, 1.0
	v_fmac_f32_e32 v96, v97, v96
	v_div_scale_f32 v97, vcc, 1.0, v94, 1.0
	v_mul_f32_e32 v99, v97, v96
	v_fma_f32 v100, -v95, v99, v97
	v_fmac_f32_e32 v99, v100, v96
	v_fma_f32 v95, -v95, v99, v97
	v_div_fmas_f32 v95, v95, v96, v99
	v_div_fixup_f32 v94, v95, v94, 1.0
	v_mul_f32_e32 v95, 0xbfb8aa3b, v89
	v_exp_f32_e32 v95, v95
	s_nop 0
	v_add_f32_e32 v95, 1.0, v95
	v_div_scale_f32 v96, s[0:1], v95, v95, 1.0
	v_rcp_f32_e32 v97, v96
	s_nop 0
	v_fma_f32 v99, -v96, v97, 1.0
	v_fmac_f32_e32 v97, v99, v97
	v_div_scale_f32 v99, vcc, 1.0, v95, 1.0
	v_mul_f32_e32 v100, v99, v97
	v_fma_f32 v101, -v96, v100, v99
	v_fmac_f32_e32 v100, v101, v97
	v_fma_f32 v96, -v96, v100, v99
	v_div_fmas_f32 v96, v96, v97, v100
	v_div_fixup_f32 v95, v96, v95, 1.0
	v_mul_f32_e32 v96, 0xbfb8aa3b, v85
	v_exp_f32_e32 v96, v96
	v_cvt_pk_bf16_f32 v91, v91, v95
	s_nop 0
	v_add_f32_e32 v96, 1.0, v96
	v_div_scale_f32 v97, s[0:1], v96, v96, 1.0
	v_rcp_f32_e32 v99, v97
	s_nop 0
	v_fma_f32 v100, -v97, v99, 1.0
	v_fmac_f32_e32 v99, v100, v99
	v_div_scale_f32 v100, vcc, 1.0, v96, 1.0
	v_mul_f32_e32 v101, v100, v99
	v_fma_f32 v102, -v97, v101, v100
	v_fmac_f32_e32 v101, v102, v99
	v_fma_f32 v97, -v97, v101, v100
	v_div_fmas_f32 v97, v97, v99, v101
	v_div_fixup_f32 v96, v97, v96, 1.0
	v_cvt_pk_bf16_f32 v93, v94, v96
	v_mad_i64_i32 v[94:95], s[0:1], v98, s29, 0
	v_lshl_add_u64 v[94:95], v[94:95], 1, s[90:91]
	v_lshl_add_u64 v[94:95], v[130:131], 1, v[94:95]
	global_store_dwordx4 v[94:95], v[90:93], off offset:256

; DEVI void gemm_epi(const GJob& jb, int row, int col, f32x4 v0, f32x4 v1) {
;     ...
;   else if (mode == 1) { float* p = (float*)jb.out + (size_t)row * jb.ldo + col; *(f32x4*)p = v0; *(f32x4*)(p + 4) = v1; }
.LBB0_523:
	s_and_b64 vcc, exec, s[12:13]
	s_cbranch_vccz .LBB0_528
	s_cmp_gt_i32 s71, 0
	s_mov_b64 s[10:11], -1
	s_cbranch_scc0 .LBB0_526
	v_mad_i64_i32 v[90:91], s[0:1], v98, s29, 0
	v_lshl_add_u64 v[90:91], v[90:91], 2, s[90:91]
	v_lshl_add_u64 v[90:91], v[130:131], 2, v[90:91]
	global_store_dwordx4 v[90:91], v[86:89], off offset:512
	global_store_dwordx4 v[90:91], v[82:85], off offset:528
	s_mov_b64 s[10:11], 0

; DEVI float bf_lo(unsigned u) { return __uint_as_float(u << 16); }
; DEVI float bf_hi(unsigned u) { return __uint_as_float(u & 0xffff0000u); }
; DEVI float sigmoidf_(float x) { return 1.f / (1.f + __expf(-x)); }
; DEVI u32x4 pack8(f32x4 a, f32x4 b) { u32x4 o; o.x = cvt_pk_bf16(a[0], a[1]); o.y = cvt_pk_bf16(a[2], a[3]); o.z = cvt_pk_bf16(b[0], b[1]); o.w = cvt_pk_bf16(b[2], b[3]); return o; }
; DEVI void gemm_epi(const GJob& jb, int row, int col, f32x4 v0, f32x4 v1) {
;     ...
;   if (mode == 0) { *(u32x4*)((bf16_t*)jb.out + (size_t)row * jb.ldo + col) = pack8(v0, v1); }
;   else if (mode == 1) { float* p = (float*)jb.out + (size_t)row * jb.ldo + col; *(f32x4*)p = v0; *(f32x4*)(p + 4) = v1; }
;   else if (mode == 2) { f32x4 s0, s1; for (int i = 0; i < 4; ++i) { s0[i] = sigmoidf_(v0[i]); s1[i] = sigmoidf_(v1[i]); } *(u32x4*)((bf16_t*)jb.out + (size_t)row * jb.ldo + col) = pack8(s0, s1); }
;   else if (mode == 7) {
;     const u32x4 g = *(const u32x4*)((const bf16_t*)jb.aux + (size_t)row * NGATE + 2 * 2048 + col);
;     const f32x4 g0 = {bf_lo(g.x), bf_hi(g.x), bf_lo(g.y), bf_hi(g.y)}, g1 = {bf_lo(g.z), bf_hi(g.z), bf_lo(g.w), bf_hi(g.w)};
;     *(u32x4*)((bf16_t*)jb.out + (size_t)row * 2048 + col) = pack8(g0 * v0, g1 * v1);
;   } else {
;     const float* xp = (const float*)jb.aux + (size_t)row * jb.ldo + col; const float* gp = (const float*)jb.aux2 + col;
;     float* op = (float*)jb.out + (size_t)row * jb.ldo + col;
;     const f32x4 x0 = *(const f32x4*)xp, x1 = *(const f32x4*)(xp + 4), t0 = *(const f32x4*)gp, t1 = *(const f32x4*)(gp + 4);
;     *(f32x4*)op = x0 + t0 * v0; *(f32x4*)(op + 4) = x1 + t1 * v1;
.LBB0_528:
	s_and_b64 vcc, exec, s[8:9]
	s_cbranch_vccz .LBB0_530
	v_mad_i64_i32 v[90:91], s[0:1], v98, s29, 0
	v_lshlrev_b64 v[90:91], 2, v[90:91]
	v_lshl_add_u64 v[92:93], s[94:95], 0, v[90:91]
	v_lshlrev_b64 v[94:95], 2, v[130:131]
	v_lshl_add_u64 v[96:97], v[92:93], 0, v[94:95]
	v_lshl_add_u64 v[104:105], s[88:89], 0, v[94:95]
	v_lshl_add_u64 v[90:91], s[90:91], 0, v[90:91]
	v_lshl_add_u64 v[108:109], v[90:91], 0, v[94:95]
	global_load_dwordx4 v[90:93], v[96:97], off offset:512
	s_nop 0
	global_load_dwordx4 v[94:97], v[96:97], off offset:528
	s_nop 0
	global_load_dwordx4 v[100:103], v[104:105], off offset:512
	s_nop 0
	global_load_dwordx4 v[104:107], v[104:105], off offset:528
	s_mov_b64 s[10:11], 0
	s_waitcnt vmcnt(0) lgkmcnt(0)
	v_pk_fma_f32 v[92:93], v[88:89], v[102:103], v[92:93]
	v_pk_fma_f32 v[90:91], v[86:87], v[100:101], v[90:91]
	global_store_dwordx4 v[108:109], v[90:93], off offset:512
	s_nop 1
	v_pk_fma_f32 v[92:93], v[84:85], v[106:107], v[96:97]
	v_pk_fma_f32 v[90:91], v[82:83], v[104:105], v[94:95]
	global_store_dwordx4 v[108:109], v[90:93], off offset:528
.LBB0_530:
	s_andn2_b64 vcc, exec, s[10:11]
	s_cbranch_vccnz .LBB0_532
	v_cvt_pk_bf16_f32 v86, v86, v87
	v_cvt_pk_bf16_f32 v87, v88, v89
	v_cvt_pk_bf16_f32 v88, v82, v83
	v_mad_i64_i32 v[82:83], s[0:1], v98, s29, 0
	v_lshl_add_u64 v[82:83], v[82:83], 1, s[90:91]
	v_lshl_add_u64 v[82:83], v[130:131], 1, v[82:83]
	v_cvt_pk_bf16_f32 v89, v84, v85
	global_store_dwordx4 v[82:83], v[86:89], off offset:256
.LBB0_532:
	v_or_b32_e32 v82, 48, v132
	v_ashrrev_i32_e32 v83, 31, v82
	v_mad_i64_i32 v[86:87], s[0:1], v82, s33, 0
	v_lshlrev_b64 v[84:85], 12, v[82:83]
	s_mov_b64 s[12:13], -1
	s_mov_b64 s[10:11], 0
	s_cmp_lt_i32 s71, 2
	s_mov_b64 s[8:9], 0
	s_cbranch_scc1 .LBB0_541
	s_cmp_gt_i32 s71, 6
	s_cbranch_scc0 .LBB0_537
	s_cmp_eq_u32 s71, 7
	s_mov_b64 s[8:9], -1
	s_cbranch_scc0 .LBB0_536
	v_lshl_add_u64 v[88:89], s[94:95], 0, v[86:87]
	v_lshlrev_b64 v[92:93], 1, v[130:131]
	v_lshl_add_u64 v[88:89], v[88:89], 0, v[92:93]
	v_add_co_u32_e32 v88, vcc, 0x2000, v88
	v_lshl_add_u64 v[94:95], s[90:91], 0, v[84:85]
	s_nop 0
	v_addc_co_u32_e32 v89, vcc, 0, v89, vcc
	global_load_dwordx4 v[88:91], v[88:89], off
	v_lshl_add_u64 v[92:93], v[94:95], 0, v[92:93]
	s_mov_b64 s[8:9], 0
	s_waitcnt vmcnt(0) lgkmcnt(0)
	v_lshlrev_b32_e32 v94, 16, v88
	v_and_b32_e32 v95, 0xffff0000, v88
	v_lshlrev_b32_e32 v88, 16, v89
	v_and_b32_e32 v89, 0xffff0000, v89
	v_lshlrev_b32_e32 v96, 16, v90
	v_and_b32_e32 v97, 0xffff0000, v90
	v_lshlrev_b32_e32 v90, 16, v91
	v_and_b32_e32 v91, 0xffff0000, v91
	v_pk_mul_f32 v[98:99], v[80:81], v[88:89]
	v_pk_mul_f32 v[88:89], v[78:79], v[94:95]
	v_pk_mul_f32 v[94:95], v[76:77], v[90:91]
	v_pk_mul_f32 v[90:91], v[74:75], v[96:97]
	v_cvt_pk_bf16_f32 v88, v88, v89
	v_cvt_pk_bf16_f32 v89, v98, v99
	s_nop 0
	v_cvt_pk_bf16_f32 v90, v90, v91
	v_cvt_pk_bf16_f32 v91, v94, v95
	global_store_dwordx4 v[92:93], v[88:91], off

; DEVI u32x4 pack8(f32x4 a, f32x4 b) { u32x4 o; o.x = cvt_pk_bf16(a[0], a[1]); o.y = cvt_pk_bf16(a[2], a[3]); o.z = cvt_pk_bf16(b[0], b[1]); o.w = cvt_pk_bf16(b[2], b[3]); return o; }
; DEVI float sigmoidf_(float x) { return 1.f / (1.f + __expf(-x)); }
; DEVI void gemm_epi(const GJob& jb, int row, int col, f32x4 v0, f32x4 v1) {
;     ...
;   else if (mode == 2) { f32x4 s0, s1; for (int i = 0; i < 4; ++i) { s0[i] = sigmoidf_(v0[i]); s1[i] = sigmoidf_(v1[i]); } *(u32x4*)((bf16_t*)jb.out + (size_t)row * jb.ldo + col) = pack8(s0, s1); }
.LBB0_537:
	s_and_b64 vcc, exec, s[12:13]
	s_cbranch_vccz .LBB0_540
	s_cmp_eq_u32 s71, 2
	s_mov_b64 s[8:9], -1
	s_cbranch_scc0 .LBB0_540
	v_mul_f32_e32 v0, 0xbfb8aa3b, v78
	v_exp_f32_e32 v0, v0
	s_mov_b64 s[8:9], 0
	v_add_f32_e32 v0, 1.0, v0
	v_div_scale_f32 v83, s[0:1], v0, v0, 1.0
	v_rcp_f32_e32 v88, v83
	s_nop 0
	v_fma_f32 v89, -v83, v88, 1.0
	v_fmac_f32_e32 v88, v89, v88
	v_div_scale_f32 v89, vcc, 1.0, v0, 1.0
	v_mul_f32_e32 v90, v89, v88
	v_fma_f32 v91, -v83, v90, v89
	v_fmac_f32_e32 v90, v91, v88
	v_fma_f32 v83, -v83, v90, v89
	v_div_fmas_f32 v83, v83, v88, v90
	v_div_fixup_f32 v0, v83, v0, 1.0
	v_mul_f32_e32 v83, 0xbfb8aa3b, v74
	v_exp_f32_e32 v83, v83
	s_nop 0
	v_add_f32_e32 v83, 1.0, v83
	v_div_scale_f32 v88, s[0:1], v83, v83, 1.0
	v_rcp_f32_e32 v89, v88
	s_nop 0
	v_fma_f32 v90, -v88, v89, 1.0
	v_fmac_f32_e32 v89, v90, v89
	v_div_scale_f32 v90, vcc, 1.0, v83, 1.0
	v_mul_f32_e32 v91, v90, v89
	v_fma_f32 v92, -v88, v91, v90
	v_fmac_f32_e32 v91, v92, v89
	v_fma_f32 v88, -v88, v91, v90
	v_div_fmas_f32 v88, v88, v89, v91
	v_div_fixup_f32 v83, v88, v83, 1.0
	v_mul_f32_e32 v88, 0xbfb8aa3b, v79
	v_exp_f32_e32 v88, v88
	s_nop 0
	v_add_f32_e32 v88, 1.0, v88
	v_div_scale_f32 v89, s[0:1], v88, v88, 1.0
	v_rcp_f32_e32 v90, v89
	s_nop 0
	v_fma_f32 v91, -v89, v90, 1.0
	v_fmac_f32_e32 v90, v91, v90
	v_div_scale_f32 v91, vcc, 1.0, v88, 1.0
	v_mul_f32_e32 v92, v91, v90
	v_fma_f32 v93, -v89, v92, v91
	v_fmac_f32_e32 v92, v93, v90
	v_fma_f32 v89, -v89, v92, v91
	v_div_fmas_f32 v89, v89, v90, v92
	v_div_fixup_f32 v88, v89, v88, 1.0
	v_mul_f32_e32 v89, 0xbfb8aa3b, v75
	v_exp_f32_e32 v89, v89
	v_cvt_pk_bf16_f32 v88, v0, v88
	s_nop 0
	v_add_f32_e32 v89, 1.0, v89
	v_div_scale_f32 v90, s[0:1], v89, v89, 1.0
	v_rcp_f32_e32 v91, v90
	s_nop 0
	v_fma_f32 v92, -v90, v91, 1.0
	v_fmac_f32_e32 v91, v92, v91
	v_div_scale_f32 v92, vcc, 1.0, v89, 1.0
	v_mul_f32_e32 v93, v92, v91
	v_fma_f32 v94, -v90, v93, v92
	v_fmac_f32_e32 v93, v94, v91
	v_fma_f32 v90, -v90, v93, v92
	v_div_fmas_f32 v90, v90, v91, v93
	v_div_fixup_f32 v90, v90, v89, 1.0
	v_mul_f32_e32 v89, 0xbfb8aa3b, v80
	v_exp_f32_e32 v89, v89
	v_cvt_pk_bf16_f32 v90, v83, v90
	s_nop 0
	v_add_f32_e32 v89, 1.0, v89
	v_div_scale_f32 v91, s[0:1], v89, v89, 1.0
	v_rcp_f32_e32 v92, v91
	s_nop 0
	v_fma_f32 v93, -v91, v92, 1.0
	v_fmac_f32_e32 v92, v93, v92
	v_div_scale_f32 v93, vcc, 1.0, v89, 1.0
	v_mul_f32_e32 v94, v93, v92
	v_fma_f32 v95, -v91, v94, v93
	v_fmac_f32_e32 v94, v95, v92
	v_fma_f32 v91, -v91, v94, v93
	v_div_fmas_f32 v91, v91, v92, v94
	v_div_fixup_f32 v89, v91, v89, 1.0
	v_mul_f32_e32 v91, 0xbfb8aa3b, v76
	v_exp_f32_e32 v91, v91
	s_nop 0
	v_add_f32_e32 v91, 1.0, v91
	v_div_scale_f32 v92, s[0:1], v91, v91, 1.0
	v_rcp_f32_e32 v93, v92
	s_nop 0
	v_fma_f32 v94, -v92, v93, 1.0
	v_fmac_f32_e32 v93, v94, v93
	v_div_scale_f32 v94, vcc, 1.0, v91, 1.0
	v_mul_f32_e32 v95, v94, v93
	v_fma_f32 v96, -v92, v95, v94
	v_fmac_f32_e32 v95, v96, v93
	v_fma_f32 v92, -v92, v95, v94
	v_div_fmas_f32 v92, v92, v93, v95
	v_div_fixup_f32 v91, v92, v91, 1.0
	v_mul_f32_e32 v92, 0xbfb8aa3b, v81
	v_exp_f32_e32 v92, v92
	s_nop 0
	v_add_f32_e32 v92, 1.0, v92
	v_div_scale_f32 v93, s[0:1], v92, v92, 1.0
	v_rcp_f32_e32 v94, v93
	s_nop 0
	v_fma_f32 v95, -v93, v94, 1.0
	v_fmac_f32_e32 v94, v95, v94
	v_div_scale_f32 v95, vcc, 1.0, v92, 1.0
	v_mul_f32_e32 v96, v95, v94
	v_fma_f32 v97, -v93, v96, v95
	v_fmac_f32_e32 v96, v97, v94
	v_fma_f32 v93, -v93, v96, v95
	v_div_fmas_f32 v93, v93, v94, v96
	v_div_fixup_f32 v92, v93, v92, 1.0
	v_mul_f32_e32 v93, 0xbfb8aa3b, v77
	v_exp_f32_e32 v93, v93
	v_cvt_pk_bf16_f32 v89, v89, v92
	s_nop 0
	v_add_f32_e32 v93, 1.0, v93
	v_div_scale_f32 v94, s[0:1], v93, v93, 1.0
	v_rcp_f32_e32 v95, v94
	s_nop 0
	v_fma_f32 v96, -v94, v95, 1.0
	v_fmac_f32_e32 v95, v96, v95
	v_div_scale_f32 v96, vcc, 1.0, v93, 1.0
	v_mul_f32_e32 v97, v96, v95
	v_fma_f32 v98, -v94, v97, v96
	v_fmac_f32_e32 v97, v98, v95
	v_fma_f32 v94, -v94, v97, v96
	v_div_fmas_f32 v94, v94, v95, v97
	v_div_fixup_f32 v93, v94, v93, 1.0
	v_cvt_pk_bf16_f32 v91, v91, v93
	v_mad_i64_i32 v[92:93], s[0:1], v82, s29, 0
	v_lshl_add_u64 v[92:93], v[92:93], 1, s[90:91]
	v_lshl_add_u64 v[92:93], v[130:131], 1, v[92:93]
	global_store_dwordx4 v[92:93], v[88:91], off

; DEVI void gemm_epi(const GJob& jb, int row, int col, f32x4 v0, f32x4 v1) {
;     ...
;   else if (mode == 1) { float* p = (float*)jb.out + (size_t)row * jb.ldo + col; *(f32x4*)p = v0; *(f32x4*)(p + 4) = v1; }
.LBB0_541:
	s_and_b64 vcc, exec, s[12:13]
	s_cbranch_vccz .LBB0_546
	s_cmp_gt_i32 s71, 0
	s_mov_b64 s[10:11], -1
	s_cbranch_scc0 .LBB0_544
	v_mad_i64_i32 v[88:89], s[0:1], v82, s29, 0
	v_lshl_add_u64 v[88:89], v[88:89], 2, s[90:91]
	v_lshl_add_u64 v[88:89], v[130:131], 2, v[88:89]
	global_store_dwordx4 v[88:89], v[78:81], off
	global_store_dwordx4 v[88:89], v[74:77], off offset:16
	s_mov_b64 s[10:11], 0

; DEVI float bf_lo(unsigned u) { return __uint_as_float(u << 16); }
; DEVI float bf_hi(unsigned u) { return __uint_as_float(u & 0xffff0000u); }
; DEVI float sigmoidf_(float x) { return 1.f / (1.f + __expf(-x)); }
; DEVI u32x4 pack8(f32x4 a, f32x4 b) { u32x4 o; o.x = cvt_pk_bf16(a[0], a[1]); o.y = cvt_pk_bf16(a[2], a[3]); o.z = cvt_pk_bf16(b[0], b[1]); o.w = cvt_pk_bf16(b[2], b[3]); return o; }
; DEVI void gemm_epi(const GJob& jb, int row, int col, f32x4 v0, f32x4 v1) {
;     ...
;   if (mode == 0) { *(u32x4*)((bf16_t*)jb.out + (size_t)row * jb.ldo + col) = pack8(v0, v1); }
;   else if (mode == 1) { float* p = (float*)jb.out + (size_t)row * jb.ldo + col; *(f32x4*)p = v0; *(f32x4*)(p + 4) = v1; }
;   else if (mode == 2) { f32x4 s0, s1; for (int i = 0; i < 4; ++i) { s0[i] = sigmoidf_(v0[i]); s1[i] = sigmoidf_(v1[i]); } *(u32x4*)((bf16_t*)jb.out + (size_t)row * jb.ldo + col) = pack8(s0, s1); }
;   else if (mode == 7) {
;     const u32x4 g = *(const u32x4*)((const bf16_t*)jb.aux + (size_t)row * NGATE + 2 * 2048 + col);
;     const f32x4 g0 = {bf_lo(g.x), bf_hi(g.x), bf_lo(g.y), bf_hi(g.y)}, g1 = {bf_lo(g.z), bf_hi(g.z), bf_lo(g.w), bf_hi(g.w)};
;     *(u32x4*)((bf16_t*)jb.out + (size_t)row * 2048 + col) = pack8(g0 * v0, g1 * v1);
;   } else {
;     const float* xp = (const float*)jb.aux + (size_t)row * jb.ldo + col; const float* gp = (const float*)jb.aux2 + col;
;     float* op = (float*)jb.out + (size_t)row * jb.ldo + col;
;     const f32x4 x0 = *(const f32x4*)xp, x1 = *(const f32x4*)(xp + 4), t0 = *(const f32x4*)gp, t1 = *(const f32x4*)(gp + 4);
;     *(f32x4*)op = x0 + t0 * v0; *(f32x4*)(op + 4) = x1 + t1 * v1;
.LBB0_546:
	s_and_b64 vcc, exec, s[8:9]
	s_cbranch_vccz .LBB0_548
	v_mad_i64_i32 v[88:89], s[0:1], v82, s29, 0
	v_lshlrev_b64 v[88:89], 2, v[88:89]
	v_lshl_add_u64 v[90:91], s[94:95], 0, v[88:89]
	v_lshlrev_b64 v[92:93], 2, v[130:131]
	v_lshl_add_u64 v[94:95], v[90:91], 0, v[92:93]
	v_lshl_add_u64 v[100:101], s[88:89], 0, v[92:93]
	v_lshl_add_u64 v[88:89], s[90:91], 0, v[88:89]
	v_lshl_add_u64 v[104:105], v[88:89], 0, v[92:93]
	global_load_dwordx4 v[88:91], v[94:95], off
	s_nop 0
	global_load_dwordx4 v[92:95], v[94:95], off offset:16
	s_nop 0
	global_load_dwordx4 v[96:99], v[100:101], off
	s_nop 0
	global_load_dwordx4 v[100:103], v[100:101], off offset:16
	s_mov_b64 s[10:11], 0
	s_waitcnt vmcnt(0) lgkmcnt(0)
	v_pk_fma_f32 v[90:91], v[80:81], v[98:99], v[90:91]
	v_pk_fma_f32 v[88:89], v[78:79], v[96:97], v[88:89]
	global_store_dwordx4 v[104:105], v[88:91], off
	s_nop 1
	v_pk_fma_f32 v[90:91], v[76:77], v[102:103], v[94:95]
	v_pk_fma_f32 v[88:89], v[74:75], v[100:101], v[92:93]
	global_store_dwordx4 v[104:105], v[88:91], off offset:16
.LBB0_548:
	s_andn2_b64 vcc, exec, s[10:11]
	s_cbranch_vccnz .LBB0_550
	v_cvt_pk_bf16_f32 v78, v78, v79
	v_cvt_pk_bf16_f32 v79, v80, v81
	v_cvt_pk_bf16_f32 v80, v74, v75
	v_mad_i64_i32 v[74:75], s[0:1], v82, s29, 0
	v_lshl_add_u64 v[74:75], v[74:75], 1, s[90:91]
	v_lshl_add_u64 v[74:75], v[130:131], 1, v[74:75]
	v_cvt_pk_bf16_f32 v81, v76, v77
	global_store_dwordx4 v[74:75], v[78:81], off
.LBB0_550:
	s_mov_b64 s[12:13], -1
	s_mov_b64 s[10:11], 0
	s_cmp_lt_i32 s71, 2
	s_mov_b64 s[8:9], 0
	s_cbranch_scc1 .LBB0_559
	s_cmp_gt_i32 s71, 6
	s_cbranch_scc0 .LBB0_555
	s_cmp_eq_u32 s71, 7
	s_mov_b64 s[8:9], -1
	s_cbranch_scc0 .LBB0_554
	v_lshl_add_u64 v[74:75], s[94:95], 0, v[86:87]
	v_ashrrev_i32_e32 v123, 31, v122
	v_lshl_add_u64 v[74:75], v[122:123], 1, v[74:75]
	v_add_co_u32_e32 v74, vcc, 0x2000, v74
	v_lshl_add_u64 v[78:79], s[90:91], 0, v[84:85]
	s_nop 0
	v_addc_co_u32_e32 v75, vcc, 0, v75, vcc
	global_load_dwordx4 v[74:77], v[74:75], off
	v_lshl_add_u64 v[78:79], v[130:131], 1, v[78:79]
	s_mov_b64 s[8:9], 0
	s_waitcnt vmcnt(0) lgkmcnt(0)
	v_lshlrev_b32_e32 v80, 16, v74
	v_and_b32_e32 v81, 0xffff0000, v74
	v_lshlrev_b32_e32 v74, 16, v75
	v_and_b32_e32 v75, 0xffff0000, v75
	v_lshlrev_b32_e32 v84, 16, v76
	v_and_b32_e32 v85, 0xffff0000, v76
	v_lshlrev_b32_e32 v76, 16, v77
	v_and_b32_e32 v77, 0xffff0000, v77
	v_pk_mul_f32 v[86:87], v[72:73], v[74:75]
	v_pk_mul_f32 v[74:75], v[70:71], v[80:81]
	v_pk_mul_f32 v[80:81], v[68:69], v[76:77]
	v_pk_mul_f32 v[76:77], v[66:67], v[84:85]
	v_cvt_pk_bf16_f32 v74, v74, v75
	v_cvt_pk_bf16_f32 v75, v86, v87
	s_nop 0
	v_cvt_pk_bf16_f32 v76, v76, v77
	v_cvt_pk_bf16_f32 v77, v80, v81
	global_store_dwordx4 v[78:79], v[74:77], off offset:256

; DEVI u32x4 pack8(f32x4 a, f32x4 b) { u32x4 o; o.x = cvt_pk_bf16(a[0], a[1]); o.y = cvt_pk_bf16(a[2], a[3]); o.z = cvt_pk_bf16(b[0], b[1]); o.w = cvt_pk_bf16(b[2], b[3]); return o; }
; DEVI float sigmoidf_(float x) { return 1.f / (1.f + __expf(-x)); }
; DEVI void gemm_epi(const GJob& jb, int row, int col, f32x4 v0, f32x4 v1) {
;     ...
;   else if (mode == 2) { f32x4 s0, s1; for (int i = 0; i < 4; ++i) { s0[i] = sigmoidf_(v0[i]); s1[i] = sigmoidf_(v1[i]); } *(u32x4*)((bf16_t*)jb.out + (size_t)row * jb.ldo + col) = pack8(s0, s1); }
.LBB0_555:
	s_and_b64 vcc, exec, s[12:13]
	s_cbranch_vccz .LBB0_558
	s_cmp_eq_u32 s71, 2
	s_mov_b64 s[8:9], -1
	s_cbranch_scc0 .LBB0_558
	v_mul_f32_e32 v0, 0xbfb8aa3b, v70
	v_exp_f32_e32 v0, v0
	s_mov_b64 s[8:9], 0
	v_add_f32_e32 v0, 1.0, v0
	v_div_scale_f32 v74, s[0:1], v0, v0, 1.0
	v_rcp_f32_e32 v75, v74
	s_nop 0
	v_fma_f32 v76, -v74, v75, 1.0
	v_fmac_f32_e32 v75, v76, v75
	v_div_scale_f32 v76, vcc, 1.0, v0, 1.0
	v_mul_f32_e32 v77, v76, v75
	v_fma_f32 v78, -v74, v77, v76
	v_fmac_f32_e32 v77, v78, v75
	v_fma_f32 v74, -v74, v77, v76
	v_div_fmas_f32 v74, v74, v75, v77
	v_div_fixup_f32 v0, v74, v0, 1.0
	v_mul_f32_e32 v74, 0xbfb8aa3b, v66
	v_exp_f32_e32 v74, v74
	s_nop 0
	v_add_f32_e32 v74, 1.0, v74
	v_div_scale_f32 v75, s[0:1], v74, v74, 1.0
	v_rcp_f32_e32 v76, v75
	s_nop 0
	v_fma_f32 v77, -v75, v76, 1.0
	v_fmac_f32_e32 v76, v77, v76
	v_div_scale_f32 v77, vcc, 1.0, v74, 1.0
	v_mul_f32_e32 v78, v77, v76
	v_fma_f32 v79, -v75, v78, v77
	v_fmac_f32_e32 v78, v79, v76
	v_fma_f32 v75, -v75, v78, v77
	v_div_fmas_f32 v75, v75, v76, v78
	v_div_fixup_f32 v76, v75, v74, 1.0
	v_mul_f32_e32 v74, 0xbfb8aa3b, v71
	v_exp_f32_e32 v74, v74
	s_nop 0
	v_add_f32_e32 v74, 1.0, v74
	v_div_scale_f32 v75, s[0:1], v74, v74, 1.0
	v_rcp_f32_e32 v77, v75
	s_nop 0
	v_fma_f32 v78, -v75, v77, 1.0
	v_fmac_f32_e32 v77, v78, v77
	v_div_scale_f32 v78, vcc, 1.0, v74, 1.0
	v_mul_f32_e32 v79, v78, v77
	v_fma_f32 v80, -v75, v79, v78
	v_fmac_f32_e32 v79, v80, v77
	v_fma_f32 v75, -v75, v79, v78
	v_div_fmas_f32 v75, v75, v77, v79
	v_div_fixup_f32 v74, v75, v74, 1.0
	v_mul_f32_e32 v75, 0xbfb8aa3b, v67
	v_exp_f32_e32 v75, v75
	v_cvt_pk_bf16_f32 v74, v0, v74
	s_nop 0
	v_add_f32_e32 v75, 1.0, v75
	v_div_scale_f32 v77, s[0:1], v75, v75, 1.0
	v_rcp_f32_e32 v78, v77
	s_nop 0
	v_fma_f32 v79, -v77, v78, 1.0
	v_fmac_f32_e32 v78, v79, v78
	v_div_scale_f32 v79, vcc, 1.0, v75, 1.0
	v_mul_f32_e32 v80, v79, v78
	v_fma_f32 v81, -v77, v80, v79
	v_fmac_f32_e32 v80, v81, v78
	v_fma_f32 v77, -v77, v80, v79
	v_div_fmas_f32 v77, v77, v78, v80
	v_div_fixup_f32 v77, v77, v75, 1.0
	v_mul_f32_e32 v75, 0xbfb8aa3b, v72
	v_exp_f32_e32 v75, v75
	v_cvt_pk_bf16_f32 v76, v76, v77
	s_nop 0
	v_add_f32_e32 v75, 1.0, v75
	v_div_scale_f32 v78, s[0:1], v75, v75, 1.0
	v_rcp_f32_e32 v79, v78
	s_nop 0
	v_fma_f32 v80, -v78, v79, 1.0
	v_fmac_f32_e32 v79, v80, v79
	v_div_scale_f32 v80, vcc, 1.0, v75, 1.0
	v_mul_f32_e32 v81, v80, v79
	v_fma_f32 v83, -v78, v81, v80
	v_fmac_f32_e32 v81, v83, v79
	v_fma_f32 v78, -v78, v81, v80
	v_div_fmas_f32 v78, v78, v79, v81
	v_div_fixup_f32 v75, v78, v75, 1.0
	v_mul_f32_e32 v78, 0xbfb8aa3b, v68
	v_exp_f32_e32 v78, v78
	s_nop 0
	v_add_f32_e32 v78, 1.0, v78
	v_div_scale_f32 v79, s[0:1], v78, v78, 1.0
	v_rcp_f32_e32 v80, v79
	s_nop 0
	v_fma_f32 v81, -v79, v80, 1.0
	v_fmac_f32_e32 v80, v81, v80
	v_div_scale_f32 v81, vcc, 1.0, v78, 1.0
	v_mul_f32_e32 v83, v81, v80
	v_fma_f32 v84, -v79, v83, v81
	v_fmac_f32_e32 v83, v84, v80
	v_fma_f32 v79, -v79, v83, v81
	v_div_fmas_f32 v79, v79, v80, v83
	v_div_fixup_f32 v78, v79, v78, 1.0
	v_mul_f32_e32 v79, 0xbfb8aa3b, v73
	v_exp_f32_e32 v79, v79
	s_nop 0
	v_add_f32_e32 v79, 1.0, v79
	v_div_scale_f32 v80, s[0:1], v79, v79, 1.0
	v_rcp_f32_e32 v81, v80
	s_nop 0
	v_fma_f32 v83, -v80, v81, 1.0
	v_fmac_f32_e32 v81, v83, v81
	v_div_scale_f32 v83, vcc, 1.0, v79, 1.0
	v_mul_f32_e32 v84, v83, v81
	v_fma_f32 v85, -v80, v84, v83
	v_fmac_f32_e32 v84, v85, v81
	v_fma_f32 v80, -v80, v84, v83
	v_div_fmas_f32 v80, v80, v81, v84
	v_div_fixup_f32 v79, v80, v79, 1.0
	v_mul_f32_e32 v80, 0xbfb8aa3b, v69
	v_exp_f32_e32 v80, v80
	v_cvt_pk_bf16_f32 v75, v75, v79
	s_nop 0
	v_add_f32_e32 v80, 1.0, v80
	v_div_scale_f32 v81, s[0:1], v80, v80, 1.0
	v_rcp_f32_e32 v83, v81
	s_nop 0
	v_fma_f32 v84, -v81, v83, 1.0
	v_fmac_f32_e32 v83, v84, v83
	v_div_scale_f32 v84, vcc, 1.0, v80, 1.0
	v_mul_f32_e32 v85, v84, v83
	v_fma_f32 v86, -v81, v85, v84
	v_fmac_f32_e32 v85, v86, v83
	v_fma_f32 v81, -v81, v85, v84
	v_div_fmas_f32 v81, v81, v83, v85
	v_div_fixup_f32 v80, v81, v80, 1.0
	v_cvt_pk_bf16_f32 v77, v78, v80
	v_mad_i64_i32 v[78:79], s[0:1], v82, s29, 0
	v_lshl_add_u64 v[78:79], v[78:79], 1, s[90:91]
	v_lshl_add_u64 v[78:79], v[130:131], 1, v[78:79]
	global_store_dwordx4 v[78:79], v[74:77], off offset:256

; DEVI void gemm_epi(const GJob& jb, int row, int col, f32x4 v0, f32x4 v1) {
;     ...
;   else if (mode == 1) { float* p = (float*)jb.out + (size_t)row * jb.ldo + col; *(f32x4*)p = v0; *(f32x4*)(p + 4) = v1; }
.LBB0_559:
	s_and_b64 vcc, exec, s[12:13]
	s_cbranch_vccz .LBB0_564
	s_cmp_gt_i32 s71, 0
	s_mov_b64 s[10:11], -1
	s_cbranch_scc0 .LBB0_562
	v_mad_i64_i32 v[74:75], s[0:1], v82, s29, 0
	v_lshl_add_u64 v[74:75], v[74:75], 2, s[90:91]
	v_lshl_add_u64 v[74:75], v[130:131], 2, v[74:75]
	global_store_dwordx4 v[74:75], v[70:73], off offset:512
	global_store_dwordx4 v[74:75], v[66:69], off offset:528
	s_mov_b64 s[10:11], 0

; DEVI float bf_lo(unsigned u) { return __uint_as_float(u << 16); }
; DEVI float bf_hi(unsigned u) { return __uint_as_float(u & 0xffff0000u); }
; DEVI float sigmoidf_(float x) { return 1.f / (1.f + __expf(-x)); }
; DEVI u32x4 pack8(f32x4 a, f32x4 b) { u32x4 o; o.x = cvt_pk_bf16(a[0], a[1]); o.y = cvt_pk_bf16(a[2], a[3]); o.z = cvt_pk_bf16(b[0], b[1]); o.w = cvt_pk_bf16(b[2], b[3]); return o; }
; DEVI void gemm_epi(const GJob& jb, int row, int col, f32x4 v0, f32x4 v1) {
;     ...
;   if (mode == 0) { *(u32x4*)((bf16_t*)jb.out + (size_t)row * jb.ldo + col) = pack8(v0, v1); }
;   else if (mode == 1) { float* p = (float*)jb.out + (size_t)row * jb.ldo + col; *(f32x4*)p = v0; *(f32x4*)(p + 4) = v1; }
;   else if (mode == 2) { f32x4 s0, s1; for (int i = 0; i < 4; ++i) { s0[i] = sigmoidf_(v0[i]); s1[i] = sigmoidf_(v1[i]); } *(u32x4*)((bf16_t*)jb.out + (size_t)row * jb.ldo + col) = pack8(s0, s1); }
;   else if (mode == 7) {
;     const u32x4 g = *(const u32x4*)((const bf16_t*)jb.aux + (size_t)row * NGATE + 2 * 2048 + col);
;     const f32x4 g0 = {bf_lo(g.x), bf_hi(g.x), bf_lo(g.y), bf_hi(g.y)}, g1 = {bf_lo(g.z), bf_hi(g.z), bf_lo(g.w), bf_hi(g.w)};
;     *(u32x4*)((bf16_t*)jb.out + (size_t)row * 2048 + col) = pack8(g0 * v0, g1 * v1);
;   } else {
;     const float* xp = (const float*)jb.aux + (size_t)row * jb.ldo + col; const float* gp = (const float*)jb.aux2 + col;
;     float* op = (float*)jb.out + (size_t)row * jb.ldo + col;
;     const f32x4 x0 = *(const f32x4*)xp, x1 = *(const f32x4*)(xp + 4), t0 = *(const f32x4*)gp, t1 = *(const f32x4*)(gp + 4);
;     *(f32x4*)op = x0 + t0 * v0; *(f32x4*)(op + 4) = x1 + t1 * v1;
.LBB0_564:
	s_and_b64 vcc, exec, s[8:9]
	s_cbranch_vccz .LBB0_566
	v_mad_i64_i32 v[74:75], s[0:1], v82, s29, 0
	v_lshlrev_b64 v[74:75], 2, v[74:75]
	v_lshl_add_u64 v[76:77], s[94:95], 0, v[74:75]
	v_lshlrev_b64 v[78:79], 2, v[130:131]
	v_lshl_add_u64 v[80:81], v[76:77], 0, v[78:79]
	v_lshl_add_u64 v[88:89], s[88:89], 0, v[78:79]
	v_lshl_add_u64 v[74:75], s[90:91], 0, v[74:75]
	v_lshl_add_u64 v[92:93], v[74:75], 0, v[78:79]
	global_load_dwordx4 v[74:77], v[80:81], off offset:512
	s_nop 0
	global_load_dwordx4 v[78:81], v[80:81], off offset:528
	s_nop 0
	global_load_dwordx4 v[84:87], v[88:89], off offset:512
	s_nop 0
	global_load_dwordx4 v[88:91], v[88:89], off offset:528
	s_mov_b64 s[10:11], 0
	s_waitcnt vmcnt(0) lgkmcnt(0)
	v_pk_fma_f32 v[76:77], v[72:73], v[86:87], v[76:77]
	v_pk_fma_f32 v[74:75], v[70:71], v[84:85], v[74:75]
	global_store_dwordx4 v[92:93], v[74:77], off offset:512
	s_nop 1
	v_pk_fma_f32 v[76:77], v[68:69], v[90:91], v[80:81]
	v_pk_fma_f32 v[74:75], v[66:67], v[88:89], v[78:79]
	global_store_dwordx4 v[92:93], v[74:77], off offset:528
.LBB0_566:
	s_andn2_b64 vcc, exec, s[10:11]
	s_cbranch_vccnz .LBB0_568
	v_cvt_pk_bf16_f32 v70, v70, v71
	v_cvt_pk_bf16_f32 v71, v72, v73
	v_cvt_pk_bf16_f32 v72, v66, v67
	v_mad_i64_i32 v[66:67], s[0:1], v82, s29, 0
	v_lshl_add_u64 v[66:67], v[66:67], 1, s[90:91]
	v_lshl_add_u64 v[66:67], v[130:131], 1, v[66:67]
	v_cvt_pk_bf16_f32 v73, v68, v69
	global_store_dwordx4 v[66:67], v[70:73], off offset:256
.LBB0_568:
	v_add_u32_e32 v66, 0x80, v132
	v_ashrrev_i32_e32 v67, 31, v66
	v_mad_i64_i32 v[70:71], s[0:1], v66, s33, 0
	v_lshlrev_b64 v[68:69], 12, v[66:67]
	s_mov_b64 s[12:13], -1
	s_mov_b64 s[10:11], 0
	s_cmp_lt_i32 s71, 2
	s_mov_b64 s[8:9], 0
	s_cbranch_scc1 .LBB0_577
	s_cmp_gt_i32 s71, 6
	s_cbranch_scc0 .LBB0_573
	s_cmp_eq_u32 s71, 7
	s_mov_b64 s[8:9], -1
	s_cbranch_scc0 .LBB0_572
	v_lshl_add_u64 v[72:73], s[94:95], 0, v[70:71]
	v_lshlrev_b64 v[76:77], 1, v[130:131]
	v_lshl_add_u64 v[72:73], v[72:73], 0, v[76:77]
	v_add_co_u32_e32 v72, vcc, 0x2000, v72
	v_lshl_add_u64 v[78:79], s[90:91], 0, v[68:69]
	s_nop 0
	v_addc_co_u32_e32 v73, vcc, 0, v73, vcc
	global_load_dwordx4 v[72:75], v[72:73], off
	v_lshl_add_u64 v[76:77], v[78:79], 0, v[76:77]
	s_mov_b64 s[8:9], 0
	s_waitcnt vmcnt(0) lgkmcnt(0)
	v_lshlrev_b32_e32 v78, 16, v72
	v_and_b32_e32 v79, 0xffff0000, v72
	v_lshlrev_b32_e32 v72, 16, v73
	v_and_b32_e32 v73, 0xffff0000, v73
	v_lshlrev_b32_e32 v80, 16, v74
	v_and_b32_e32 v81, 0xffff0000, v74
	v_lshlrev_b32_e32 v74, 16, v75
	v_and_b32_e32 v75, 0xffff0000, v75
	v_pk_mul_f32 v[82:83], v[64:65], v[72:73]
	v_pk_mul_f32 v[72:73], v[62:63], v[78:79]
	v_pk_mul_f32 v[78:79], v[60:61], v[74:75]
	v_pk_mul_f32 v[74:75], v[58:59], v[80:81]
	v_cvt_pk_bf16_f32 v72, v72, v73
	v_cvt_pk_bf16_f32 v73, v82, v83
	s_nop 0
	v_cvt_pk_bf16_f32 v74, v74, v75
	v_cvt_pk_bf16_f32 v75, v78, v79
	global_store_dwordx4 v[76:77], v[72:75], off

; DEVI u32x4 pack8(f32x4 a, f32x4 b) { u32x4 o; o.x = cvt_pk_bf16(a[0], a[1]); o.y = cvt_pk_bf16(a[2], a[3]); o.z = cvt_pk_bf16(b[0], b[1]); o.w = cvt_pk_bf16(b[2], b[3]); return o; }
; DEVI float sigmoidf_(float x) { return 1.f / (1.f + __expf(-x)); }
; DEVI void gemm_epi(const GJob& jb, int row, int col, f32x4 v0, f32x4 v1) {
;     ...
;   else if (mode == 2) { f32x4 s0, s1; for (int i = 0; i < 4; ++i) { s0[i] = sigmoidf_(v0[i]); s1[i] = sigmoidf_(v1[i]); } *(u32x4*)((bf16_t*)jb.out + (size_t)row * jb.ldo + col) = pack8(s0, s1); }
.LBB0_573:
	s_and_b64 vcc, exec, s[12:13]
	s_cbranch_vccz .LBB0_576
	s_cmp_eq_u32 s71, 2
	s_mov_b64 s[8:9], -1
	s_cbranch_scc0 .LBB0_576
	v_mul_f32_e32 v0, 0xbfb8aa3b, v62
	v_exp_f32_e32 v0, v0
	s_mov_b64 s[8:9], 0
	v_add_f32_e32 v0, 1.0, v0
	v_div_scale_f32 v67, s[0:1], v0, v0, 1.0
	v_rcp_f32_e32 v72, v67
	s_nop 0
	v_fma_f32 v73, -v67, v72, 1.0
	v_fmac_f32_e32 v72, v73, v72
	v_div_scale_f32 v73, vcc, 1.0, v0, 1.0
	v_mul_f32_e32 v74, v73, v72
	v_fma_f32 v75, -v67, v74, v73
	v_fmac_f32_e32 v74, v75, v72
	v_fma_f32 v67, -v67, v74, v73
	v_div_fmas_f32 v67, v67, v72, v74
	v_div_fixup_f32 v0, v67, v0, 1.0
	v_mul_f32_e32 v67, 0xbfb8aa3b, v58
	v_exp_f32_e32 v67, v67
	s_nop 0
	v_add_f32_e32 v67, 1.0, v67
	v_div_scale_f32 v72, s[0:1], v67, v67, 1.0
	v_rcp_f32_e32 v73, v72
	s_nop 0
	v_fma_f32 v74, -v72, v73, 1.0
	v_fmac_f32_e32 v73, v74, v73
	v_div_scale_f32 v74, vcc, 1.0, v67, 1.0
	v_mul_f32_e32 v75, v74, v73
	v_fma_f32 v76, -v72, v75, v74
	v_fmac_f32_e32 v75, v76, v73
	v_fma_f32 v72, -v72, v75, v74
	v_div_fmas_f32 v72, v72, v73, v75
	v_div_fixup_f32 v67, v72, v67, 1.0
	v_mul_f32_e32 v72, 0xbfb8aa3b, v63
	v_exp_f32_e32 v72, v72
	s_nop 0
	v_add_f32_e32 v72, 1.0, v72
	v_div_scale_f32 v73, s[0:1], v72, v72, 1.0
	v_rcp_f32_e32 v74, v73
	s_nop 0
	v_fma_f32 v75, -v73, v74, 1.0
	v_fmac_f32_e32 v74, v75, v74
	v_div_scale_f32 v75, vcc, 1.0, v72, 1.0
	v_mul_f32_e32 v76, v75, v74
	v_fma_f32 v77, -v73, v76, v75
	v_fmac_f32_e32 v76, v77, v74
	v_fma_f32 v73, -v73, v76, v75
	v_div_fmas_f32 v73, v73, v74, v76
	v_div_fixup_f32 v72, v73, v72, 1.0
	v_mul_f32_e32 v73, 0xbfb8aa3b, v59
	v_exp_f32_e32 v73, v73
	v_cvt_pk_bf16_f32 v72, v0, v72
	s_nop 0
	v_add_f32_e32 v73, 1.0, v73
	v_div_scale_f32 v74, s[0:1], v73, v73, 1.0
	v_rcp_f32_e32 v75, v74
	s_nop 0
	v_fma_f32 v76, -v74, v75, 1.0
	v_fmac_f32_e32 v75, v76, v75
	v_div_scale_f32 v76, vcc, 1.0, v73, 1.0
	v_mul_f32_e32 v77, v76, v75
	v_fma_f32 v78, -v74, v77, v76
	v_fmac_f32_e32 v77, v78, v75
	v_fma_f32 v74, -v74, v77, v76
	v_div_fmas_f32 v74, v74, v75, v77
	v_div_fixup_f32 v74, v74, v73, 1.0
	v_mul_f32_e32 v73, 0xbfb8aa3b, v64
	v_exp_f32_e32 v73, v73
	v_cvt_pk_bf16_f32 v74, v67, v74
	s_nop 0
	v_add_f32_e32 v73, 1.0, v73
	v_div_scale_f32 v75, s[0:1], v73, v73, 1.0
	v_rcp_f32_e32 v76, v75
	s_nop 0
	v_fma_f32 v77, -v75, v76, 1.0
	v_fmac_f32_e32 v76, v77, v76
	v_div_scale_f32 v77, vcc, 1.0, v73, 1.0
	v_mul_f32_e32 v78, v77, v76
	v_fma_f32 v79, -v75, v78, v77
	v_fmac_f32_e32 v78, v79, v76
	v_fma_f32 v75, -v75, v78, v77
	v_div_fmas_f32 v75, v75, v76, v78
	v_div_fixup_f32 v73, v75, v73, 1.0
	v_mul_f32_e32 v75, 0xbfb8aa3b, v60
	v_exp_f32_e32 v75, v75
	s_nop 0
	v_add_f32_e32 v75, 1.0, v75
	v_div_scale_f32 v76, s[0:1], v75, v75, 1.0
	v_rcp_f32_e32 v77, v76
	s_nop 0
	v_fma_f32 v78, -v76, v77, 1.0
	v_fmac_f32_e32 v77, v78, v77
	v_div_scale_f32 v78, vcc, 1.0, v75, 1.0
	v_mul_f32_e32 v79, v78, v77
	v_fma_f32 v80, -v76, v79, v78
	v_fmac_f32_e32 v79, v80, v77
	v_fma_f32 v76, -v76, v79, v78
	v_div_fmas_f32 v76, v76, v77, v79
	v_div_fixup_f32 v75, v76, v75, 1.0
	v_mul_f32_e32 v76, 0xbfb8aa3b, v65
	v_exp_f32_e32 v76, v76
	s_nop 0
	v_add_f32_e32 v76, 1.0, v76
	v_div_scale_f32 v77, s[0:1], v76, v76, 1.0
	v_rcp_f32_e32 v78, v77
	s_nop 0
	v_fma_f32 v79, -v77, v78, 1.0
	v_fmac_f32_e32 v78, v79, v78
	v_div_scale_f32 v79, vcc, 1.0, v76, 1.0
	v_mul_f32_e32 v80, v79, v78
	v_fma_f32 v81, -v77, v80, v79
	v_fmac_f32_e32 v80, v81, v78
	v_fma_f32 v77, -v77, v80, v79
	v_div_fmas_f32 v77, v77, v78, v80
	v_div_fixup_f32 v76, v77, v76, 1.0
	v_mul_f32_e32 v77, 0xbfb8aa3b, v61
	v_exp_f32_e32 v77, v77
	v_cvt_pk_bf16_f32 v73, v73, v76
	s_nop 0
	v_add_f32_e32 v77, 1.0, v77
	v_div_scale_f32 v78, s[0:1], v77, v77, 1.0
	v_rcp_f32_e32 v79, v78
	s_nop 0
	v_fma_f32 v80, -v78, v79, 1.0
	v_fmac_f32_e32 v79, v80, v79
	v_div_scale_f32 v80, vcc, 1.0, v77, 1.0
	v_mul_f32_e32 v81, v80, v79
	v_fma_f32 v82, -v78, v81, v80
	v_fmac_f32_e32 v81, v82, v79
	v_fma_f32 v78, -v78, v81, v80
	v_div_fmas_f32 v78, v78, v79, v81
	v_div_fixup_f32 v77, v78, v77, 1.0
	v_cvt_pk_bf16_f32 v75, v75, v77
	v_mad_i64_i32 v[76:77], s[0:1], v66, s29, 0
	v_lshl_add_u64 v[76:77], v[76:77], 1, s[90:91]
	v_lshl_add_u64 v[76:77], v[130:131], 1, v[76:77]
	global_store_dwordx4 v[76:77], v[72:75], off

; DEVI void gemm_epi(const GJob& jb, int row, int col, f32x4 v0, f32x4 v1) {
;     ...
;   else if (mode == 1) { float* p = (float*)jb.out + (size_t)row * jb.ldo + col; *(f32x4*)p = v0; *(f32x4*)(p + 4) = v1; }
.LBB0_577:
	s_and_b64 vcc, exec, s[12:13]
	s_cbranch_vccz .LBB0_582
	s_cmp_gt_i32 s71, 0
	s_mov_b64 s[10:11], -1
	s_cbranch_scc0 .LBB0_580
	v_mad_i64_i32 v[72:73], s[0:1], v66, s29, 0
	v_lshl_add_u64 v[72:73], v[72:73], 2, s[90:91]
	v_lshl_add_u64 v[72:73], v[130:131], 2, v[72:73]
	global_store_dwordx4 v[72:73], v[62:65], off
	global_store_dwordx4 v[72:73], v[58:61], off offset:16
	s_mov_b64 s[10:11], 0

; DEVI float bf_lo(unsigned u) { return __uint_as_float(u << 16); }
; DEVI float bf_hi(unsigned u) { return __uint_as_float(u & 0xffff0000u); }
; DEVI float sigmoidf_(float x) { return 1.f / (1.f + __expf(-x)); }
; DEVI u32x4 pack8(f32x4 a, f32x4 b) { u32x4 o; o.x = cvt_pk_bf16(a[0], a[1]); o.y = cvt_pk_bf16(a[2], a[3]); o.z = cvt_pk_bf16(b[0], b[1]); o.w = cvt_pk_bf16(b[2], b[3]); return o; }
; DEVI void gemm_epi(const GJob& jb, int row, int col, f32x4 v0, f32x4 v1) {
;     ...
;   if (mode == 0) { *(u32x4*)((bf16_t*)jb.out + (size_t)row * jb.ldo + col) = pack8(v0, v1); }
;   else if (mode == 1) { float* p = (float*)jb.out + (size_t)row * jb.ldo + col; *(f32x4*)p = v0; *(f32x4*)(p + 4) = v1; }
;   else if (mode == 2) { f32x4 s0, s1; for (int i = 0; i < 4; ++i) { s0[i] = sigmoidf_(v0[i]); s1[i] = sigmoidf_(v1[i]); } *(u32x4*)((bf16_t*)jb.out + (size_t)row * jb.ldo + col) = pack8(s0, s1); }
;   else if (mode == 7) {
;     const u32x4 g = *(const u32x4*)((const bf16_t*)jb.aux + (size_t)row * NGATE + 2 * 2048 + col);
;     const f32x4 g0 = {bf_lo(g.x), bf_hi(g.x), bf_lo(g.y), bf_hi(g.y)}, g1 = {bf_lo(g.z), bf_hi(g.z), bf_lo(g.w), bf_hi(g.w)};
;     *(u32x4*)((bf16_t*)jb.out + (size_t)row * 2048 + col) = pack8(g0 * v0, g1 * v1);
;   } else {
;     const float* xp = (const float*)jb.aux + (size_t)row * jb.ldo + col; const float* gp = (const float*)jb.aux2 + col;
;     float* op = (float*)jb.out + (size_t)row * jb.ldo + col;
;     const f32x4 x0 = *(const f32x4*)xp, x1 = *(const f32x4*)(xp + 4), t0 = *(const f32x4*)gp, t1 = *(const f32x4*)(gp + 4);
;     *(f32x4*)op = x0 + t0 * v0; *(f32x4*)(op + 4) = x1 + t1 * v1;
.LBB0_582:
	s_and_b64 vcc, exec, s[8:9]
	s_cbranch_vccz .LBB0_584
	v_mad_i64_i32 v[72:73], s[0:1], v66, s29, 0
	v_lshlrev_b64 v[72:73], 2, v[72:73]
	v_lshl_add_u64 v[74:75], s[94:95], 0, v[72:73]
	v_lshlrev_b64 v[76:77], 2, v[130:131]
	v_lshl_add_u64 v[78:79], v[74:75], 0, v[76:77]
	v_lshl_add_u64 v[84:85], s[88:89], 0, v[76:77]
	v_lshl_add_u64 v[72:73], s[90:91], 0, v[72:73]
	v_lshl_add_u64 v[88:89], v[72:73], 0, v[76:77]
	global_load_dwordx4 v[72:75], v[78:79], off
	s_nop 0
	global_load_dwordx4 v[76:79], v[78:79], off offset:16
	s_nop 0
	global_load_dwordx4 v[80:83], v[84:85], off
	s_nop 0
	global_load_dwordx4 v[84:87], v[84:85], off offset:16
	s_mov_b64 s[10:11], 0
	s_waitcnt vmcnt(0) lgkmcnt(0)
	v_pk_fma_f32 v[74:75], v[64:65], v[82:83], v[74:75]
	v_pk_fma_f32 v[72:73], v[62:63], v[80:81], v[72:73]
	global_store_dwordx4 v[88:89], v[72:75], off
	s_nop 1
	v_pk_fma_f32 v[74:75], v[60:61], v[86:87], v[78:79]
	v_pk_fma_f32 v[72:73], v[58:59], v[84:85], v[76:77]
	global_store_dwordx4 v[88:89], v[72:75], off offset:16
.LBB0_584:
	s_andn2_b64 vcc, exec, s[10:11]
	s_cbranch_vccnz .LBB0_586
	v_cvt_pk_bf16_f32 v62, v62, v63
	v_cvt_pk_bf16_f32 v63, v64, v65
	v_cvt_pk_bf16_f32 v64, v58, v59
	v_mad_i64_i32 v[58:59], s[0:1], v66, s29, 0
	v_lshl_add_u64 v[58:59], v[58:59], 1, s[90:91]
	v_lshl_add_u64 v[58:59], v[130:131], 1, v[58:59]
	v_cvt_pk_bf16_f32 v65, v60, v61
	global_store_dwordx4 v[58:59], v[62:65], off
.LBB0_586:
	s_mov_b64 s[12:13], -1
	s_mov_b64 s[10:11], 0
	s_cmp_lt_i32 s71, 2
	s_mov_b64 s[8:9], 0
	s_cbranch_scc1 .LBB0_595
	s_cmp_gt_i32 s71, 6
	s_cbranch_scc0 .LBB0_591
	s_cmp_eq_u32 s71, 7
	s_mov_b64 s[8:9], -1
	s_cbranch_scc0 .LBB0_590
	v_lshl_add_u64 v[58:59], s[94:95], 0, v[70:71]
	v_ashrrev_i32_e32 v123, 31, v122
	v_lshl_add_u64 v[58:59], v[122:123], 1, v[58:59]
	v_add_co_u32_e32 v58, vcc, 0x2000, v58
	v_lshl_add_u64 v[62:63], s[90:91], 0, v[68:69]
	s_nop 0
	v_addc_co_u32_e32 v59, vcc, 0, v59, vcc
	global_load_dwordx4 v[58:61], v[58:59], off
	v_lshl_add_u64 v[62:63], v[130:131], 1, v[62:63]
	s_mov_b64 s[8:9], 0
	s_waitcnt vmcnt(0) lgkmcnt(0)
	v_lshlrev_b32_e32 v64, 16, v58
	v_and_b32_e32 v65, 0xffff0000, v58
	v_lshlrev_b32_e32 v58, 16, v59
	v_and_b32_e32 v59, 0xffff0000, v59
	v_lshlrev_b32_e32 v68, 16, v60
	v_and_b32_e32 v69, 0xffff0000, v60
	v_lshlrev_b32_e32 v60, 16, v61
	v_and_b32_e32 v61, 0xffff0000, v61
	v_pk_mul_f32 v[70:71], v[56:57], v[58:59]
	v_pk_mul_f32 v[58:59], v[54:55], v[64:65]
	v_pk_mul_f32 v[64:65], v[52:53], v[60:61]
	v_pk_mul_f32 v[60:61], v[50:51], v[68:69]
	v_cvt_pk_bf16_f32 v58, v58, v59
	v_cvt_pk_bf16_f32 v59, v70, v71
	s_nop 0
	v_cvt_pk_bf16_f32 v60, v60, v61
	v_cvt_pk_bf16_f32 v61, v64, v65
	global_store_dwordx4 v[62:63], v[58:61], off offset:256

; DEVI u32x4 pack8(f32x4 a, f32x4 b) { u32x4 o; o.x = cvt_pk_bf16(a[0], a[1]); o.y = cvt_pk_bf16(a[2], a[3]); o.z = cvt_pk_bf16(b[0], b[1]); o.w = cvt_pk_bf16(b[2], b[3]); return o; }
; DEVI float sigmoidf_(float x) { return 1.f / (1.f + __expf(-x)); }
; DEVI void gemm_epi(const GJob& jb, int row, int col, f32x4 v0, f32x4 v1) {
;     ...
;   else if (mode == 2) { f32x4 s0, s1; for (int i = 0; i < 4; ++i) { s0[i] = sigmoidf_(v0[i]); s1[i] = sigmoidf_(v1[i]); } *(u32x4*)((bf16_t*)jb.out + (size_t)row * jb.ldo + col) = pack8(s0, s1); }
.LBB0_591:
	s_and_b64 vcc, exec, s[12:13]
	s_cbranch_vccz .LBB0_594
	s_cmp_eq_u32 s71, 2
	s_mov_b64 s[8:9], -1
	s_cbranch_scc0 .LBB0_594
	v_mul_f32_e32 v0, 0xbfb8aa3b, v54
	v_exp_f32_e32 v0, v0
	s_mov_b64 s[8:9], 0
	v_add_f32_e32 v0, 1.0, v0
	v_div_scale_f32 v58, s[0:1], v0, v0, 1.0
	v_rcp_f32_e32 v59, v58
	s_nop 0
	v_fma_f32 v60, -v58, v59, 1.0
	v_fmac_f32_e32 v59, v60, v59
	v_div_scale_f32 v60, vcc, 1.0, v0, 1.0
	v_mul_f32_e32 v61, v60, v59
	v_fma_f32 v62, -v58, v61, v60
	v_fmac_f32_e32 v61, v62, v59
	v_fma_f32 v58, -v58, v61, v60
	v_div_fmas_f32 v58, v58, v59, v61
	v_div_fixup_f32 v0, v58, v0, 1.0
	v_mul_f32_e32 v58, 0xbfb8aa3b, v50
	v_exp_f32_e32 v58, v58
	s_nop 0
	v_add_f32_e32 v58, 1.0, v58
	v_div_scale_f32 v59, s[0:1], v58, v58, 1.0
	v_rcp_f32_e32 v60, v59
	s_nop 0
	v_fma_f32 v61, -v59, v60, 1.0
	v_fmac_f32_e32 v60, v61, v60
	v_div_scale_f32 v61, vcc, 1.0, v58, 1.0
	v_mul_f32_e32 v62, v61, v60
	v_fma_f32 v63, -v59, v62, v61
	v_fmac_f32_e32 v62, v63, v60
	v_fma_f32 v59, -v59, v62, v61
	v_div_fmas_f32 v59, v59, v60, v62
	v_div_fixup_f32 v60, v59, v58, 1.0
	v_mul_f32_e32 v58, 0xbfb8aa3b, v55
	v_exp_f32_e32 v58, v58
	s_nop 0
	v_add_f32_e32 v58, 1.0, v58
	v_div_scale_f32 v59, s[0:1], v58, v58, 1.0
	v_rcp_f32_e32 v61, v59
	s_nop 0
	v_fma_f32 v62, -v59, v61, 1.0
	v_fmac_f32_e32 v61, v62, v61
	v_div_scale_f32 v62, vcc, 1.0, v58, 1.0
	v_mul_f32_e32 v63, v62, v61
	v_fma_f32 v64, -v59, v63, v62
	v_fmac_f32_e32 v63, v64, v61
	v_fma_f32 v59, -v59, v63, v62
	v_div_fmas_f32 v59, v59, v61, v63
	v_div_fixup_f32 v58, v59, v58, 1.0
	v_mul_f32_e32 v59, 0xbfb8aa3b, v51
	v_exp_f32_e32 v59, v59
	v_cvt_pk_bf16_f32 v58, v0, v58
	s_nop 0
	v_add_f32_e32 v59, 1.0, v59
	v_div_scale_f32 v61, s[0:1], v59, v59, 1.0
	v_rcp_f32_e32 v62, v61
	s_nop 0
	v_fma_f32 v63, -v61, v62, 1.0
	v_fmac_f32_e32 v62, v63, v62
	v_div_scale_f32 v63, vcc, 1.0, v59, 1.0
	v_mul_f32_e32 v64, v63, v62
	v_fma_f32 v65, -v61, v64, v63
	v_fmac_f32_e32 v64, v65, v62
	v_fma_f32 v61, -v61, v64, v63
	v_div_fmas_f32 v61, v61, v62, v64
	v_div_fixup_f32 v61, v61, v59, 1.0
	v_mul_f32_e32 v59, 0xbfb8aa3b, v56
	v_exp_f32_e32 v59, v59
	v_cvt_pk_bf16_f32 v60, v60, v61
	s_nop 0
	v_add_f32_e32 v59, 1.0, v59
	v_div_scale_f32 v62, s[0:1], v59, v59, 1.0
	v_rcp_f32_e32 v63, v62
	s_nop 0
	v_fma_f32 v64, -v62, v63, 1.0
	v_fmac_f32_e32 v63, v64, v63
	v_div_scale_f32 v64, vcc, 1.0, v59, 1.0
	v_mul_f32_e32 v65, v64, v63
	v_fma_f32 v67, -v62, v65, v64
	v_fmac_f32_e32 v65, v67, v63
	v_fma_f32 v62, -v62, v65, v64
	v_div_fmas_f32 v62, v62, v63, v65
	v_div_fixup_f32 v59, v62, v59, 1.0
	v_mul_f32_e32 v62, 0xbfb8aa3b, v52
	v_exp_f32_e32 v62, v62
	s_nop 0
	v_add_f32_e32 v62, 1.0, v62
	v_div_scale_f32 v63, s[0:1], v62, v62, 1.0
	v_rcp_f32_e32 v64, v63
	s_nop 0
	v_fma_f32 v65, -v63, v64, 1.0
	v_fmac_f32_e32 v64, v65, v64
	v_div_scale_f32 v65, vcc, 1.0, v62, 1.0
	v_mul_f32_e32 v67, v65, v64
	v_fma_f32 v68, -v63, v67, v65
	v_fmac_f32_e32 v67, v68, v64
	v_fma_f32 v63, -v63, v67, v65
	v_div_fmas_f32 v63, v63, v64, v67
	v_div_fixup_f32 v62, v63, v62, 1.0
	v_mul_f32_e32 v63, 0xbfb8aa3b, v57
	v_exp_f32_e32 v63, v63
	s_nop 0
	v_add_f32_e32 v63, 1.0, v63
	v_div_scale_f32 v64, s[0:1], v63, v63, 1.0
	v_rcp_f32_e32 v65, v64
	s_nop 0
	v_fma_f32 v67, -v64, v65, 1.0
	v_fmac_f32_e32 v65, v67, v65
	v_div_scale_f32 v67, vcc, 1.0, v63, 1.0
	v_mul_f32_e32 v68, v67, v65
	v_fma_f32 v69, -v64, v68, v67
	v_fmac_f32_e32 v68, v69, v65
	v_fma_f32 v64, -v64, v68, v67
	v_div_fmas_f32 v64, v64, v65, v68
	v_div_fixup_f32 v63, v64, v63, 1.0
	v_mul_f32_e32 v64, 0xbfb8aa3b, v53
	v_exp_f32_e32 v64, v64
	v_cvt_pk_bf16_f32 v59, v59, v63
	s_nop 0
	v_add_f32_e32 v64, 1.0, v64
	v_div_scale_f32 v65, s[0:1], v64, v64, 1.0
	v_rcp_f32_e32 v67, v65
	s_nop 0
	v_fma_f32 v68, -v65, v67, 1.0
	v_fmac_f32_e32 v67, v68, v67
	v_div_scale_f32 v68, vcc, 1.0, v64, 1.0
	v_mul_f32_e32 v69, v68, v67
	v_fma_f32 v70, -v65, v69, v68
	v_fmac_f32_e32 v69, v70, v67
	v_fma_f32 v65, -v65, v69, v68
	v_div_fmas_f32 v65, v65, v67, v69
	v_div_fixup_f32 v64, v65, v64, 1.0
	v_cvt_pk_bf16_f32 v61, v62, v64
	v_mad_i64_i32 v[62:63], s[0:1], v66, s29, 0
	v_lshl_add_u64 v[62:63], v[62:63], 1, s[90:91]
	v_lshl_add_u64 v[62:63], v[130:131], 1, v[62:63]
	global_store_dwordx4 v[62:63], v[58:61], off offset:256

; DEVI void gemm_epi(const GJob& jb, int row, int col, f32x4 v0, f32x4 v1) {
;     ...
;   else if (mode == 1) { float* p = (float*)jb.out + (size_t)row * jb.ldo + col; *(f32x4*)p = v0; *(f32x4*)(p + 4) = v1; }
.LBB0_595:
	s_and_b64 vcc, exec, s[12:13]
	s_cbranch_vccz .LBB0_600
	s_cmp_gt_i32 s71, 0
	s_mov_b64 s[10:11], -1
	s_cbranch_scc0 .LBB0_598
	v_mad_i64_i32 v[58:59], s[0:1], v66, s29, 0
	v_lshl_add_u64 v[58:59], v[58:59], 2, s[90:91]
	v_lshl_add_u64 v[58:59], v[130:131], 2, v[58:59]
	global_store_dwordx4 v[58:59], v[54:57], off offset:512
	global_store_dwordx4 v[58:59], v[50:53], off offset:528
	s_mov_b64 s[10:11], 0

; DEVI float bf_lo(unsigned u) { return __uint_as_float(u << 16); }
; DEVI float bf_hi(unsigned u) { return __uint_as_float(u & 0xffff0000u); }
; DEVI float sigmoidf_(float x) { return 1.f / (1.f + __expf(-x)); }
; DEVI u32x4 pack8(f32x4 a, f32x4 b) { u32x4 o; o.x = cvt_pk_bf16(a[0], a[1]); o.y = cvt_pk_bf16(a[2], a[3]); o.z = cvt_pk_bf16(b[0], b[1]); o.w = cvt_pk_bf16(b[2], b[3]); return o; }
; DEVI void gemm_epi(const GJob& jb, int row, int col, f32x4 v0, f32x4 v1) {
;     ...
;   if (mode == 0) { *(u32x4*)((bf16_t*)jb.out + (size_t)row * jb.ldo + col) = pack8(v0, v1); }
;   else if (mode == 1) { float* p = (float*)jb.out + (size_t)row * jb.ldo + col; *(f32x4*)p = v0; *(f32x4*)(p + 4) = v1; }
;   else if (mode == 2) { f32x4 s0, s1; for (int i = 0; i < 4; ++i) { s0[i] = sigmoidf_(v0[i]); s1[i] = sigmoidf_(v1[i]); } *(u32x4*)((bf16_t*)jb.out + (size_t)row * jb.ldo + col) = pack8(s0, s1); }
;   else if (mode == 7) {
;     const u32x4 g = *(const u32x4*)((const bf16_t*)jb.aux + (size_t)row * NGATE + 2 * 2048 + col);
;     const f32x4 g0 = {bf_lo(g.x), bf_hi(g.x), bf_lo(g.y), bf_hi(g.y)}, g1 = {bf_lo(g.z), bf_hi(g.z), bf_lo(g.w), bf_hi(g.w)};
;     *(u32x4*)((bf16_t*)jb.out + (size_t)row * 2048 + col) = pack8(g0 * v0, g1 * v1);
;   } else {
;     const float* xp = (const float*)jb.aux + (size_t)row * jb.ldo + col; const float* gp = (const float*)jb.aux2 + col;
;     float* op = (float*)jb.out + (size_t)row * jb.ldo + col;
;     const f32x4 x0 = *(const f32x4*)xp, x1 = *(const f32x4*)(xp + 4), t0 = *(const f32x4*)gp, t1 = *(const f32x4*)(gp + 4);
;     *(f32x4*)op = x0 + t0 * v0; *(f32x4*)(op + 4) = x1 + t1 * v1;
.LBB0_600:
	s_and_b64 vcc, exec, s[8:9]
	s_cbranch_vccz .LBB0_602
	v_mad_i64_i32 v[58:59], s[0:1], v66, s29, 0
	v_lshlrev_b64 v[58:59], 2, v[58:59]
	v_lshl_add_u64 v[60:61], s[94:95], 0, v[58:59]
	v_lshlrev_b64 v[62:63], 2, v[130:131]
	v_lshl_add_u64 v[64:65], v[60:61], 0, v[62:63]
	v_lshl_add_u64 v[72:73], s[88:89], 0, v[62:63]
	v_lshl_add_u64 v[58:59], s[90:91], 0, v[58:59]
	v_lshl_add_u64 v[76:77], v[58:59], 0, v[62:63]
	global_load_dwordx4 v[58:61], v[64:65], off offset:512
	s_nop 0
	global_load_dwordx4 v[62:65], v[64:65], off offset:528
	s_nop 0
	global_load_dwordx4 v[68:71], v[72:73], off offset:512
	s_nop 0
	global_load_dwordx4 v[72:75], v[72:73], off offset:528
	s_mov_b64 s[10:11], 0
	s_waitcnt vmcnt(0) lgkmcnt(0)
	v_pk_fma_f32 v[60:61], v[56:57], v[70:71], v[60:61]
	v_pk_fma_f32 v[58:59], v[54:55], v[68:69], v[58:59]
	global_store_dwordx4 v[76:77], v[58:61], off offset:512
	s_nop 1
	v_pk_fma_f32 v[60:61], v[52:53], v[74:75], v[64:65]
	v_pk_fma_f32 v[58:59], v[50:51], v[72:73], v[62:63]
	global_store_dwordx4 v[76:77], v[58:61], off offset:528
.LBB0_602:
	s_andn2_b64 vcc, exec, s[10:11]
	s_cbranch_vccnz .LBB0_604
	v_cvt_pk_bf16_f32 v54, v54, v55
	v_cvt_pk_bf16_f32 v55, v56, v57
	v_cvt_pk_bf16_f32 v56, v50, v51
	v_mad_i64_i32 v[50:51], s[0:1], v66, s29, 0
	v_lshl_add_u64 v[50:51], v[50:51], 1, s[90:91]
	v_lshl_add_u64 v[50:51], v[130:131], 1, v[50:51]
	v_cvt_pk_bf16_f32 v57, v52, v53
	global_store_dwordx4 v[50:51], v[54:57], off offset:256
.LBB0_604:
	v_add_u32_e32 v50, 0x90, v132
	v_ashrrev_i32_e32 v51, 31, v50
	v_mad_i64_i32 v[54:55], s[0:1], v50, s33, 0
	v_lshlrev_b64 v[52:53], 12, v[50:51]
	s_mov_b64 s[12:13], -1
	s_mov_b64 s[10:11], 0
	s_cmp_lt_i32 s71, 2
	s_mov_b64 s[8:9], 0
	s_cbranch_scc1 .LBB0_613
	s_cmp_gt_i32 s71, 6
	s_cbranch_scc0 .LBB0_609
	s_cmp_eq_u32 s71, 7
	s_mov_b64 s[8:9], -1
	s_cbranch_scc0 .LBB0_608
	v_lshl_add_u64 v[56:57], s[94:95], 0, v[54:55]
	v_lshlrev_b64 v[60:61], 1, v[130:131]
	v_lshl_add_u64 v[56:57], v[56:57], 0, v[60:61]
	v_add_co_u32_e32 v56, vcc, 0x2000, v56
	v_lshl_add_u64 v[62:63], s[90:91], 0, v[52:53]
	s_nop 0
	v_addc_co_u32_e32 v57, vcc, 0, v57, vcc
	global_load_dwordx4 v[56:59], v[56:57], off
	v_lshl_add_u64 v[60:61], v[62:63], 0, v[60:61]
	s_mov_b64 s[8:9], 0
	s_waitcnt vmcnt(0) lgkmcnt(0)
	v_lshlrev_b32_e32 v62, 16, v56
	v_and_b32_e32 v63, 0xffff0000, v56
	v_lshlrev_b32_e32 v56, 16, v57
	v_and_b32_e32 v57, 0xffff0000, v57
	v_lshlrev_b32_e32 v64, 16, v58
	v_and_b32_e32 v65, 0xffff0000, v58
	v_lshlrev_b32_e32 v58, 16, v59
	v_and_b32_e32 v59, 0xffff0000, v59
	v_pk_mul_f32 v[66:67], v[48:49], v[56:57]
	v_pk_mul_f32 v[56:57], v[46:47], v[62:63]
	v_pk_mul_f32 v[62:63], v[44:45], v[58:59]
	v_pk_mul_f32 v[58:59], v[42:43], v[64:65]
	v_cvt_pk_bf16_f32 v56, v56, v57
	v_cvt_pk_bf16_f32 v57, v66, v67
	s_nop 0
	v_cvt_pk_bf16_f32 v58, v58, v59
	v_cvt_pk_bf16_f32 v59, v62, v63
	global_store_dwordx4 v[60:61], v[56:59], off

; DEVI u32x4 pack8(f32x4 a, f32x4 b) { u32x4 o; o.x = cvt_pk_bf16(a[0], a[1]); o.y = cvt_pk_bf16(a[2], a[3]); o.z = cvt_pk_bf16(b[0], b[1]); o.w = cvt_pk_bf16(b[2], b[3]); return o; }
; DEVI float sigmoidf_(float x) { return 1.f / (1.f + __expf(-x)); }
; DEVI void gemm_epi(const GJob& jb, int row, int col, f32x4 v0, f32x4 v1) {
;     ...
;   else if (mode == 2) { f32x4 s0, s1; for (int i = 0; i < 4; ++i) { s0[i] = sigmoidf_(v0[i]); s1[i] = sigmoidf_(v1[i]); } *(u32x4*)((bf16_t*)jb.out + (size_t)row * jb.ldo + col) = pack8(s0, s1); }
.LBB0_609:
	s_and_b64 vcc, exec, s[12:13]
	s_cbranch_vccz .LBB0_612
	s_cmp_eq_u32 s71, 2
	s_mov_b64 s[8:9], -1
	s_cbranch_scc0 .LBB0_612
	v_mul_f32_e32 v0, 0xbfb8aa3b, v46
	v_exp_f32_e32 v0, v0
	s_mov_b64 s[8:9], 0
	v_add_f32_e32 v0, 1.0, v0
	v_div_scale_f32 v51, s[0:1], v0, v0, 1.0
	v_rcp_f32_e32 v56, v51
	s_nop 0
	v_fma_f32 v57, -v51, v56, 1.0
	v_fmac_f32_e32 v56, v57, v56
	v_div_scale_f32 v57, vcc, 1.0, v0, 1.0
	v_mul_f32_e32 v58, v57, v56
	v_fma_f32 v59, -v51, v58, v57
	v_fmac_f32_e32 v58, v59, v56
	v_fma_f32 v51, -v51, v58, v57
	v_div_fmas_f32 v51, v51, v56, v58
	v_div_fixup_f32 v0, v51, v0, 1.0
	v_mul_f32_e32 v51, 0xbfb8aa3b, v42
	v_exp_f32_e32 v51, v51
	s_nop 0
	v_add_f32_e32 v51, 1.0, v51
	v_div_scale_f32 v56, s[0:1], v51, v51, 1.0
	v_rcp_f32_e32 v57, v56
	s_nop 0
	v_fma_f32 v58, -v56, v57, 1.0
	v_fmac_f32_e32 v57, v58, v57
	v_div_scale_f32 v58, vcc, 1.0, v51, 1.0
	v_mul_f32_e32 v59, v58, v57
	v_fma_f32 v60, -v56, v59, v58
	v_fmac_f32_e32 v59, v60, v57
	v_fma_f32 v56, -v56, v59, v58
	v_div_fmas_f32 v56, v56, v57, v59
	v_div_fixup_f32 v51, v56, v51, 1.0
	v_mul_f32_e32 v56, 0xbfb8aa3b, v47
	v_exp_f32_e32 v56, v56
	s_nop 0
	v_add_f32_e32 v56, 1.0, v56
	v_div_scale_f32 v57, s[0:1], v56, v56, 1.0
	v_rcp_f32_e32 v58, v57
	s_nop 0
	v_fma_f32 v59, -v57, v58, 1.0
	v_fmac_f32_e32 v58, v59, v58
	v_div_scale_f32 v59, vcc, 1.0, v56, 1.0
	v_mul_f32_e32 v60, v59, v58
	v_fma_f32 v61, -v57, v60, v59
	v_fmac_f32_e32 v60, v61, v58
	v_fma_f32 v57, -v57, v60, v59
	v_div_fmas_f32 v57, v57, v58, v60
	v_div_fixup_f32 v56, v57, v56, 1.0
	v_mul_f32_e32 v57, 0xbfb8aa3b, v43
	v_exp_f32_e32 v57, v57
	v_cvt_pk_bf16_f32 v56, v0, v56
	s_nop 0
	v_add_f32_e32 v57, 1.0, v57
	v_div_scale_f32 v58, s[0:1], v57, v57, 1.0
	v_rcp_f32_e32 v59, v58
	s_nop 0
	v_fma_f32 v60, -v58, v59, 1.0
	v_fmac_f32_e32 v59, v60, v59
	v_div_scale_f32 v60, vcc, 1.0, v57, 1.0
	v_mul_f32_e32 v61, v60, v59
	v_fma_f32 v62, -v58, v61, v60
	v_fmac_f32_e32 v61, v62, v59
	v_fma_f32 v58, -v58, v61, v60
	v_div_fmas_f32 v58, v58, v59, v61
	v_div_fixup_f32 v58, v58, v57, 1.0
	v_mul_f32_e32 v57, 0xbfb8aa3b, v48
	v_exp_f32_e32 v57, v57
	v_cvt_pk_bf16_f32 v58, v51, v58
	s_nop 0
	v_add_f32_e32 v57, 1.0, v57
	v_div_scale_f32 v59, s[0:1], v57, v57, 1.0
	v_rcp_f32_e32 v60, v59
	s_nop 0
	v_fma_f32 v61, -v59, v60, 1.0
	v_fmac_f32_e32 v60, v61, v60
	v_div_scale_f32 v61, vcc, 1.0, v57, 1.0
	v_mul_f32_e32 v62, v61, v60
	v_fma_f32 v63, -v59, v62, v61
	v_fmac_f32_e32 v62, v63, v60
	v_fma_f32 v59, -v59, v62, v61
	v_div_fmas_f32 v59, v59, v60, v62
	v_div_fixup_f32 v57, v59, v57, 1.0
	v_mul_f32_e32 v59, 0xbfb8aa3b, v44
	v_exp_f32_e32 v59, v59
	s_nop 0
	v_add_f32_e32 v59, 1.0, v59
	v_div_scale_f32 v60, s[0:1], v59, v59, 1.0
	v_rcp_f32_e32 v61, v60
	s_nop 0
	v_fma_f32 v62, -v60, v61, 1.0
	v_fmac_f32_e32 v61, v62, v61
	v_div_scale_f32 v62, vcc, 1.0, v59, 1.0
	v_mul_f32_e32 v63, v62, v61
	v_fma_f32 v64, -v60, v63, v62
	v_fmac_f32_e32 v63, v64, v61
	v_fma_f32 v60, -v60, v63, v62
	v_div_fmas_f32 v60, v60, v61, v63
	v_div_fixup_f32 v59, v60, v59, 1.0
	v_mul_f32_e32 v60, 0xbfb8aa3b, v49
	v_exp_f32_e32 v60, v60
	s_nop 0
	v_add_f32_e32 v60, 1.0, v60
	v_div_scale_f32 v61, s[0:1], v60, v60, 1.0
	v_rcp_f32_e32 v62, v61
	s_nop 0
	v_fma_f32 v63, -v61, v62, 1.0
	v_fmac_f32_e32 v62, v63, v62
	v_div_scale_f32 v63, vcc, 1.0, v60, 1.0
	v_mul_f32_e32 v64, v63, v62
	v_fma_f32 v65, -v61, v64, v63
	v_fmac_f32_e32 v64, v65, v62
	v_fma_f32 v61, -v61, v64, v63
	v_div_fmas_f32 v61, v61, v62, v64
	v_div_fixup_f32 v60, v61, v60, 1.0
	v_mul_f32_e32 v61, 0xbfb8aa3b, v45
	v_exp_f32_e32 v61, v61
	v_cvt_pk_bf16_f32 v57, v57, v60
	s_nop 0
	v_add_f32_e32 v61, 1.0, v61
	v_div_scale_f32 v62, s[0:1], v61, v61, 1.0
	v_rcp_f32_e32 v63, v62
	s_nop 0
	v_fma_f32 v64, -v62, v63, 1.0
	v_fmac_f32_e32 v63, v64, v63
	v_div_scale_f32 v64, vcc, 1.0, v61, 1.0
	v_mul_f32_e32 v65, v64, v63
	v_fma_f32 v66, -v62, v65, v64
	v_fmac_f32_e32 v65, v66, v63
	v_fma_f32 v62, -v62, v65, v64
	v_div_fmas_f32 v62, v62, v63, v65
	v_div_fixup_f32 v61, v62, v61, 1.0
	v_cvt_pk_bf16_f32 v59, v59, v61
	v_mad_i64_i32 v[60:61], s[0:1], v50, s29, 0
	v_lshl_add_u64 v[60:61], v[60:61], 1, s[90:91]
	v_lshl_add_u64 v[60:61], v[130:131], 1, v[60:61]
	global_store_dwordx4 v[60:61], v[56:59], off

; DEVI void gemm_epi(const GJob& jb, int row, int col, f32x4 v0, f32x4 v1) {
;     ...
;   else if (mode == 1) { float* p = (float*)jb.out + (size_t)row * jb.ldo + col; *(f32x4*)p = v0; *(f32x4*)(p + 4) = v1; }
.LBB0_613:
	s_and_b64 vcc, exec, s[12:13]
	s_cbranch_vccz .LBB0_618
	s_cmp_gt_i32 s71, 0
	s_mov_b64 s[10:11], -1
	s_cbranch_scc0 .LBB0_616
	v_mad_i64_i32 v[56:57], s[0:1], v50, s29, 0
	v_lshl_add_u64 v[56:57], v[56:57], 2, s[90:91]
	v_lshl_add_u64 v[56:57], v[130:131], 2, v[56:57]
	global_store_dwordx4 v[56:57], v[46:49], off
	global_store_dwordx4 v[56:57], v[42:45], off offset:16
	s_mov_b64 s[10:11], 0

; DEVI float bf_lo(unsigned u) { return __uint_as_float(u << 16); }
; DEVI float bf_hi(unsigned u) { return __uint_as_float(u & 0xffff0000u); }
; DEVI float sigmoidf_(float x) { return 1.f / (1.f + __expf(-x)); }
; DEVI u32x4 pack8(f32x4 a, f32x4 b) { u32x4 o; o.x = cvt_pk_bf16(a[0], a[1]); o.y = cvt_pk_bf16(a[2], a[3]); o.z = cvt_pk_bf16(b[0], b[1]); o.w = cvt_pk_bf16(b[2], b[3]); return o; }
; DEVI void gemm_epi(const GJob& jb, int row, int col, f32x4 v0, f32x4 v1) {
;     ...
;   if (mode == 0) { *(u32x4*)((bf16_t*)jb.out + (size_t)row * jb.ldo + col) = pack8(v0, v1); }
;   else if (mode == 1) { float* p = (float*)jb.out + (size_t)row * jb.ldo + col; *(f32x4*)p = v0; *(f32x4*)(p + 4) = v1; }
;   else if (mode == 2) { f32x4 s0, s1; for (int i = 0; i < 4; ++i) { s0[i] = sigmoidf_(v0[i]); s1[i] = sigmoidf_(v1[i]); } *(u32x4*)((bf16_t*)jb.out + (size_t)row * jb.ldo + col) = pack8(s0, s1); }
;   else if (mode == 7) {
;     const u32x4 g = *(const u32x4*)((const bf16_t*)jb.aux + (size_t)row * NGATE + 2 * 2048 + col);
;     const f32x4 g0 = {bf_lo(g.x), bf_hi(g.x), bf_lo(g.y), bf_hi(g.y)}, g1 = {bf_lo(g.z), bf_hi(g.z), bf_lo(g.w), bf_hi(g.w)};
;     *(u32x4*)((bf16_t*)jb.out + (size_t)row * 2048 + col) = pack8(g0 * v0, g1 * v1);
;   } else {
;     const float* xp = (const float*)jb.aux + (size_t)row * jb.ldo + col; const float* gp = (const float*)jb.aux2 + col;
;     float* op = (float*)jb.out + (size_t)row * jb.ldo + col;
;     const f32x4 x0 = *(const f32x4*)xp, x1 = *(const f32x4*)(xp + 4), t0 = *(const f32x4*)gp, t1 = *(const f32x4*)(gp + 4);
;     *(f32x4*)op = x0 + t0 * v0; *(f32x4*)(op + 4) = x1 + t1 * v1;
.LBB0_618:
	s_and_b64 vcc, exec, s[8:9]
	s_cbranch_vccz .LBB0_620
	v_mad_i64_i32 v[56:57], s[0:1], v50, s29, 0
	v_lshlrev_b64 v[56:57], 2, v[56:57]
	v_lshl_add_u64 v[58:59], s[94:95], 0, v[56:57]
	v_lshlrev_b64 v[60:61], 2, v[130:131]
	v_lshl_add_u64 v[62:63], v[58:59], 0, v[60:61]
	v_lshl_add_u64 v[68:69], s[88:89], 0, v[60:61]
	v_lshl_add_u64 v[56:57], s[90:91], 0, v[56:57]
	v_lshl_add_u64 v[72:73], v[56:57], 0, v[60:61]
	global_load_dwordx4 v[56:59], v[62:63], off
	s_nop 0
	global_load_dwordx4 v[60:63], v[62:63], off offset:16
	s_nop 0
	global_load_dwordx4 v[64:67], v[68:69], off
	s_nop 0
	global_load_dwordx4 v[68:71], v[68:69], off offset:16
	s_mov_b64 s[10:11], 0
	s_waitcnt vmcnt(0) lgkmcnt(0)
	v_pk_fma_f32 v[58:59], v[48:49], v[66:67], v[58:59]
	v_pk_fma_f32 v[56:57], v[46:47], v[64:65], v[56:57]
	global_store_dwordx4 v[72:73], v[56:59], off
	s_nop 1
	v_pk_fma_f32 v[58:59], v[44:45], v[70:71], v[62:63]
	v_pk_fma_f32 v[56:57], v[42:43], v[68:69], v[60:61]
	global_store_dwordx4 v[72:73], v[56:59], off offset:16
.LBB0_620:
	s_andn2_b64 vcc, exec, s[10:11]
	s_cbranch_vccnz .LBB0_622
	v_cvt_pk_bf16_f32 v46, v46, v47
	v_cvt_pk_bf16_f32 v47, v48, v49
	v_cvt_pk_bf16_f32 v48, v42, v43
	v_mad_i64_i32 v[42:43], s[0:1], v50, s29, 0
	v_lshl_add_u64 v[42:43], v[42:43], 1, s[90:91]
	v_lshl_add_u64 v[42:43], v[130:131], 1, v[42:43]
	v_cvt_pk_bf16_f32 v49, v44, v45
	global_store_dwordx4 v[42:43], v[46:49], off
.LBB0_622:
	s_mov_b64 s[12:13], -1
	s_mov_b64 s[10:11], 0
	s_cmp_lt_i32 s71, 2
	s_mov_b64 s[8:9], 0
	s_cbranch_scc1 .LBB0_631
	s_cmp_gt_i32 s71, 6
	s_cbranch_scc0 .LBB0_627
	s_cmp_eq_u32 s71, 7
	s_mov_b64 s[8:9], -1
	s_cbranch_scc0 .LBB0_626
	v_lshl_add_u64 v[42:43], s[94:95], 0, v[54:55]
	v_ashrrev_i32_e32 v123, 31, v122
	v_lshl_add_u64 v[42:43], v[122:123], 1, v[42:43]
	v_add_co_u32_e32 v42, vcc, 0x2000, v42
	v_lshl_add_u64 v[46:47], s[90:91], 0, v[52:53]
	s_nop 0
	v_addc_co_u32_e32 v43, vcc, 0, v43, vcc
	global_load_dwordx4 v[42:45], v[42:43], off
	v_lshl_add_u64 v[46:47], v[130:131], 1, v[46:47]
	s_mov_b64 s[8:9], 0
	s_waitcnt vmcnt(0) lgkmcnt(0)
	v_lshlrev_b32_e32 v48, 16, v42
	v_and_b32_e32 v49, 0xffff0000, v42
	v_lshlrev_b32_e32 v42, 16, v43
	v_and_b32_e32 v43, 0xffff0000, v43
	v_lshlrev_b32_e32 v52, 16, v44
	v_and_b32_e32 v53, 0xffff0000, v44
	v_lshlrev_b32_e32 v44, 16, v45
	v_and_b32_e32 v45, 0xffff0000, v45
	v_pk_mul_f32 v[54:55], v[40:41], v[42:43]
	v_pk_mul_f32 v[42:43], v[38:39], v[48:49]
	v_pk_mul_f32 v[48:49], v[36:37], v[44:45]
	v_pk_mul_f32 v[44:45], v[34:35], v[52:53]
	v_cvt_pk_bf16_f32 v42, v42, v43
	v_cvt_pk_bf16_f32 v43, v54, v55
	s_nop 0
	v_cvt_pk_bf16_f32 v44, v44, v45
	v_cvt_pk_bf16_f32 v45, v48, v49
	global_store_dwordx4 v[46:47], v[42:45], off offset:256

; DEVI u32x4 pack8(f32x4 a, f32x4 b) { u32x4 o; o.x = cvt_pk_bf16(a[0], a[1]); o.y = cvt_pk_bf16(a[2], a[3]); o.z = cvt_pk_bf16(b[0], b[1]); o.w = cvt_pk_bf16(b[2], b[3]); return o; }
; DEVI float sigmoidf_(float x) { return 1.f / (1.f + __expf(-x)); }
; DEVI void gemm_epi(const GJob& jb, int row, int col, f32x4 v0, f32x4 v1) {
;     ...
;   else if (mode == 2) { f32x4 s0, s1; for (int i = 0; i < 4; ++i) { s0[i] = sigmoidf_(v0[i]); s1[i] = sigmoidf_(v1[i]); } *(u32x4*)((bf16_t*)jb.out + (size_t)row * jb.ldo + col) = pack8(s0, s1); }
.LBB0_627:
	s_and_b64 vcc, exec, s[12:13]
	s_cbranch_vccz .LBB0_630
	s_cmp_eq_u32 s71, 2
	s_mov_b64 s[8:9], -1
	s_cbranch_scc0 .LBB0_630
	v_mul_f32_e32 v0, 0xbfb8aa3b, v38
	v_exp_f32_e32 v0, v0
	s_mov_b64 s[8:9], 0
	v_add_f32_e32 v0, 1.0, v0
	v_div_scale_f32 v42, s[0:1], v0, v0, 1.0
	v_rcp_f32_e32 v43, v42
	s_nop 0
	v_fma_f32 v44, -v42, v43, 1.0
	v_fmac_f32_e32 v43, v44, v43
	v_div_scale_f32 v44, vcc, 1.0, v0, 1.0
	v_mul_f32_e32 v45, v44, v43
	v_fma_f32 v46, -v42, v45, v44
	v_fmac_f32_e32 v45, v46, v43
	v_fma_f32 v42, -v42, v45, v44
	v_div_fmas_f32 v42, v42, v43, v45
	v_div_fixup_f32 v0, v42, v0, 1.0
	v_mul_f32_e32 v42, 0xbfb8aa3b, v34
	v_exp_f32_e32 v42, v42
	s_nop 0
	v_add_f32_e32 v42, 1.0, v42
	v_div_scale_f32 v43, s[0:1], v42, v42, 1.0
	v_rcp_f32_e32 v44, v43
	s_nop 0
	v_fma_f32 v45, -v43, v44, 1.0
	v_fmac_f32_e32 v44, v45, v44
	v_div_scale_f32 v45, vcc, 1.0, v42, 1.0
	v_mul_f32_e32 v46, v45, v44
	v_fma_f32 v47, -v43, v46, v45
	v_fmac_f32_e32 v46, v47, v44
	v_fma_f32 v43, -v43, v46, v45
	v_div_fmas_f32 v43, v43, v44, v46
	v_div_fixup_f32 v44, v43, v42, 1.0
	v_mul_f32_e32 v42, 0xbfb8aa3b, v39
	v_exp_f32_e32 v42, v42
	s_nop 0
	v_add_f32_e32 v42, 1.0, v42
	v_div_scale_f32 v43, s[0:1], v42, v42, 1.0
	v_rcp_f32_e32 v45, v43
	s_nop 0
	v_fma_f32 v46, -v43, v45, 1.0
	v_fmac_f32_e32 v45, v46, v45
	v_div_scale_f32 v46, vcc, 1.0, v42, 1.0
	v_mul_f32_e32 v47, v46, v45
	v_fma_f32 v48, -v43, v47, v46
	v_fmac_f32_e32 v47, v48, v45
	v_fma_f32 v43, -v43, v47, v46
	v_div_fmas_f32 v43, v43, v45, v47
	v_div_fixup_f32 v42, v43, v42, 1.0
	v_mul_f32_e32 v43, 0xbfb8aa3b, v35
	v_exp_f32_e32 v43, v43
	v_cvt_pk_bf16_f32 v42, v0, v42
	s_nop 0
	v_add_f32_e32 v43, 1.0, v43
	v_div_scale_f32 v45, s[0:1], v43, v43, 1.0
	v_rcp_f32_e32 v46, v45
	s_nop 0
	v_fma_f32 v47, -v45, v46, 1.0
	v_fmac_f32_e32 v46, v47, v46
	v_div_scale_f32 v47, vcc, 1.0, v43, 1.0
	v_mul_f32_e32 v48, v47, v46
	v_fma_f32 v49, -v45, v48, v47
	v_fmac_f32_e32 v48, v49, v46
	v_fma_f32 v45, -v45, v48, v47
	v_div_fmas_f32 v45, v45, v46, v48
	v_div_fixup_f32 v45, v45, v43, 1.0
	v_mul_f32_e32 v43, 0xbfb8aa3b, v40
	v_exp_f32_e32 v43, v43
	v_cvt_pk_bf16_f32 v44, v44, v45
	s_nop 0
	v_add_f32_e32 v43, 1.0, v43
	v_div_scale_f32 v46, s[0:1], v43, v43, 1.0
	v_rcp_f32_e32 v47, v46
	s_nop 0
	v_fma_f32 v48, -v46, v47, 1.0
	v_fmac_f32_e32 v47, v48, v47
	v_div_scale_f32 v48, vcc, 1.0, v43, 1.0
	v_mul_f32_e32 v49, v48, v47
	v_fma_f32 v51, -v46, v49, v48
	v_fmac_f32_e32 v49, v51, v47
	v_fma_f32 v46, -v46, v49, v48
	v_div_fmas_f32 v46, v46, v47, v49
	v_div_fixup_f32 v43, v46, v43, 1.0
	v_mul_f32_e32 v46, 0xbfb8aa3b, v36
	v_exp_f32_e32 v46, v46
	s_nop 0
	v_add_f32_e32 v46, 1.0, v46
	v_div_scale_f32 v47, s[0:1], v46, v46, 1.0
	v_rcp_f32_e32 v48, v47
	s_nop 0
	v_fma_f32 v49, -v47, v48, 1.0
	v_fmac_f32_e32 v48, v49, v48
	v_div_scale_f32 v49, vcc, 1.0, v46, 1.0
	v_mul_f32_e32 v51, v49, v48
	v_fma_f32 v52, -v47, v51, v49
	v_fmac_f32_e32 v51, v52, v48
	v_fma_f32 v47, -v47, v51, v49
	v_div_fmas_f32 v47, v47, v48, v51
	v_div_fixup_f32 v46, v47, v46, 1.0
	v_mul_f32_e32 v47, 0xbfb8aa3b, v41
	v_exp_f32_e32 v47, v47
	s_nop 0
	v_add_f32_e32 v47, 1.0, v47
	v_div_scale_f32 v48, s[0:1], v47, v47, 1.0
	v_rcp_f32_e32 v49, v48
	s_nop 0
	v_fma_f32 v51, -v48, v49, 1.0
	v_fmac_f32_e32 v49, v51, v49
	v_div_scale_f32 v51, vcc, 1.0, v47, 1.0
	v_mul_f32_e32 v52, v51, v49
	v_fma_f32 v53, -v48, v52, v51
	v_fmac_f32_e32 v52, v53, v49
	v_fma_f32 v48, -v48, v52, v51
	v_div_fmas_f32 v48, v48, v49, v52
	v_div_fixup_f32 v47, v48, v47, 1.0
	v_mul_f32_e32 v48, 0xbfb8aa3b, v37
	v_exp_f32_e32 v48, v48
	v_cvt_pk_bf16_f32 v43, v43, v47
	s_nop 0
	v_add_f32_e32 v48, 1.0, v48
	v_div_scale_f32 v49, s[0:1], v48, v48, 1.0
	v_rcp_f32_e32 v51, v49
	s_nop 0
	v_fma_f32 v52, -v49, v51, 1.0
	v_fmac_f32_e32 v51, v52, v51
	v_div_scale_f32 v52, vcc, 1.0, v48, 1.0
	v_mul_f32_e32 v53, v52, v51
	v_fma_f32 v54, -v49, v53, v52
	v_fmac_f32_e32 v53, v54, v51
	v_fma_f32 v49, -v49, v53, v52
	v_div_fmas_f32 v49, v49, v51, v53
	v_div_fixup_f32 v48, v49, v48, 1.0
	v_cvt_pk_bf16_f32 v45, v46, v48
	v_mad_i64_i32 v[46:47], s[0:1], v50, s29, 0
	v_lshl_add_u64 v[46:47], v[46:47], 1, s[90:91]
	v_lshl_add_u64 v[46:47], v[130:131], 1, v[46:47]
	global_store_dwordx4 v[46:47], v[42:45], off offset:256

; DEVI void gemm_epi(const GJob& jb, int row, int col, f32x4 v0, f32x4 v1) {
;     ...
;   else if (mode == 1) { float* p = (float*)jb.out + (size_t)row * jb.ldo + col; *(f32x4*)p = v0; *(f32x4*)(p + 4) = v1; }
.LBB0_631:
	s_and_b64 vcc, exec, s[12:13]
	s_cbranch_vccz .LBB0_636
	s_cmp_gt_i32 s71, 0
	s_mov_b64 s[10:11], -1
	s_cbranch_scc0 .LBB0_634
	v_mad_i64_i32 v[42:43], s[0:1], v50, s29, 0
	v_lshl_add_u64 v[42:43], v[42:43], 2, s[90:91]
	v_lshl_add_u64 v[42:43], v[130:131], 2, v[42:43]
	global_store_dwordx4 v[42:43], v[38:41], off offset:512
	global_store_dwordx4 v[42:43], v[34:37], off offset:528
	s_mov_b64 s[10:11], 0

; DEVI float bf_lo(unsigned u) { return __uint_as_float(u << 16); }
; DEVI float bf_hi(unsigned u) { return __uint_as_float(u & 0xffff0000u); }
; DEVI float sigmoidf_(float x) { return 1.f / (1.f + __expf(-x)); }
; DEVI u32x4 pack8(f32x4 a, f32x4 b) { u32x4 o; o.x = cvt_pk_bf16(a[0], a[1]); o.y = cvt_pk_bf16(a[2], a[3]); o.z = cvt_pk_bf16(b[0], b[1]); o.w = cvt_pk_bf16(b[2], b[3]); return o; }
; DEVI void gemm_epi(const GJob& jb, int row, int col, f32x4 v0, f32x4 v1) {
;     ...
;   if (mode == 0) { *(u32x4*)((bf16_t*)jb.out + (size_t)row * jb.ldo + col) = pack8(v0, v1); }
;   else if (mode == 1) { float* p = (float*)jb.out + (size_t)row * jb.ldo + col; *(f32x4*)p = v0; *(f32x4*)(p + 4) = v1; }
;   else if (mode == 2) { f32x4 s0, s1; for (int i = 0; i < 4; ++i) { s0[i] = sigmoidf_(v0[i]); s1[i] = sigmoidf_(v1[i]); } *(u32x4*)((bf16_t*)jb.out + (size_t)row * jb.ldo + col) = pack8(s0, s1); }
;   else if (mode == 7) {
;     const u32x4 g = *(const u32x4*)((const bf16_t*)jb.aux + (size_t)row * NGATE + 2 * 2048 + col);
;     const f32x4 g0 = {bf_lo(g.x), bf_hi(g.x), bf_lo(g.y), bf_hi(g.y)}, g1 = {bf_lo(g.z), bf_hi(g.z), bf_lo(g.w), bf_hi(g.w)};
;     *(u32x4*)((bf16_t*)jb.out + (size_t)row * 2048 + col) = pack8(g0 * v0, g1 * v1);
;   } else {
;     const float* xp = (const float*)jb.aux + (size_t)row * jb.ldo + col; const float* gp = (const float*)jb.aux2 + col;
;     float* op = (float*)jb.out + (size_t)row * jb.ldo + col;
;     const f32x4 x0 = *(const f32x4*)xp, x1 = *(const f32x4*)(xp + 4), t0 = *(const f32x4*)gp, t1 = *(const f32x4*)(gp + 4);
;     *(f32x4*)op = x0 + t0 * v0; *(f32x4*)(op + 4) = x1 + t1 * v1;
.LBB0_636:
	s_and_b64 vcc, exec, s[8:9]
	s_cbranch_vccz .LBB0_638
	v_mad_i64_i32 v[42:43], s[0:1], v50, s29, 0
	v_lshlrev_b64 v[42:43], 2, v[42:43]
	v_lshl_add_u64 v[44:45], s[94:95], 0, v[42:43]
	v_lshlrev_b64 v[46:47], 2, v[130:131]
	v_lshl_add_u64 v[48:49], v[44:45], 0, v[46:47]
	v_lshl_add_u64 v[56:57], s[88:89], 0, v[46:47]
	v_lshl_add_u64 v[42:43], s[90:91], 0, v[42:43]
	v_lshl_add_u64 v[60:61], v[42:43], 0, v[46:47]
	global_load_dwordx4 v[42:45], v[48:49], off offset:512
	s_nop 0
	global_load_dwordx4 v[46:49], v[48:49], off offset:528
	s_nop 0
	global_load_dwordx4 v[52:55], v[56:57], off offset:512
	s_nop 0
	global_load_dwordx4 v[56:59], v[56:57], off offset:528
	s_mov_b64 s[10:11], 0
	s_waitcnt vmcnt(0) lgkmcnt(0)
	v_pk_fma_f32 v[44:45], v[40:41], v[54:55], v[44:45]
	v_pk_fma_f32 v[42:43], v[38:39], v[52:53], v[42:43]
	global_store_dwordx4 v[60:61], v[42:45], off offset:512
	s_nop 1
	v_pk_fma_f32 v[44:45], v[36:37], v[58:59], v[48:49]
	v_pk_fma_f32 v[42:43], v[34:35], v[56:57], v[46:47]
	global_store_dwordx4 v[60:61], v[42:45], off offset:528
.LBB0_638:
	s_andn2_b64 vcc, exec, s[10:11]
	s_cbranch_vccnz .LBB0_640
	v_cvt_pk_bf16_f32 v38, v38, v39
	v_cvt_pk_bf16_f32 v39, v40, v41
	v_cvt_pk_bf16_f32 v40, v34, v35
	v_mad_i64_i32 v[34:35], s[0:1], v50, s29, 0
	v_lshl_add_u64 v[34:35], v[34:35], 1, s[90:91]
	v_lshl_add_u64 v[34:35], v[130:131], 1, v[34:35]
	v_cvt_pk_bf16_f32 v41, v36, v37
	global_store_dwordx4 v[34:35], v[38:41], off offset:256
.LBB0_640:
	v_add_u32_e32 v34, 0xa0, v132
	v_ashrrev_i32_e32 v35, 31, v34
	v_mad_i64_i32 v[38:39], s[0:1], v34, s33, 0
	v_lshlrev_b64 v[36:37], 12, v[34:35]
	s_mov_b64 s[12:13], -1
	s_mov_b64 s[10:11], 0
	s_cmp_lt_i32 s71, 2
	s_mov_b64 s[8:9], 0
	s_cbranch_scc1 .LBB0_649
	s_cmp_gt_i32 s71, 6
	s_cbranch_scc0 .LBB0_645
	s_cmp_eq_u32 s71, 7
	s_mov_b64 s[8:9], -1
	s_cbranch_scc0 .LBB0_644
	v_lshl_add_u64 v[40:41], s[94:95], 0, v[38:39]
	v_lshlrev_b64 v[44:45], 1, v[130:131]
	v_lshl_add_u64 v[40:41], v[40:41], 0, v[44:45]
	v_add_co_u32_e32 v40, vcc, 0x2000, v40
	v_lshl_add_u64 v[46:47], s[90:91], 0, v[36:37]
	s_nop 0
	v_addc_co_u32_e32 v41, vcc, 0, v41, vcc
	global_load_dwordx4 v[40:43], v[40:41], off
	v_lshl_add_u64 v[44:45], v[46:47], 0, v[44:45]
	s_mov_b64 s[8:9], 0
	s_waitcnt vmcnt(0) lgkmcnt(0)
	v_lshlrev_b32_e32 v46, 16, v40
	v_and_b32_e32 v47, 0xffff0000, v40
	v_lshlrev_b32_e32 v40, 16, v41
	v_and_b32_e32 v41, 0xffff0000, v41
	v_lshlrev_b32_e32 v48, 16, v42
	v_and_b32_e32 v49, 0xffff0000, v42
	v_lshlrev_b32_e32 v42, 16, v43
	v_and_b32_e32 v43, 0xffff0000, v43
	v_pk_mul_f32 v[50:51], v[32:33], v[40:41]
	v_pk_mul_f32 v[40:41], v[30:31], v[46:47]
	v_pk_mul_f32 v[46:47], v[28:29], v[42:43]
	v_pk_mul_f32 v[42:43], v[26:27], v[48:49]
	v_cvt_pk_bf16_f32 v40, v40, v41
	v_cvt_pk_bf16_f32 v41, v50, v51
	s_nop 0
	v_cvt_pk_bf16_f32 v42, v42, v43
	v_cvt_pk_bf16_f32 v43, v46, v47
	global_store_dwordx4 v[44:45], v[40:43], off

; DEVI u32x4 pack8(f32x4 a, f32x4 b) { u32x4 o; o.x = cvt_pk_bf16(a[0], a[1]); o.y = cvt_pk_bf16(a[2], a[3]); o.z = cvt_pk_bf16(b[0], b[1]); o.w = cvt_pk_bf16(b[2], b[3]); return o; }
; DEVI float sigmoidf_(float x) { return 1.f / (1.f + __expf(-x)); }
; DEVI void gemm_epi(const GJob& jb, int row, int col, f32x4 v0, f32x4 v1) {
;     ...
;   else if (mode == 2) { f32x4 s0, s1; for (int i = 0; i < 4; ++i) { s0[i] = sigmoidf_(v0[i]); s1[i] = sigmoidf_(v1[i]); } *(u32x4*)((bf16_t*)jb.out + (size_t)row * jb.ldo + col) = pack8(s0, s1); }
.LBB0_645:
	s_and_b64 vcc, exec, s[12:13]
	s_cbranch_vccz .LBB0_648
	s_cmp_eq_u32 s71, 2
	s_mov_b64 s[8:9], -1
	s_cbranch_scc0 .LBB0_648
	v_mul_f32_e32 v0, 0xbfb8aa3b, v30
	v_exp_f32_e32 v0, v0
	s_mov_b64 s[8:9], 0
	v_add_f32_e32 v0, 1.0, v0
	v_div_scale_f32 v35, s[0:1], v0, v0, 1.0
	v_rcp_f32_e32 v40, v35
	s_nop 0
	v_fma_f32 v41, -v35, v40, 1.0
	v_fmac_f32_e32 v40, v41, v40
	v_div_scale_f32 v41, vcc, 1.0, v0, 1.0
	v_mul_f32_e32 v42, v41, v40
	v_fma_f32 v43, -v35, v42, v41
	v_fmac_f32_e32 v42, v43, v40
	v_fma_f32 v35, -v35, v42, v41
	v_div_fmas_f32 v35, v35, v40, v42
	v_div_fixup_f32 v0, v35, v0, 1.0
	v_mul_f32_e32 v35, 0xbfb8aa3b, v26
	v_exp_f32_e32 v35, v35
	s_nop 0
	v_add_f32_e32 v35, 1.0, v35
	v_div_scale_f32 v40, s[0:1], v35, v35, 1.0
	v_rcp_f32_e32 v41, v40
	s_nop 0
	v_fma_f32 v42, -v40, v41, 1.0
	v_fmac_f32_e32 v41, v42, v41
	v_div_scale_f32 v42, vcc, 1.0, v35, 1.0
	v_mul_f32_e32 v43, v42, v41
	v_fma_f32 v44, -v40, v43, v42
	v_fmac_f32_e32 v43, v44, v41
	v_fma_f32 v40, -v40, v43, v42
	v_div_fmas_f32 v40, v40, v41, v43
	v_div_fixup_f32 v35, v40, v35, 1.0
	v_mul_f32_e32 v40, 0xbfb8aa3b, v31
	v_exp_f32_e32 v40, v40
	s_nop 0
	v_add_f32_e32 v40, 1.0, v40
	v_div_scale_f32 v41, s[0:1], v40, v40, 1.0
	v_rcp_f32_e32 v42, v41
	s_nop 0
	v_fma_f32 v43, -v41, v42, 1.0
	v_fmac_f32_e32 v42, v43, v42
	v_div_scale_f32 v43, vcc, 1.0, v40, 1.0
	v_mul_f32_e32 v44, v43, v42
	v_fma_f32 v45, -v41, v44, v43
	v_fmac_f32_e32 v44, v45, v42
	v_fma_f32 v41, -v41, v44, v43
	v_div_fmas_f32 v41, v41, v42, v44
	v_div_fixup_f32 v40, v41, v40, 1.0
	v_mul_f32_e32 v41, 0xbfb8aa3b, v27
	v_exp_f32_e32 v41, v41
	v_cvt_pk_bf16_f32 v40, v0, v40
	s_nop 0
	v_add_f32_e32 v41, 1.0, v41
	v_div_scale_f32 v42, s[0:1], v41, v41, 1.0
	v_rcp_f32_e32 v43, v42
	s_nop 0
	v_fma_f32 v44, -v42, v43, 1.0
	v_fmac_f32_e32 v43, v44, v43
	v_div_scale_f32 v44, vcc, 1.0, v41, 1.0
	v_mul_f32_e32 v45, v44, v43
	v_fma_f32 v46, -v42, v45, v44
	v_fmac_f32_e32 v45, v46, v43
	v_fma_f32 v42, -v42, v45, v44
	v_div_fmas_f32 v42, v42, v43, v45
	v_div_fixup_f32 v42, v42, v41, 1.0
	v_mul_f32_e32 v41, 0xbfb8aa3b, v32
	v_exp_f32_e32 v41, v41
	v_cvt_pk_bf16_f32 v42, v35, v42
	s_nop 0
	v_add_f32_e32 v41, 1.0, v41
	v_div_scale_f32 v43, s[0:1], v41, v41, 1.0
	v_rcp_f32_e32 v44, v43
	s_nop 0
	v_fma_f32 v45, -v43, v44, 1.0
	v_fmac_f32_e32 v44, v45, v44
	v_div_scale_f32 v45, vcc, 1.0, v41, 1.0
	v_mul_f32_e32 v46, v45, v44
	v_fma_f32 v47, -v43, v46, v45
	v_fmac_f32_e32 v46, v47, v44
	v_fma_f32 v43, -v43, v46, v45
	v_div_fmas_f32 v43, v43, v44, v46
	v_div_fixup_f32 v41, v43, v41, 1.0
	v_mul_f32_e32 v43, 0xbfb8aa3b, v28
	v_exp_f32_e32 v43, v43
	s_nop 0
	v_add_f32_e32 v43, 1.0, v43
	v_div_scale_f32 v44, s[0:1], v43, v43, 1.0
	v_rcp_f32_e32 v45, v44
	s_nop 0
	v_fma_f32 v46, -v44, v45, 1.0
	v_fmac_f32_e32 v45, v46, v45
	v_div_scale_f32 v46, vcc, 1.0, v43, 1.0
	v_mul_f32_e32 v47, v46, v45
	v_fma_f32 v48, -v44, v47, v46
	v_fmac_f32_e32 v47, v48, v45
	v_fma_f32 v44, -v44, v47, v46
	v_div_fmas_f32 v44, v44, v45, v47
	v_div_fixup_f32 v43, v44, v43, 1.0
	v_mul_f32_e32 v44, 0xbfb8aa3b, v33
	v_exp_f32_e32 v44, v44
	s_nop 0
	v_add_f32_e32 v44, 1.0, v44
	v_div_scale_f32 v45, s[0:1], v44, v44, 1.0
	v_rcp_f32_e32 v46, v45
	s_nop 0
	v_fma_f32 v47, -v45, v46, 1.0
	v_fmac_f32_e32 v46, v47, v46
	v_div_scale_f32 v47, vcc, 1.0, v44, 1.0
	v_mul_f32_e32 v48, v47, v46
	v_fma_f32 v49, -v45, v48, v47
	v_fmac_f32_e32 v48, v49, v46
	v_fma_f32 v45, -v45, v48, v47
	v_div_fmas_f32 v45, v45, v46, v48
	v_div_fixup_f32 v44, v45, v44, 1.0
	v_mul_f32_e32 v45, 0xbfb8aa3b, v29
	v_exp_f32_e32 v45, v45
	v_cvt_pk_bf16_f32 v41, v41, v44
	s_nop 0
	v_add_f32_e32 v45, 1.0, v45
	v_div_scale_f32 v46, s[0:1], v45, v45, 1.0
	v_rcp_f32_e32 v47, v46
	s_nop 0
	v_fma_f32 v48, -v46, v47, 1.0
	v_fmac_f32_e32 v47, v48, v47
	v_div_scale_f32 v48, vcc, 1.0, v45, 1.0
	v_mul_f32_e32 v49, v48, v47
	v_fma_f32 v50, -v46, v49, v48
	v_fmac_f32_e32 v49, v50, v47
	v_fma_f32 v46, -v46, v49, v48
	v_div_fmas_f32 v46, v46, v47, v49
	v_div_fixup_f32 v45, v46, v45, 1.0
	v_cvt_pk_bf16_f32 v43, v43, v45
	v_mad_i64_i32 v[44:45], s[0:1], v34, s29, 0
	v_lshl_add_u64 v[44:45], v[44:45], 1, s[90:91]
	v_lshl_add_u64 v[44:45], v[130:131], 1, v[44:45]
	global_store_dwordx4 v[44:45], v[40:43], off

; DEVI void gemm_epi(const GJob& jb, int row, int col, f32x4 v0, f32x4 v1) {
;     ...
;   else if (mode == 1) { float* p = (float*)jb.out + (size_t)row * jb.ldo + col; *(f32x4*)p = v0; *(f32x4*)(p + 4) = v1; }
.LBB0_649:
	s_and_b64 vcc, exec, s[12:13]
	s_cbranch_vccz .LBB0_654
	s_cmp_gt_i32 s71, 0
	s_mov_b64 s[10:11], -1
	s_cbranch_scc0 .LBB0_652
	v_mad_i64_i32 v[40:41], s[0:1], v34, s29, 0
	v_lshl_add_u64 v[40:41], v[40:41], 2, s[90:91]
	v_lshl_add_u64 v[40:41], v[130:131], 2, v[40:41]
	global_store_dwordx4 v[40:41], v[30:33], off
	global_store_dwordx4 v[40:41], v[26:29], off offset:16
	s_mov_b64 s[10:11], 0

; DEVI float bf_lo(unsigned u) { return __uint_as_float(u << 16); }
; DEVI float bf_hi(unsigned u) { return __uint_as_float(u & 0xffff0000u); }
; DEVI float sigmoidf_(float x) { return 1.f / (1.f + __expf(-x)); }
; DEVI u32x4 pack8(f32x4 a, f32x4 b) { u32x4 o; o.x = cvt_pk_bf16(a[0], a[1]); o.y = cvt_pk_bf16(a[2], a[3]); o.z = cvt_pk_bf16(b[0], b[1]); o.w = cvt_pk_bf16(b[2], b[3]); return o; }
; DEVI void gemm_epi(const GJob& jb, int row, int col, f32x4 v0, f32x4 v1) {
;     ...
;   if (mode == 0) { *(u32x4*)((bf16_t*)jb.out + (size_t)row * jb.ldo + col) = pack8(v0, v1); }
;   else if (mode == 1) { float* p = (float*)jb.out + (size_t)row * jb.ldo + col; *(f32x4*)p = v0; *(f32x4*)(p + 4) = v1; }
;   else if (mode == 2) { f32x4 s0, s1; for (int i = 0; i < 4; ++i) { s0[i] = sigmoidf_(v0[i]); s1[i] = sigmoidf_(v1[i]); } *(u32x4*)((bf16_t*)jb.out + (size_t)row * jb.ldo + col) = pack8(s0, s1); }
;   else if (mode == 7) {
;     const u32x4 g = *(const u32x4*)((const bf16_t*)jb.aux + (size_t)row * NGATE + 2 * 2048 + col);
;     const f32x4 g0 = {bf_lo(g.x), bf_hi(g.x), bf_lo(g.y), bf_hi(g.y)}, g1 = {bf_lo(g.z), bf_hi(g.z), bf_lo(g.w), bf_hi(g.w)};
;     *(u32x4*)((bf16_t*)jb.out + (size_t)row * 2048 + col) = pack8(g0 * v0, g1 * v1);
;   } else {
;     const float* xp = (const float*)jb.aux + (size_t)row * jb.ldo + col; const float* gp = (const float*)jb.aux2 + col;
;     float* op = (float*)jb.out + (size_t)row * jb.ldo + col;
;     const f32x4 x0 = *(const f32x4*)xp, x1 = *(const f32x4*)(xp + 4), t0 = *(const f32x4*)gp, t1 = *(const f32x4*)(gp + 4);
;     *(f32x4*)op = x0 + t0 * v0; *(f32x4*)(op + 4) = x1 + t1 * v1;
.LBB0_654:
	s_and_b64 vcc, exec, s[8:9]
	s_cbranch_vccz .LBB0_656
	v_mad_i64_i32 v[40:41], s[0:1], v34, s29, 0
	v_lshlrev_b64 v[40:41], 2, v[40:41]
	v_lshl_add_u64 v[42:43], s[94:95], 0, v[40:41]
	v_lshlrev_b64 v[44:45], 2, v[130:131]
	v_lshl_add_u64 v[46:47], v[42:43], 0, v[44:45]
	v_lshl_add_u64 v[52:53], s[88:89], 0, v[44:45]
	v_lshl_add_u64 v[40:41], s[90:91], 0, v[40:41]
	v_lshl_add_u64 v[56:57], v[40:41], 0, v[44:45]
	global_load_dwordx4 v[40:43], v[46:47], off
	s_nop 0
	global_load_dwordx4 v[44:47], v[46:47], off offset:16
	s_nop 0
	global_load_dwordx4 v[48:51], v[52:53], off
	s_nop 0
	global_load_dwordx4 v[52:55], v[52:53], off offset:16
	s_mov_b64 s[10:11], 0
	s_waitcnt vmcnt(0) lgkmcnt(0)
	v_pk_fma_f32 v[42:43], v[32:33], v[50:51], v[42:43]
	v_pk_fma_f32 v[40:41], v[30:31], v[48:49], v[40:41]
	global_store_dwordx4 v[56:57], v[40:43], off
	s_nop 1
	v_pk_fma_f32 v[42:43], v[28:29], v[54:55], v[46:47]
	v_pk_fma_f32 v[40:41], v[26:27], v[52:53], v[44:45]
	global_store_dwordx4 v[56:57], v[40:43], off offset:16
.LBB0_656:
	s_andn2_b64 vcc, exec, s[10:11]
	s_cbranch_vccnz .LBB0_658
	v_cvt_pk_bf16_f32 v30, v30, v31
	v_cvt_pk_bf16_f32 v31, v32, v33
	v_cvt_pk_bf16_f32 v32, v26, v27
	v_mad_i64_i32 v[26:27], s[0:1], v34, s29, 0
	v_lshl_add_u64 v[26:27], v[26:27], 1, s[90:91]
	v_lshl_add_u64 v[26:27], v[130:131], 1, v[26:27]
	v_cvt_pk_bf16_f32 v33, v28, v29
	global_store_dwordx4 v[26:27], v[30:33], off
.LBB0_658:
	s_mov_b64 s[12:13], -1
	s_mov_b64 s[10:11], 0
	s_cmp_lt_i32 s71, 2
	s_mov_b64 s[8:9], 0
	s_cbranch_scc1 .LBB0_667
	s_cmp_gt_i32 s71, 6
	s_cbranch_scc0 .LBB0_663
	s_cmp_eq_u32 s71, 7
	s_mov_b64 s[8:9], -1
	s_cbranch_scc0 .LBB0_662
	v_lshl_add_u64 v[26:27], s[94:95], 0, v[38:39]
	v_ashrrev_i32_e32 v123, 31, v122
	v_lshl_add_u64 v[26:27], v[122:123], 1, v[26:27]
	v_add_co_u32_e32 v26, vcc, 0x2000, v26
	v_lshl_add_u64 v[30:31], s[90:91], 0, v[36:37]
	s_nop 0
	v_addc_co_u32_e32 v27, vcc, 0, v27, vcc
	global_load_dwordx4 v[26:29], v[26:27], off
	v_lshl_add_u64 v[30:31], v[130:131], 1, v[30:31]
	s_mov_b64 s[8:9], 0
	s_waitcnt vmcnt(0) lgkmcnt(0)
	v_lshlrev_b32_e32 v32, 16, v26
	v_and_b32_e32 v33, 0xffff0000, v26
	v_lshlrev_b32_e32 v26, 16, v27
	v_and_b32_e32 v27, 0xffff0000, v27
	v_lshlrev_b32_e32 v36, 16, v28
	v_and_b32_e32 v37, 0xffff0000, v28
	v_lshlrev_b32_e32 v28, 16, v29
	v_and_b32_e32 v29, 0xffff0000, v29
	v_pk_mul_f32 v[38:39], v[24:25], v[26:27]
	v_pk_mul_f32 v[26:27], v[22:23], v[32:33]
	v_pk_mul_f32 v[32:33], v[20:21], v[28:29]
	v_pk_mul_f32 v[28:29], v[18:19], v[36:37]
	v_cvt_pk_bf16_f32 v26, v26, v27
	v_cvt_pk_bf16_f32 v27, v38, v39
	s_nop 0
	v_cvt_pk_bf16_f32 v28, v28, v29
	v_cvt_pk_bf16_f32 v29, v32, v33
	global_store_dwordx4 v[30:31], v[26:29], off offset:256

; DEVI u32x4 pack8(f32x4 a, f32x4 b) { u32x4 o; o.x = cvt_pk_bf16(a[0], a[1]); o.y = cvt_pk_bf16(a[2], a[3]); o.z = cvt_pk_bf16(b[0], b[1]); o.w = cvt_pk_bf16(b[2], b[3]); return o; }
; DEVI float sigmoidf_(float x) { return 1.f / (1.f + __expf(-x)); }
; DEVI void gemm_epi(const GJob& jb, int row, int col, f32x4 v0, f32x4 v1) {
;     ...
;   else if (mode == 2) { f32x4 s0, s1; for (int i = 0; i < 4; ++i) { s0[i] = sigmoidf_(v0[i]); s1[i] = sigmoidf_(v1[i]); } *(u32x4*)((bf16_t*)jb.out + (size_t)row * jb.ldo + col) = pack8(s0, s1); }
.LBB0_663:
	s_and_b64 vcc, exec, s[12:13]
	s_cbranch_vccz .LBB0_666
	s_cmp_eq_u32 s71, 2
	s_mov_b64 s[8:9], -1
	s_cbranch_scc0 .LBB0_666
	v_mul_f32_e32 v0, 0xbfb8aa3b, v22
	v_exp_f32_e32 v0, v0
	s_mov_b64 s[8:9], 0
	v_add_f32_e32 v0, 1.0, v0
	v_div_scale_f32 v26, s[0:1], v0, v0, 1.0
	v_rcp_f32_e32 v27, v26
	s_nop 0
	v_fma_f32 v28, -v26, v27, 1.0
	v_fmac_f32_e32 v27, v28, v27
	v_div_scale_f32 v28, vcc, 1.0, v0, 1.0
	v_mul_f32_e32 v29, v28, v27
	v_fma_f32 v30, -v26, v29, v28
	v_fmac_f32_e32 v29, v30, v27
	v_fma_f32 v26, -v26, v29, v28
	v_div_fmas_f32 v26, v26, v27, v29
	v_div_fixup_f32 v0, v26, v0, 1.0
	v_mul_f32_e32 v26, 0xbfb8aa3b, v18
	v_exp_f32_e32 v26, v26
	s_nop 0
	v_add_f32_e32 v26, 1.0, v26
	v_div_scale_f32 v27, s[0:1], v26, v26, 1.0
	v_rcp_f32_e32 v28, v27
	s_nop 0
	v_fma_f32 v29, -v27, v28, 1.0
	v_fmac_f32_e32 v28, v29, v28
	v_div_scale_f32 v29, vcc, 1.0, v26, 1.0
	v_mul_f32_e32 v30, v29, v28
	v_fma_f32 v31, -v27, v30, v29
	v_fmac_f32_e32 v30, v31, v28
	v_fma_f32 v27, -v27, v30, v29
	v_div_fmas_f32 v27, v27, v28, v30
	v_div_fixup_f32 v28, v27, v26, 1.0
	v_mul_f32_e32 v26, 0xbfb8aa3b, v23
	v_exp_f32_e32 v26, v26
	s_nop 0
	v_add_f32_e32 v26, 1.0, v26
	v_div_scale_f32 v27, s[0:1], v26, v26, 1.0
	v_rcp_f32_e32 v29, v27
	s_nop 0
	v_fma_f32 v30, -v27, v29, 1.0
	v_fmac_f32_e32 v29, v30, v29
	v_div_scale_f32 v30, vcc, 1.0, v26, 1.0
	v_mul_f32_e32 v31, v30, v29
	v_fma_f32 v32, -v27, v31, v30
	v_fmac_f32_e32 v31, v32, v29
	v_fma_f32 v27, -v27, v31, v30
	v_div_fmas_f32 v27, v27, v29, v31
	v_div_fixup_f32 v26, v27, v26, 1.0
	v_mul_f32_e32 v27, 0xbfb8aa3b, v19
	v_exp_f32_e32 v27, v27
	v_cvt_pk_bf16_f32 v26, v0, v26
	s_nop 0
	v_add_f32_e32 v27, 1.0, v27
	v_div_scale_f32 v29, s[0:1], v27, v27, 1.0
	v_rcp_f32_e32 v30, v29
	s_nop 0
	v_fma_f32 v31, -v29, v30, 1.0
	v_fmac_f32_e32 v30, v31, v30
	v_div_scale_f32 v31, vcc, 1.0, v27, 1.0
	v_mul_f32_e32 v32, v31, v30
	v_fma_f32 v33, -v29, v32, v31
	v_fmac_f32_e32 v32, v33, v30
	v_fma_f32 v29, -v29, v32, v31
	v_div_fmas_f32 v29, v29, v30, v32
	v_div_fixup_f32 v29, v29, v27, 1.0
	v_mul_f32_e32 v27, 0xbfb8aa3b, v24
	v_exp_f32_e32 v27, v27
	v_cvt_pk_bf16_f32 v28, v28, v29
	s_nop 0
	v_add_f32_e32 v27, 1.0, v27
	v_div_scale_f32 v30, s[0:1], v27, v27, 1.0
	v_rcp_f32_e32 v31, v30
	s_nop 0
	v_fma_f32 v32, -v30, v31, 1.0
	v_fmac_f32_e32 v31, v32, v31
	v_div_scale_f32 v32, vcc, 1.0, v27, 1.0
	v_mul_f32_e32 v33, v32, v31
	v_fma_f32 v35, -v30, v33, v32
	v_fmac_f32_e32 v33, v35, v31
	v_fma_f32 v30, -v30, v33, v32
	v_div_fmas_f32 v30, v30, v31, v33
	v_div_fixup_f32 v27, v30, v27, 1.0
	v_mul_f32_e32 v30, 0xbfb8aa3b, v20
	v_exp_f32_e32 v30, v30
	s_nop 0
	v_add_f32_e32 v30, 1.0, v30
	v_div_scale_f32 v31, s[0:1], v30, v30, 1.0
	v_rcp_f32_e32 v32, v31
	s_nop 0
	v_fma_f32 v33, -v31, v32, 1.0
	v_fmac_f32_e32 v32, v33, v32
	v_div_scale_f32 v33, vcc, 1.0, v30, 1.0
	v_mul_f32_e32 v35, v33, v32
	v_fma_f32 v36, -v31, v35, v33
	v_fmac_f32_e32 v35, v36, v32
	v_fma_f32 v31, -v31, v35, v33
	v_div_fmas_f32 v31, v31, v32, v35
	v_div_fixup_f32 v30, v31, v30, 1.0
	v_mul_f32_e32 v31, 0xbfb8aa3b, v25
	v_exp_f32_e32 v31, v31
	s_nop 0
	v_add_f32_e32 v31, 1.0, v31
	v_div_scale_f32 v32, s[0:1], v31, v31, 1.0
	v_rcp_f32_e32 v33, v32
	s_nop 0
	v_fma_f32 v35, -v32, v33, 1.0
	v_fmac_f32_e32 v33, v35, v33
	v_div_scale_f32 v35, vcc, 1.0, v31, 1.0
	v_mul_f32_e32 v36, v35, v33
	v_fma_f32 v37, -v32, v36, v35
	v_fmac_f32_e32 v36, v37, v33
	v_fma_f32 v32, -v32, v36, v35
	v_div_fmas_f32 v32, v32, v33, v36
	v_div_fixup_f32 v31, v32, v31, 1.0
	v_mul_f32_e32 v32, 0xbfb8aa3b, v21
	v_exp_f32_e32 v32, v32
	v_cvt_pk_bf16_f32 v27, v27, v31
	s_nop 0
	v_add_f32_e32 v32, 1.0, v32
	v_div_scale_f32 v33, s[0:1], v32, v32, 1.0
	v_rcp_f32_e32 v35, v33
	s_nop 0
	v_fma_f32 v36, -v33, v35, 1.0
	v_fmac_f32_e32 v35, v36, v35
	v_div_scale_f32 v36, vcc, 1.0, v32, 1.0
	v_mul_f32_e32 v37, v36, v35
	v_fma_f32 v38, -v33, v37, v36
	v_fmac_f32_e32 v37, v38, v35
	v_fma_f32 v33, -v33, v37, v36
	v_div_fmas_f32 v33, v33, v35, v37
	v_div_fixup_f32 v32, v33, v32, 1.0
	v_cvt_pk_bf16_f32 v29, v30, v32
	v_mad_i64_i32 v[30:31], s[0:1], v34, s29, 0
	v_lshl_add_u64 v[30:31], v[30:31], 1, s[90:91]
	v_lshl_add_u64 v[30:31], v[130:131], 1, v[30:31]
	global_store_dwordx4 v[30:31], v[26:29], off offset:256

; DEVI void gemm_epi(const GJob& jb, int row, int col, f32x4 v0, f32x4 v1) {
;     ...
;   else if (mode == 1) { float* p = (float*)jb.out + (size_t)row * jb.ldo + col; *(f32x4*)p = v0; *(f32x4*)(p + 4) = v1; }
.LBB0_667:
	s_and_b64 vcc, exec, s[12:13]
	s_cbranch_vccz .LBB0_672
	s_cmp_gt_i32 s71, 0
	s_mov_b64 s[10:11], -1
	s_cbranch_scc0 .LBB0_670
	v_mad_i64_i32 v[26:27], s[0:1], v34, s29, 0
	v_lshl_add_u64 v[26:27], v[26:27], 2, s[90:91]
	v_lshl_add_u64 v[26:27], v[130:131], 2, v[26:27]
	global_store_dwordx4 v[26:27], v[22:25], off offset:512
	global_store_dwordx4 v[26:27], v[18:21], off offset:528
	s_mov_b64 s[10:11], 0

; DEVI float bf_lo(unsigned u) { return __uint_as_float(u << 16); }
; DEVI float bf_hi(unsigned u) { return __uint_as_float(u & 0xffff0000u); }
; DEVI float sigmoidf_(float x) { return 1.f / (1.f + __expf(-x)); }
; DEVI u32x4 pack8(f32x4 a, f32x4 b) { u32x4 o; o.x = cvt_pk_bf16(a[0], a[1]); o.y = cvt_pk_bf16(a[2], a[3]); o.z = cvt_pk_bf16(b[0], b[1]); o.w = cvt_pk_bf16(b[2], b[3]); return o; }
; DEVI void gemm_epi(const GJob& jb, int row, int col, f32x4 v0, f32x4 v1) {
;     ...
;   if (mode == 0) { *(u32x4*)((bf16_t*)jb.out + (size_t)row * jb.ldo + col) = pack8(v0, v1); }
;   else if (mode == 1) { float* p = (float*)jb.out + (size_t)row * jb.ldo + col; *(f32x4*)p = v0; *(f32x4*)(p + 4) = v1; }
;   else if (mode == 2) { f32x4 s0, s1; for (int i = 0; i < 4; ++i) { s0[i] = sigmoidf_(v0[i]); s1[i] = sigmoidf_(v1[i]); } *(u32x4*)((bf16_t*)jb.out + (size_t)row * jb.ldo + col) = pack8(s0, s1); }
;   else if (mode == 7) {
;     const u32x4 g = *(const u32x4*)((const bf16_t*)jb.aux + (size_t)row * NGATE + 2 * 2048 + col);
;     const f32x4 g0 = {bf_lo(g.x), bf_hi(g.x), bf_lo(g.y), bf_hi(g.y)}, g1 = {bf_lo(g.z), bf_hi(g.z), bf_lo(g.w), bf_hi(g.w)};
;     *(u32x4*)((bf16_t*)jb.out + (size_t)row * 2048 + col) = pack8(g0 * v0, g1 * v1);
;   } else {
;     const float* xp = (const float*)jb.aux + (size_t)row * jb.ldo + col; const float* gp = (const float*)jb.aux2 + col;
;     float* op = (float*)jb.out + (size_t)row * jb.ldo + col;
;     const f32x4 x0 = *(const f32x4*)xp, x1 = *(const f32x4*)(xp + 4), t0 = *(const f32x4*)gp, t1 = *(const f32x4*)(gp + 4);
;     *(f32x4*)op = x0 + t0 * v0; *(f32x4*)(op + 4) = x1 + t1 * v1;
.LBB0_672:
	s_and_b64 vcc, exec, s[8:9]
	s_cbranch_vccz .LBB0_674
	v_mad_i64_i32 v[26:27], s[0:1], v34, s29, 0
	v_lshlrev_b64 v[26:27], 2, v[26:27]
	v_lshl_add_u64 v[28:29], s[94:95], 0, v[26:27]
	v_lshlrev_b64 v[30:31], 2, v[130:131]
	v_lshl_add_u64 v[32:33], v[28:29], 0, v[30:31]
	v_lshl_add_u64 v[40:41], s[88:89], 0, v[30:31]
	v_lshl_add_u64 v[26:27], s[90:91], 0, v[26:27]
	v_lshl_add_u64 v[44:45], v[26:27], 0, v[30:31]
	global_load_dwordx4 v[26:29], v[32:33], off offset:512
	s_nop 0
	global_load_dwordx4 v[30:33], v[32:33], off offset:528
	s_nop 0
	global_load_dwordx4 v[36:39], v[40:41], off offset:512
	s_nop 0
	global_load_dwordx4 v[40:43], v[40:41], off offset:528
	s_mov_b64 s[10:11], 0
	s_waitcnt vmcnt(0) lgkmcnt(0)
	v_pk_fma_f32 v[28:29], v[24:25], v[38:39], v[28:29]
	v_pk_fma_f32 v[26:27], v[22:23], v[36:37], v[26:27]
	global_store_dwordx4 v[44:45], v[26:29], off offset:512
	s_nop 1
	v_pk_fma_f32 v[28:29], v[20:21], v[42:43], v[32:33]
	v_pk_fma_f32 v[26:27], v[18:19], v[40:41], v[30:31]
	global_store_dwordx4 v[44:45], v[26:29], off offset:528
.LBB0_674:
	s_andn2_b64 vcc, exec, s[10:11]
	s_cbranch_vccnz .LBB0_676
	v_cvt_pk_bf16_f32 v22, v22, v23
	v_cvt_pk_bf16_f32 v23, v24, v25
	v_cvt_pk_bf16_f32 v24, v18, v19
	v_mad_i64_i32 v[18:19], s[0:1], v34, s29, 0
	v_lshl_add_u64 v[18:19], v[18:19], 1, s[90:91]
	v_lshl_add_u64 v[18:19], v[130:131], 1, v[18:19]
	v_cvt_pk_bf16_f32 v25, v20, v21
	global_store_dwordx4 v[18:19], v[22:25], off offset:256
.LBB0_676:
	v_add_u32_e32 v18, 0xb0, v132
	v_ashrrev_i32_e32 v19, 31, v18
	v_mad_i64_i32 v[22:23], s[0:1], v18, s33, 0
	v_lshlrev_b64 v[20:21], 12, v[18:19]
	s_mov_b64 s[12:13], -1
	s_mov_b64 s[10:11], 0
	s_cmp_lt_i32 s71, 2
	s_mov_b64 s[8:9], 0
	s_cbranch_scc1 .LBB0_685
	s_cmp_gt_i32 s71, 6
	s_cbranch_scc0 .LBB0_681
	s_cmp_eq_u32 s71, 7
	s_mov_b64 s[8:9], -1
	s_cbranch_scc0 .LBB0_680
	v_lshl_add_u64 v[24:25], s[94:95], 0, v[22:23]
	v_lshlrev_b64 v[28:29], 1, v[130:131]
	v_lshl_add_u64 v[24:25], v[24:25], 0, v[28:29]
	v_add_co_u32_e32 v24, vcc, 0x2000, v24
	v_lshl_add_u64 v[30:31], s[90:91], 0, v[20:21]
	s_nop 0
	v_addc_co_u32_e32 v25, vcc, 0, v25, vcc
	global_load_dwordx4 v[24:27], v[24:25], off
	v_lshl_add_u64 v[28:29], v[30:31], 0, v[28:29]
	s_mov_b64 s[8:9], 0
	s_waitcnt vmcnt(0) lgkmcnt(0)
	v_lshlrev_b32_e32 v30, 16, v24
	v_and_b32_e32 v31, 0xffff0000, v24
	v_lshlrev_b32_e32 v24, 16, v25
	v_and_b32_e32 v25, 0xffff0000, v25
	v_lshlrev_b32_e32 v32, 16, v26
	v_and_b32_e32 v33, 0xffff0000, v26
	v_lshlrev_b32_e32 v26, 16, v27
	v_and_b32_e32 v27, 0xffff0000, v27
	v_pk_mul_f32 v[34:35], v[16:17], v[24:25]
	v_pk_mul_f32 v[24:25], v[14:15], v[30:31]
	v_pk_mul_f32 v[30:31], v[12:13], v[26:27]
	v_pk_mul_f32 v[26:27], v[10:11], v[32:33]
	v_cvt_pk_bf16_f32 v24, v24, v25
	v_cvt_pk_bf16_f32 v25, v34, v35
	s_nop 0
	v_cvt_pk_bf16_f32 v26, v26, v27
	v_cvt_pk_bf16_f32 v27, v30, v31
	global_store_dwordx4 v[28:29], v[24:27], off

; DEVI u32x4 pack8(f32x4 a, f32x4 b) { u32x4 o; o.x = cvt_pk_bf16(a[0], a[1]); o.y = cvt_pk_bf16(a[2], a[3]); o.z = cvt_pk_bf16(b[0], b[1]); o.w = cvt_pk_bf16(b[2], b[3]); return o; }
; DEVI float sigmoidf_(float x) { return 1.f / (1.f + __expf(-x)); }
; DEVI void gemm_epi(const GJob& jb, int row, int col, f32x4 v0, f32x4 v1) {
;     ...
;   else if (mode == 2) { f32x4 s0, s1; for (int i = 0; i < 4; ++i) { s0[i] = sigmoidf_(v0[i]); s1[i] = sigmoidf_(v1[i]); } *(u32x4*)((bf16_t*)jb.out + (size_t)row * jb.ldo + col) = pack8(s0, s1); }
.LBB0_681:
	s_and_b64 vcc, exec, s[12:13]
	s_cbranch_vccz .LBB0_684
	s_cmp_eq_u32 s71, 2
	s_mov_b64 s[8:9], -1
	s_cbranch_scc0 .LBB0_684
	v_mul_f32_e32 v0, 0xbfb8aa3b, v14
	v_exp_f32_e32 v0, v0
	s_mov_b64 s[8:9], 0
	v_add_f32_e32 v0, 1.0, v0
	v_div_scale_f32 v19, s[0:1], v0, v0, 1.0
	v_rcp_f32_e32 v24, v19
	s_nop 0
	v_fma_f32 v25, -v19, v24, 1.0
	v_fmac_f32_e32 v24, v25, v24
	v_div_scale_f32 v25, vcc, 1.0, v0, 1.0
	v_mul_f32_e32 v26, v25, v24
	v_fma_f32 v27, -v19, v26, v25
	v_fmac_f32_e32 v26, v27, v24
	v_fma_f32 v19, -v19, v26, v25
	v_div_fmas_f32 v19, v19, v24, v26
	v_div_fixup_f32 v0, v19, v0, 1.0
	v_mul_f32_e32 v19, 0xbfb8aa3b, v10
	v_exp_f32_e32 v19, v19
	s_nop 0
	v_add_f32_e32 v19, 1.0, v19
	v_div_scale_f32 v24, s[0:1], v19, v19, 1.0
	v_rcp_f32_e32 v25, v24
	s_nop 0
	v_fma_f32 v26, -v24, v25, 1.0
	v_fmac_f32_e32 v25, v26, v25
	v_div_scale_f32 v26, vcc, 1.0, v19, 1.0
	v_mul_f32_e32 v27, v26, v25
	v_fma_f32 v28, -v24, v27, v26
	v_fmac_f32_e32 v27, v28, v25
	v_fma_f32 v24, -v24, v27, v26
	v_div_fmas_f32 v24, v24, v25, v27
	v_div_fixup_f32 v19, v24, v19, 1.0
	v_mul_f32_e32 v24, 0xbfb8aa3b, v15
	v_exp_f32_e32 v24, v24
	s_nop 0
	v_add_f32_e32 v24, 1.0, v24
	v_div_scale_f32 v25, s[0:1], v24, v24, 1.0
	v_rcp_f32_e32 v26, v25
	s_nop 0
	v_fma_f32 v27, -v25, v26, 1.0
	v_fmac_f32_e32 v26, v27, v26
	v_div_scale_f32 v27, vcc, 1.0, v24, 1.0
	v_mul_f32_e32 v28, v27, v26
	v_fma_f32 v29, -v25, v28, v27
	v_fmac_f32_e32 v28, v29, v26
	v_fma_f32 v25, -v25, v28, v27
	v_div_fmas_f32 v25, v25, v26, v28
	v_div_fixup_f32 v24, v25, v24, 1.0
	v_mul_f32_e32 v25, 0xbfb8aa3b, v11
	v_exp_f32_e32 v25, v25
	v_cvt_pk_bf16_f32 v24, v0, v24
	s_nop 0
	v_add_f32_e32 v25, 1.0, v25
	v_div_scale_f32 v26, s[0:1], v25, v25, 1.0
	v_rcp_f32_e32 v27, v26
	s_nop 0
	v_fma_f32 v28, -v26, v27, 1.0
	v_fmac_f32_e32 v27, v28, v27
	v_div_scale_f32 v28, vcc, 1.0, v25, 1.0
	v_mul_f32_e32 v29, v28, v27
	v_fma_f32 v30, -v26, v29, v28
	v_fmac_f32_e32 v29, v30, v27
	v_fma_f32 v26, -v26, v29, v28
	v_div_fmas_f32 v26, v26, v27, v29
	v_div_fixup_f32 v26, v26, v25, 1.0
	v_mul_f32_e32 v25, 0xbfb8aa3b, v16
	v_exp_f32_e32 v25, v25
	v_cvt_pk_bf16_f32 v26, v19, v26
	s_nop 0
	v_add_f32_e32 v25, 1.0, v25
	v_div_scale_f32 v27, s[0:1], v25, v25, 1.0
	v_rcp_f32_e32 v28, v27
	s_nop 0
	v_fma_f32 v29, -v27, v28, 1.0
	v_fmac_f32_e32 v28, v29, v28
	v_div_scale_f32 v29, vcc, 1.0, v25, 1.0
	v_mul_f32_e32 v30, v29, v28
	v_fma_f32 v31, -v27, v30, v29
	v_fmac_f32_e32 v30, v31, v28
	v_fma_f32 v27, -v27, v30, v29
	v_div_fmas_f32 v27, v27, v28, v30
	v_div_fixup_f32 v25, v27, v25, 1.0
	v_mul_f32_e32 v27, 0xbfb8aa3b, v12
	v_exp_f32_e32 v27, v27
	s_nop 0
	v_add_f32_e32 v27, 1.0, v27
	v_div_scale_f32 v28, s[0:1], v27, v27, 1.0
	v_rcp_f32_e32 v29, v28
	s_nop 0
	v_fma_f32 v30, -v28, v29, 1.0
	v_fmac_f32_e32 v29, v30, v29
	v_div_scale_f32 v30, vcc, 1.0, v27, 1.0
	v_mul_f32_e32 v31, v30, v29
	v_fma_f32 v32, -v28, v31, v30
	v_fmac_f32_e32 v31, v32, v29
	v_fma_f32 v28, -v28, v31, v30
	v_div_fmas_f32 v28, v28, v29, v31
	v_div_fixup_f32 v27, v28, v27, 1.0
	v_mul_f32_e32 v28, 0xbfb8aa3b, v17
	v_exp_f32_e32 v28, v28
	s_nop 0
	v_add_f32_e32 v28, 1.0, v28
	v_div_scale_f32 v29, s[0:1], v28, v28, 1.0
	v_rcp_f32_e32 v30, v29
	s_nop 0
	v_fma_f32 v31, -v29, v30, 1.0
	v_fmac_f32_e32 v30, v31, v30
	v_div_scale_f32 v31, vcc, 1.0, v28, 1.0
	v_mul_f32_e32 v32, v31, v30
	v_fma_f32 v33, -v29, v32, v31
	v_fmac_f32_e32 v32, v33, v30
	v_fma_f32 v29, -v29, v32, v31
	v_div_fmas_f32 v29, v29, v30, v32
	v_div_fixup_f32 v28, v29, v28, 1.0
	v_mul_f32_e32 v29, 0xbfb8aa3b, v13
	v_exp_f32_e32 v29, v29
	v_cvt_pk_bf16_f32 v25, v25, v28
	s_nop 0
	v_add_f32_e32 v29, 1.0, v29
	v_div_scale_f32 v30, s[0:1], v29, v29, 1.0
	v_rcp_f32_e32 v31, v30
	s_nop 0
	v_fma_f32 v32, -v30, v31, 1.0
	v_fmac_f32_e32 v31, v32, v31
	v_div_scale_f32 v32, vcc, 1.0, v29, 1.0
	v_mul_f32_e32 v33, v32, v31
	v_fma_f32 v34, -v30, v33, v32
	v_fmac_f32_e32 v33, v34, v31
	v_fma_f32 v30, -v30, v33, v32
	v_div_fmas_f32 v30, v30, v31, v33
	v_div_fixup_f32 v29, v30, v29, 1.0
	v_cvt_pk_bf16_f32 v27, v27, v29
	v_mad_i64_i32 v[28:29], s[0:1], v18, s29, 0
	v_lshl_add_u64 v[28:29], v[28:29], 1, s[90:91]
	v_lshl_add_u64 v[28:29], v[130:131], 1, v[28:29]
	global_store_dwordx4 v[28:29], v[24:27], off

; DEVI void gemm_epi(const GJob& jb, int row, int col, f32x4 v0, f32x4 v1) {
;     ...
;   else if (mode == 1) { float* p = (float*)jb.out + (size_t)row * jb.ldo + col; *(f32x4*)p = v0; *(f32x4*)(p + 4) = v1; }
.LBB0_685:
	s_and_b64 vcc, exec, s[12:13]
	s_cbranch_vccz .LBB0_690
	s_cmp_gt_i32 s71, 0
	s_mov_b64 s[10:11], -1
	s_cbranch_scc0 .LBB0_688
	v_mad_i64_i32 v[24:25], s[0:1], v18, s29, 0
	v_lshl_add_u64 v[24:25], v[24:25], 2, s[90:91]
	v_lshl_add_u64 v[24:25], v[130:131], 2, v[24:25]
	global_store_dwordx4 v[24:25], v[14:17], off
	global_store_dwordx4 v[24:25], v[10:13], off offset:16
	s_mov_b64 s[10:11], 0

; DEVI float bf_lo(unsigned u) { return __uint_as_float(u << 16); }
; DEVI float bf_hi(unsigned u) { return __uint_as_float(u & 0xffff0000u); }
; DEVI float sigmoidf_(float x) { return 1.f / (1.f + __expf(-x)); }
; DEVI u32x4 pack8(f32x4 a, f32x4 b) { u32x4 o; o.x = cvt_pk_bf16(a[0], a[1]); o.y = cvt_pk_bf16(a[2], a[3]); o.z = cvt_pk_bf16(b[0], b[1]); o.w = cvt_pk_bf16(b[2], b[3]); return o; }
; DEVI void gemm_epi(const GJob& jb, int row, int col, f32x4 v0, f32x4 v1) {
;     ...
;   if (mode == 0) { *(u32x4*)((bf16_t*)jb.out + (size_t)row * jb.ldo + col) = pack8(v0, v1); }
;   else if (mode == 1) { float* p = (float*)jb.out + (size_t)row * jb.ldo + col; *(f32x4*)p = v0; *(f32x4*)(p + 4) = v1; }
;   else if (mode == 2) { f32x4 s0, s1; for (int i = 0; i < 4; ++i) { s0[i] = sigmoidf_(v0[i]); s1[i] = sigmoidf_(v1[i]); } *(u32x4*)((bf16_t*)jb.out + (size_t)row * jb.ldo + col) = pack8(s0, s1); }
;   else if (mode == 7) {
;     const u32x4 g = *(const u32x4*)((const bf16_t*)jb.aux + (size_t)row * NGATE + 2 * 2048 + col);
;     const f32x4 g0 = {bf_lo(g.x), bf_hi(g.x), bf_lo(g.y), bf_hi(g.y)}, g1 = {bf_lo(g.z), bf_hi(g.z), bf_lo(g.w), bf_hi(g.w)};
;     *(u32x4*)((bf16_t*)jb.out + (size_t)row * 2048 + col) = pack8(g0 * v0, g1 * v1);
;   } else {
;     const float* xp = (const float*)jb.aux + (size_t)row * jb.ldo + col; const float* gp = (const float*)jb.aux2 + col;
;     float* op = (float*)jb.out + (size_t)row * jb.ldo + col;
;     const f32x4 x0 = *(const f32x4*)xp, x1 = *(const f32x4*)(xp + 4), t0 = *(const f32x4*)gp, t1 = *(const f32x4*)(gp + 4);
;     *(f32x4*)op = x0 + t0 * v0; *(f32x4*)(op + 4) = x1 + t1 * v1;
.LBB0_690:
	s_and_b64 vcc, exec, s[8:9]
	s_cbranch_vccz .LBB0_692
	v_mad_i64_i32 v[24:25], s[0:1], v18, s29, 0
	v_lshlrev_b64 v[24:25], 2, v[24:25]
	v_lshl_add_u64 v[26:27], s[94:95], 0, v[24:25]
	v_lshlrev_b64 v[28:29], 2, v[130:131]
	v_lshl_add_u64 v[30:31], v[26:27], 0, v[28:29]
	v_lshl_add_u64 v[36:37], s[88:89], 0, v[28:29]
	v_lshl_add_u64 v[24:25], s[90:91], 0, v[24:25]
	v_lshl_add_u64 v[40:41], v[24:25], 0, v[28:29]
	global_load_dwordx4 v[24:27], v[30:31], off
	s_nop 0
	global_load_dwordx4 v[28:31], v[30:31], off offset:16
	s_nop 0
	global_load_dwordx4 v[32:35], v[36:37], off
	s_nop 0
	global_load_dwordx4 v[36:39], v[36:37], off offset:16
	s_mov_b64 s[10:11], 0
	s_waitcnt vmcnt(0) lgkmcnt(0)
	v_pk_fma_f32 v[26:27], v[16:17], v[34:35], v[26:27]
	v_pk_fma_f32 v[24:25], v[14:15], v[32:33], v[24:25]
	global_store_dwordx4 v[40:41], v[24:27], off
	s_nop 1
	v_pk_fma_f32 v[26:27], v[12:13], v[38:39], v[30:31]
	v_pk_fma_f32 v[24:25], v[10:11], v[36:37], v[28:29]
	global_store_dwordx4 v[40:41], v[24:27], off offset:16
.LBB0_692:
	s_andn2_b64 vcc, exec, s[10:11]
	s_cbranch_vccnz .LBB0_694
	v_cvt_pk_bf16_f32 v14, v14, v15
	v_cvt_pk_bf16_f32 v15, v16, v17
	v_cvt_pk_bf16_f32 v16, v10, v11
	v_mad_i64_i32 v[10:11], s[0:1], v18, s29, 0
	v_lshl_add_u64 v[10:11], v[10:11], 1, s[90:91]
	v_lshl_add_u64 v[10:11], v[130:131], 1, v[10:11]
	v_cvt_pk_bf16_f32 v17, v12, v13
	global_store_dwordx4 v[10:11], v[14:17], off
.LBB0_694:
	s_mov_b64 s[12:13], -1
	s_mov_b64 s[10:11], 0
	s_cmp_lt_i32 s71, 2
	s_mov_b64 s[8:9], 0
	s_cbranch_scc1 .LBB0_703
	s_cmp_gt_i32 s71, 6
	s_cbranch_scc0 .LBB0_699
	s_cmp_eq_u32 s71, 7
	s_mov_b64 s[8:9], -1
	s_cbranch_scc0 .LBB0_698
	v_lshl_add_u64 v[10:11], s[94:95], 0, v[22:23]
	v_ashrrev_i32_e32 v123, 31, v122
	v_lshl_add_u64 v[10:11], v[122:123], 1, v[10:11]
	v_add_co_u32_e32 v10, vcc, 0x2000, v10
	v_lshl_add_u64 v[14:15], s[90:91], 0, v[20:21]
	s_nop 0
	v_addc_co_u32_e32 v11, vcc, 0, v11, vcc
	global_load_dwordx4 v[10:13], v[10:11], off
	v_lshl_add_u64 v[14:15], v[130:131], 1, v[14:15]
	s_mov_b64 s[8:9], 0
	s_waitcnt vmcnt(0) lgkmcnt(0)
	v_lshlrev_b32_e32 v16, 16, v10
	v_and_b32_e32 v17, 0xffff0000, v10
	v_lshlrev_b32_e32 v10, 16, v11
	v_and_b32_e32 v11, 0xffff0000, v11
	v_lshlrev_b32_e32 v20, 16, v12
	v_and_b32_e32 v21, 0xffff0000, v12
	v_lshlrev_b32_e32 v12, 16, v13
	v_and_b32_e32 v13, 0xffff0000, v13
	v_pk_mul_f32 v[22:23], v[8:9], v[10:11]
	v_pk_mul_f32 v[10:11], v[6:7], v[16:17]
	v_pk_mul_f32 v[16:17], v[4:5], v[12:13]
	v_pk_mul_f32 v[12:13], v[2:3], v[20:21]
	v_cvt_pk_bf16_f32 v10, v10, v11
	v_cvt_pk_bf16_f32 v11, v22, v23
	s_nop 0
	v_cvt_pk_bf16_f32 v12, v12, v13
	v_cvt_pk_bf16_f32 v13, v16, v17
	global_store_dwordx4 v[14:15], v[10:13], off offset:256

; DEVI u32x4 pack8(f32x4 a, f32x4 b) { u32x4 o; o.x = cvt_pk_bf16(a[0], a[1]); o.y = cvt_pk_bf16(a[2], a[3]); o.z = cvt_pk_bf16(b[0], b[1]); o.w = cvt_pk_bf16(b[2], b[3]); return o; }
; DEVI float sigmoidf_(float x) { return 1.f / (1.f + __expf(-x)); }
; DEVI void gemm_epi(const GJob& jb, int row, int col, f32x4 v0, f32x4 v1) {
;     ...
;   else if (mode == 2) { f32x4 s0, s1; for (int i = 0; i < 4; ++i) { s0[i] = sigmoidf_(v0[i]); s1[i] = sigmoidf_(v1[i]); } *(u32x4*)((bf16_t*)jb.out + (size_t)row * jb.ldo + col) = pack8(s0, s1); }
.LBB0_699:
	s_and_b64 vcc, exec, s[12:13]
	s_cbranch_vccz .LBB0_702
	s_cmp_eq_u32 s71, 2
	s_mov_b64 s[8:9], -1
	s_cbranch_scc0 .LBB0_702
	v_mul_f32_e32 v0, 0xbfb8aa3b, v6
	v_exp_f32_e32 v0, v0
	s_mov_b64 s[8:9], 0
	v_add_f32_e32 v0, 1.0, v0
	v_div_scale_f32 v10, s[0:1], v0, v0, 1.0
	v_rcp_f32_e32 v11, v10
	s_nop 0
	v_fma_f32 v12, -v10, v11, 1.0
	v_fmac_f32_e32 v11, v12, v11
	v_div_scale_f32 v12, vcc, 1.0, v0, 1.0
	v_mul_f32_e32 v13, v12, v11
	v_fma_f32 v14, -v10, v13, v12
	v_fmac_f32_e32 v13, v14, v11
	v_fma_f32 v10, -v10, v13, v12
	v_div_fmas_f32 v10, v10, v11, v13
	v_div_fixup_f32 v0, v10, v0, 1.0
	v_mul_f32_e32 v10, 0xbfb8aa3b, v2
	v_exp_f32_e32 v10, v10
	s_nop 0
	v_add_f32_e32 v10, 1.0, v10
	v_div_scale_f32 v11, s[0:1], v10, v10, 1.0
	v_rcp_f32_e32 v12, v11
	s_nop 0
	v_fma_f32 v13, -v11, v12, 1.0
	v_fmac_f32_e32 v12, v13, v12
	v_div_scale_f32 v13, vcc, 1.0, v10, 1.0
	v_mul_f32_e32 v14, v13, v12
	v_fma_f32 v15, -v11, v14, v13
	v_fmac_f32_e32 v14, v15, v12
	v_fma_f32 v11, -v11, v14, v13
	v_div_fmas_f32 v11, v11, v12, v14
	v_div_fixup_f32 v12, v11, v10, 1.0
	v_mul_f32_e32 v10, 0xbfb8aa3b, v7
	v_exp_f32_e32 v10, v10
	s_nop 0
	v_add_f32_e32 v10, 1.0, v10
	v_div_scale_f32 v11, s[0:1], v10, v10, 1.0
	v_rcp_f32_e32 v13, v11
	s_nop 0
	v_fma_f32 v14, -v11, v13, 1.0
	v_fmac_f32_e32 v13, v14, v13
	v_div_scale_f32 v14, vcc, 1.0, v10, 1.0
	v_mul_f32_e32 v15, v14, v13
	v_fma_f32 v16, -v11, v15, v14
	v_fmac_f32_e32 v15, v16, v13
	v_fma_f32 v11, -v11, v15, v14
	v_div_fmas_f32 v11, v11, v13, v15
	v_div_fixup_f32 v10, v11, v10, 1.0
	v_mul_f32_e32 v11, 0xbfb8aa3b, v3
	v_exp_f32_e32 v11, v11
	v_cvt_pk_bf16_f32 v10, v0, v10
	s_nop 0
	v_add_f32_e32 v11, 1.0, v11
	v_div_scale_f32 v13, s[0:1], v11, v11, 1.0
	v_rcp_f32_e32 v14, v13
	s_nop 0
	v_fma_f32 v15, -v13, v14, 1.0
	v_fmac_f32_e32 v14, v15, v14
	v_div_scale_f32 v15, vcc, 1.0, v11, 1.0
	v_mul_f32_e32 v16, v15, v14
	v_fma_f32 v17, -v13, v16, v15
	v_fmac_f32_e32 v16, v17, v14
	v_fma_f32 v13, -v13, v16, v15
	v_div_fmas_f32 v13, v13, v14, v16
	v_div_fixup_f32 v13, v13, v11, 1.0
	v_mul_f32_e32 v11, 0xbfb8aa3b, v8
	v_exp_f32_e32 v11, v11
	v_cvt_pk_bf16_f32 v12, v12, v13
	s_nop 0
	v_add_f32_e32 v11, 1.0, v11
	v_div_scale_f32 v14, s[0:1], v11, v11, 1.0
	v_rcp_f32_e32 v15, v14
	s_nop 0
	v_fma_f32 v16, -v14, v15, 1.0
	v_fmac_f32_e32 v15, v16, v15
	v_div_scale_f32 v16, vcc, 1.0, v11, 1.0
	v_mul_f32_e32 v17, v16, v15
	v_fma_f32 v19, -v14, v17, v16
	v_fmac_f32_e32 v17, v19, v15
	v_fma_f32 v14, -v14, v17, v16
	v_div_fmas_f32 v14, v14, v15, v17
	v_div_fixup_f32 v11, v14, v11, 1.0
	v_mul_f32_e32 v14, 0xbfb8aa3b, v4
	v_exp_f32_e32 v14, v14
	s_nop 0
	v_add_f32_e32 v14, 1.0, v14
	v_div_scale_f32 v15, s[0:1], v14, v14, 1.0
	v_rcp_f32_e32 v16, v15
	s_nop 0
	v_fma_f32 v17, -v15, v16, 1.0
	v_fmac_f32_e32 v16, v17, v16
	v_div_scale_f32 v17, vcc, 1.0, v14, 1.0
	v_mul_f32_e32 v19, v17, v16
	v_fma_f32 v20, -v15, v19, v17
	v_fmac_f32_e32 v19, v20, v16
	v_fma_f32 v15, -v15, v19, v17
	v_div_fmas_f32 v15, v15, v16, v19
	v_div_fixup_f32 v14, v15, v14, 1.0
	v_mul_f32_e32 v15, 0xbfb8aa3b, v9
	v_exp_f32_e32 v15, v15
	s_nop 0
	v_add_f32_e32 v15, 1.0, v15
	v_div_scale_f32 v16, s[0:1], v15, v15, 1.0
	v_rcp_f32_e32 v17, v16
	s_nop 0
	v_fma_f32 v19, -v16, v17, 1.0
	v_fmac_f32_e32 v17, v19, v17
	v_div_scale_f32 v19, vcc, 1.0, v15, 1.0
	v_mul_f32_e32 v20, v19, v17
	v_fma_f32 v21, -v16, v20, v19
	v_fmac_f32_e32 v20, v21, v17
	v_fma_f32 v16, -v16, v20, v19
	v_div_fmas_f32 v16, v16, v17, v20
	v_div_fixup_f32 v15, v16, v15, 1.0
	v_mul_f32_e32 v16, 0xbfb8aa3b, v5
	v_exp_f32_e32 v16, v16
	v_cvt_pk_bf16_f32 v11, v11, v15
	s_nop 0
	v_add_f32_e32 v16, 1.0, v16
	v_div_scale_f32 v17, s[0:1], v16, v16, 1.0
	v_rcp_f32_e32 v19, v17
	s_nop 0
	v_fma_f32 v20, -v17, v19, 1.0
	v_fmac_f32_e32 v19, v20, v19
	v_div_scale_f32 v20, vcc, 1.0, v16, 1.0
	v_mul_f32_e32 v21, v20, v19
	v_fma_f32 v22, -v17, v21, v20
	v_fmac_f32_e32 v21, v22, v19
	v_fma_f32 v17, -v17, v21, v20
	v_div_fmas_f32 v17, v17, v19, v21
	v_div_fixup_f32 v16, v17, v16, 1.0
	v_cvt_pk_bf16_f32 v13, v14, v16
	v_mad_i64_i32 v[14:15], s[0:1], v18, s29, 0
	v_lshl_add_u64 v[14:15], v[14:15], 1, s[90:91]
	v_lshl_add_u64 v[14:15], v[130:131], 1, v[14:15]
	global_store_dwordx4 v[14:15], v[10:13], off offset:256

; DEVI void gemm_epi(const GJob& jb, int row, int col, f32x4 v0, f32x4 v1) {
;     ...
;   else if (mode == 1) { float* p = (float*)jb.out + (size_t)row * jb.ldo + col; *(f32x4*)p = v0; *(f32x4*)(p + 4) = v1; }
.LBB0_703:
	s_and_b64 vcc, exec, s[12:13]
	s_cbranch_vccz .LBB0_708
	s_cmp_gt_i32 s71, 0
	s_mov_b64 s[10:11], -1
	s_cbranch_scc0 .LBB0_706
	v_mad_i64_i32 v[10:11], s[0:1], v18, s29, 0
	v_lshl_add_u64 v[10:11], v[10:11], 2, s[90:91]
	v_lshl_add_u64 v[10:11], v[130:131], 2, v[10:11]
	global_store_dwordx4 v[10:11], v[6:9], off offset:512
	global_store_dwordx4 v[10:11], v[2:5], off offset:528
	s_mov_b64 s[10:11], 0

; DEVI float bf_lo(unsigned u) { return __uint_as_float(u << 16); }
; DEVI float bf_hi(unsigned u) { return __uint_as_float(u & 0xffff0000u); }
; DEVI float sigmoidf_(float x) { return 1.f / (1.f + __expf(-x)); }
; DEVI u32x4 pack8(f32x4 a, f32x4 b) { u32x4 o; o.x = cvt_pk_bf16(a[0], a[1]); o.y = cvt_pk_bf16(a[2], a[3]); o.z = cvt_pk_bf16(b[0], b[1]); o.w = cvt_pk_bf16(b[2], b[3]); return o; }
; DEVI void gemm_epi(const GJob& jb, int row, int col, f32x4 v0, f32x4 v1) {
;     ...
;   if (mode == 0) { *(u32x4*)((bf16_t*)jb.out + (size_t)row * jb.ldo + col) = pack8(v0, v1); }
;   else if (mode == 1) { float* p = (float*)jb.out + (size_t)row * jb.ldo + col; *(f32x4*)p = v0; *(f32x4*)(p + 4) = v1; }
;   else if (mode == 2) { f32x4 s0, s1; for (int i = 0; i < 4; ++i) { s0[i] = sigmoidf_(v0[i]); s1[i] = sigmoidf_(v1[i]); } *(u32x4*)((bf16_t*)jb.out + (size_t)row * jb.ldo + col) = pack8(s0, s1); }
;   else if (mode == 7) {
;     const u32x4 g = *(const u32x4*)((const bf16_t*)jb.aux + (size_t)row * NGATE + 2 * 2048 + col);
;     const f32x4 g0 = {bf_lo(g.x), bf_hi(g.x), bf_lo(g.y), bf_hi(g.y)}, g1 = {bf_lo(g.z), bf_hi(g.z), bf_lo(g.w), bf_hi(g.w)};
;     *(u32x4*)((bf16_t*)jb.out + (size_t)row * 2048 + col) = pack8(g0 * v0, g1 * v1);
;   } else {
;     const float* xp = (const float*)jb.aux + (size_t)row * jb.ldo + col; const float* gp = (const float*)jb.aux2 + col;
;     float* op = (float*)jb.out + (size_t)row * jb.ldo + col;
;     const f32x4 x0 = *(const f32x4*)xp, x1 = *(const f32x4*)(xp + 4), t0 = *(const f32x4*)gp, t1 = *(const f32x4*)(gp + 4);
;     *(f32x4*)op = x0 + t0 * v0; *(f32x4*)(op + 4) = x1 + t1 * v1;
; DEVI void gemm_tile(const GJob& jb, int brow, int bcol, unsigned char* shm_) {
;     ...
;         gemm_epi(jb, brow + ai * HALF + wr * 64 + m * 16 + fr, bcol + bj * HALF + wc * 32 + fq * 8, acc[ai][bj][m][0], acc[ai][bj][m][1]);
;   __syncthreads();
.LBB0_708:
	s_and_b64 vcc, exec, s[8:9]
	s_cbranch_vccz .LBB0_710
	v_mad_i64_i32 v[10:11], s[0:1], v18, s29, 0
	v_lshlrev_b64 v[10:11], 2, v[10:11]
	v_lshl_add_u64 v[12:13], s[94:95], 0, v[10:11]
	v_lshlrev_b64 v[14:15], 2, v[130:131]
	v_lshl_add_u64 v[16:17], v[12:13], 0, v[14:15]
	v_lshl_add_u64 v[24:25], s[88:89], 0, v[14:15]
	v_lshl_add_u64 v[10:11], s[90:91], 0, v[10:11]
	v_lshl_add_u64 v[28:29], v[10:11], 0, v[14:15]
	global_load_dwordx4 v[10:13], v[16:17], off offset:512
	s_nop 0
	global_load_dwordx4 v[14:17], v[16:17], off offset:528
	s_nop 0
	global_load_dwordx4 v[20:23], v[24:25], off offset:512
	s_nop 0
	global_load_dwordx4 v[24:27], v[24:25], off offset:528
	s_mov_b64 s[10:11], 0
	s_waitcnt vmcnt(0) lgkmcnt(0)
	v_pk_fma_f32 v[12:13], v[8:9], v[22:23], v[12:13]
	v_pk_fma_f32 v[10:11], v[6:7], v[20:21], v[10:11]
	global_store_dwordx4 v[28:29], v[10:13], off offset:512
	s_nop 1
	v_pk_fma_f32 v[12:13], v[4:5], v[26:27], v[16:17]
	v_pk_fma_f32 v[10:11], v[2:3], v[24:25], v[14:15]
	global_store_dwordx4 v[28:29], v[10:13], off offset:528
.LBB0_710:
	s_andn2_b64 vcc, exec, s[10:11]
	s_cbranch_vccnz .LBB0_409
	v_cvt_pk_bf16_f32 v6, v6, v7
	v_cvt_pk_bf16_f32 v7, v8, v9
	v_cvt_pk_bf16_f32 v8, v2, v3
	v_mad_i64_i32 v[2:3], s[0:1], v18, s29, 0
	v_lshl_add_u64 v[2:3], v[2:3], 1, s[90:91]
	v_lshl_add_u64 v[2:3], v[130:131], 1, v[2:3]
	v_cvt_pk_bf16_f32 v9, v4, v5
	global_store_dwordx4 v[2:3], v[6:9], off offset:256
	s_branch .LBB0_409
